# v18 plus first-iteration waits counted past the epilogue stores (in_proj, gate-up, Cq; in_proj pre-loop full drain removed) and retention loop-top wait split by path
# baseline (speedup 1.0000x reference)
;     DI bool next(int i, Unit& u) const {
;         const long L = (long)i * G + c; if (L >= nwg) return false;
;         int wgid = (int)L; { const int q = nwg / NXCD, r = nwg % NXCD, xcd = wgid % NXCD, off = wgid / NXCD; wgid = (xcd < r ? xcd * (q + 1) : r * (q + 1) + (xcd - r) * q) + off; }
;         const int nig = WGM * nN, gid = wgid / nig, fm = gid * WGM, gsz = (nM - fm) < WGM ? (nM - fm) : WGM;
;         u.pm = fm + ((wgid % nig) % gsz); u.pn = (wgid % nig) / gsz; u.r0 = u.pm * BM; u.ui = i; return true;
; __global__ void __launch_bounds__(512, 2) fwd_mega(Params p) {
;     ...
;         { pg8::Gemm g{(const bf16_t*)((unsigned char*)p.out + OB_XB), DM, (const bf16_t*)(ws + WS_WIN), MT, DIN, DM}; pg8::StaticOrder S; S.init(MT, DIN, G, cb);
;           EpiInProj E{P, p.out + O_RSTD1, (const unsigned*)(p.out + O_ROPE)}; pg8::gemm_phase<EpiInProj, true>(L, g, S, E); }
.Lstg1_done:
	s_mov_b32 s98, 0
	s_cmpk_lt_i32 s64, 0x1d74
	s_cselect_b64 s[2:3], -1, 0
	s_cmpk_gt_i32 s64, 0x1d73
	v_readfirstlane_b32 s14, v153
	s_cbranch_scc1 .LBB0_208
	s_ashr_i32 s4, s64, 31
	s_lshr_b32 s4, s4, 29
	s_add_i32 s6, s64, s4
	s_and_b32 s4, s6, -8
	s_sub_i32 s7, s64, s4
	s_cmp_gt_i32 s7, 3
	s_cbranch_scc0 .LBB0_209
	s_mul_i32 s4, s7, 0x3ae
	s_add_i32 s8, s4, 4
	s_cbranch_execz .LBB0_210
	s_branch .LBB0_211

; #define PG8_STAGE(bufoff, gbase, voff) do { _Pragma("unroll") for (int _i = 0; _i < 2; ++_i) \
;         __builtin_amdgcn_global_load_lds((const unsigned*)((const char*)(gbase) + (voff)[_i]), (LAS unsigned*)(lds + (bufoff) + ldsw + _i * 8192), 16, 0, 0); } while (0)
; #define PG8_LDA(dst, b, h) do { _Pragma("unroll") for (int m = 0; m < 4; ++m) _Pragma("unroll") for (int k = 0; k < 2; ++k) dst[m][k] = *(const LAS bf16x8*)(lds + PG8_SA(b, h) + aoff + m * 2048 + k * 1024); } while (0)
; #define PG8_LDB(dst, b, h) do { _Pragma("unroll") for (int n = 0; n < 2; ++n) _Pragma("unroll") for (int k = 0; k < 2; ++k) dst[n][k] = *(const LAS bf16x8*)(lds + PG8_SB(b, h) + boff + n * 2048 + k * 1024); } while (0)
; template <class Epi, bool ALIGN_EPI>
; DI void gemm_phase(lptr lds, const Gemm g, const StaticOrder& S, const Epi& E) {
;     ...
;     const char* cA = (const char*)g.A + (size_t)cur.pm * tstepA; const char* cB = (const char*)g.Bt + (size_t)cur.pn * tstepB;
;     if constexpr (Epi::RESCALE) E.prep(cur, tid);
;     PG8_STAGE(PG8_SB(0, 0), cB, voffB); PG8_STAGE(PG8_SB(0, 1), cB + hstepB, voffB); PG8_STAGE(PG8_SA(0, 0), cA, voffA); PG8_STAGE(PG8_SA(0, 1), cA + hstepA, voffA);
;     if (wr == 1) PG8_BAR;
;     PG8_WAIT_V(2); PG8_BAR;
;     PG8_STAGE(PG8_SB(1, 0), cB + kstep, voffB); PG8_STAGE(PG8_SA(1, 0), cA + kstep, voffA); PG8_STAGE(PG8_SB(1, 1), cB + hstepB + kstep, voffB);
;     PG8_WAIT_V(6); PG8_BAR;
;     for (;;) {
;         const bool has_next = S.next(ui + 1, nxt);
;         const char* nA = has_next ? (const char*)g.A + (size_t)nxt.pm * tstepA : cA; const char* nB = has_next ? (const char*)g.Bt + (size_t)nxt.pn * tstepB : cB;
;         for (int t = 0; t < nt; t += 2) {
;             const bool last = (t == nt - 2);
;             if constexpr (Epi::RESCALE) { if (t == 4 || t == 8 || t == 12) E.rescale(acc, cur, t >> 2, wr, fr); }
;             const char* a1 = cA + (size_t)(t + 1) * kstep;
;             const char* a2 = last ? nA : cA + (size_t)(t + 2) * kstep; const char* b2 = last ? nB : cB + (size_t)(t + 2) * kstep;
;             const char* a3 = a2 + kstep; const char* b3 = b2 + kstep;
;             PG8_LDB(B0, 0, 0); PG8_LDB(B1, 0, 1); PG8_SCHED; PG8_LDA(At, 0, 0); PG8_STAGE(PG8_SA(1, 1), a1 + hstepA, voffA);
;             PG8_WAIT_V(8); PG8_WAIT_L(0); PG8_BAR; PG8_MMA(0, 0, At, B0); PG8_MMA(0, 1, At, B1); PG8_BAR; PG8_SCHED;
.LBB0_224:
	s_ashr_i32 s23, s22, 31
	s_lshl_b64 s[24:25], s[22:23], 19
	s_add_u32 s24, s92, s24
	s_addc_u32 s25, s93, s25
	s_and_b64 s[26:27], s[2:3], exec
	s_cselect_b32 s23, s25, s5
	s_cselect_b32 s31, s24, s4
	s_ashr_i32 s21, s20, 31
	s_lshl_b64 s[26:27], s[20:21], 19
	s_add_u32 s26, s19, s26
	s_addc_u32 s27, s40, s27
	s_and_b64 s[28:29], s[2:3], exec
	s_cselect_b32 s21, s27, s7
	s_cselect_b32 s33, s26, s6
	s_add_u32 s4, s4, 0x40080
	s_addc_u32 s5, s5, 0
	s_add_u32 s35, s6, 0x100
	v_mov_b32_e32 v0, 0
	s_addc_u32 s36, s7, 0
	s_mov_b32 s37, -2
	v_mov_b32_e32 v1, v0
	v_mov_b32_e32 v2, v0
	v_mov_b32_e32 v3, v0
	v_mov_b32_e32 v4, v0
	v_mov_b32_e32 v5, v0
	v_mov_b32_e32 v6, v0
	v_mov_b32_e32 v7, v0
	v_mov_b32_e32 v16, v0
	v_mov_b32_e32 v17, v0
	v_mov_b32_e32 v18, v0
	v_mov_b32_e32 v19, v0
	v_mov_b32_e32 v20, v0
	v_mov_b32_e32 v21, v0
	v_mov_b32_e32 v22, v0
	v_mov_b32_e32 v23, v0
	v_mov_b32_e32 v32, v0
	v_mov_b32_e32 v33, v0
	v_mov_b32_e32 v34, v0
	v_mov_b32_e32 v35, v0
	v_mov_b32_e32 v36, v0
	v_mov_b32_e32 v37, v0
	v_mov_b32_e32 v38, v0
	v_mov_b32_e32 v39, v0
	v_mov_b32_e32 v48, v0
	v_mov_b32_e32 v49, v0
	v_mov_b32_e32 v50, v0
	v_mov_b32_e32 v51, v0
	v_mov_b32_e32 v52, v0
	v_mov_b32_e32 v53, v0
	v_mov_b32_e32 v54, v0
	v_mov_b32_e32 v55, v0
	v_mov_b32_e32 v8, v0
	v_mov_b32_e32 v9, v0
	v_mov_b32_e32 v10, v0
	v_mov_b32_e32 v11, v0
	v_mov_b32_e32 v12, v0
	v_mov_b32_e32 v13, v0
	v_mov_b32_e32 v14, v0
	v_mov_b32_e32 v15, v0
	v_mov_b32_e32 v24, v0
	v_mov_b32_e32 v25, v0
	v_mov_b32_e32 v26, v0
	v_mov_b32_e32 v27, v0
	v_mov_b32_e32 v28, v0
	v_mov_b32_e32 v29, v0
	v_mov_b32_e32 v30, v0
	v_mov_b32_e32 v31, v0
	v_mov_b32_e32 v40, v0
	v_mov_b32_e32 v41, v0
	v_mov_b32_e32 v42, v0
	v_mov_b32_e32 v43, v0
	v_mov_b32_e32 v44, v0
	v_mov_b32_e32 v45, v0
	v_mov_b32_e32 v46, v0
	v_mov_b32_e32 v47, v0
	v_mov_b32_e32 v56, v0
	v_mov_b32_e32 v57, v0
	v_mov_b32_e32 v58, v0
	v_mov_b32_e32 v59, v0
	v_mov_b32_e32 v60, v0
	v_mov_b32_e32 v61, v0
	v_mov_b32_e32 v62, v0
	v_mov_b32_e32 v63, v0
	v_mov_b32_e32 v64, v0
	v_mov_b32_e32 v65, v0
	v_mov_b32_e32 v66, v0
	v_mov_b32_e32 v67, v0
	v_mov_b32_e32 v68, v0
	v_mov_b32_e32 v69, v0
	v_mov_b32_e32 v70, v0
	v_mov_b32_e32 v71, v0
	v_mov_b32_e32 v80, v0
	v_mov_b32_e32 v81, v0
	v_mov_b32_e32 v82, v0
	v_mov_b32_e32 v83, v0
	v_mov_b32_e32 v84, v0
	v_mov_b32_e32 v85, v0
	v_mov_b32_e32 v86, v0
	v_mov_b32_e32 v87, v0
	v_mov_b32_e32 v96, v0
	v_mov_b32_e32 v97, v0
	v_mov_b32_e32 v98, v0
	v_mov_b32_e32 v99, v0
	v_mov_b32_e32 v100, v0
	v_mov_b32_e32 v101, v0
	v_mov_b32_e32 v102, v0
	v_mov_b32_e32 v103, v0
	v_mov_b32_e32 v112, v0
	v_mov_b32_e32 v113, v0
	v_mov_b32_e32 v114, v0
	v_mov_b32_e32 v115, v0
	v_mov_b32_e32 v116, v0
	v_mov_b32_e32 v117, v0
	v_mov_b32_e32 v118, v0
	v_mov_b32_e32 v119, v0
	v_mov_b32_e32 v72, v0
	v_mov_b32_e32 v73, v0
	v_mov_b32_e32 v74, v0
	v_mov_b32_e32 v75, v0
	v_mov_b32_e32 v76, v0
	v_mov_b32_e32 v77, v0
	v_mov_b32_e32 v78, v0
	v_mov_b32_e32 v79, v0
	v_mov_b32_e32 v88, v0
	v_mov_b32_e32 v89, v0
	v_mov_b32_e32 v90, v0
	v_mov_b32_e32 v91, v0
	v_mov_b32_e32 v92, v0
	v_mov_b32_e32 v93, v0
	v_mov_b32_e32 v94, v0
	v_mov_b32_e32 v95, v0
	v_mov_b32_e32 v104, v0
	v_mov_b32_e32 v105, v0
	v_mov_b32_e32 v106, v0
	v_mov_b32_e32 v107, v0
	v_mov_b32_e32 v108, v0
	v_mov_b32_e32 v109, v0
	v_mov_b32_e32 v110, v0
	v_mov_b32_e32 v111, v0
	v_mov_b32_e32 v120, v0
	v_mov_b32_e32 v121, v0
	v_mov_b32_e32 v122, v0
	v_mov_b32_e32 v123, v0
	v_mov_b32_e32 v124, v0
	v_mov_b32_e32 v125, v0
	v_mov_b32_e32 v126, v0
	v_mov_b32_e32 v127, v0
	s_cmp_lg_u32 s98, 0
	s_cselect_b32 s99, -2, 0x7fffff00
.LBB0_225:
	ds_read_b128 v[148:151], v211
	ds_read_b128 v[154:157], v211 offset:1024
	ds_read_b128 v[158:161], v211 offset:2048
	ds_read_b128 v[162:165], v211 offset:3072
	ds_read_b128 v[166:169], v212
	ds_read_b128 v[170:173], v212 offset:1024
	ds_read_b128 v[174:177], v212 offset:2048
	ds_read_b128 v[178:181], v212 offset:3072
	s_add_u32 s6, s4, 0xfffc0080
	s_addc_u32 s7, s5, -1
	s_cmp_eq_u32 s37, 12
	s_cselect_b32 s29, s23, s7
	s_cselect_b32 s28, s31, s6
	s_cselect_b32 s7, s21, s36
	s_cselect_b32 s6, s33, s35
	v_lshl_add_u64 v[198:199], s[4:5], 0, v[140:141]
	s_add_i32 m0, s42, 0xc000
	ds_read_b128 v[182:185], v213
	ds_read_b128 v[186:189], v213 offset:1024
	ds_read_b128 v[190:193], v213 offset:2048
	ds_read_b128 v[194:197], v213 offset:3072
	ds_read_b128 v[214:217], v213 offset:4096
	ds_read_b128 v[218:221], v213 offset:5120
	ds_read_b128 v[222:225], v213 offset:6144
	ds_read_b128 v[226:229], v213 offset:7168
	global_load_lds_dwordx4 v[198:199], off
	v_lshl_add_u64 v[198:199], s[4:5], 0, v[142:143]
	s_add_i32 m0, s42, 0xe000
	s_nop 0
	global_load_lds_dwordx4 v[198:199], off
	s_cmp_eq_u32 s37, s99
	s_cbranch_scc1 .Lrx_ip_0
	s_waitcnt vmcnt(8)
; #define PG8_STAGE(bufoff, gbase, voff) do { _Pragma("unroll") for (int _i = 0; _i < 2; ++_i) \
;         __builtin_amdgcn_global_load_lds((const unsigned*)((const char*)(gbase) + (voff)[_i]), (LAS unsigned*)(lds + (bufoff) + ldsw + _i * 8192), 16, 0, 0); } while (0)
; #define PG8_LDA(dst, b, h) do { _Pragma("unroll") for (int m = 0; m < 4; ++m) _Pragma("unroll") for (int k = 0; k < 2; ++k) dst[m][k] = *(const LAS bf16x8*)(lds + PG8_SA(b, h) + aoff + m * 2048 + k * 1024); } while (0)
; #define PG8_LDB(dst, b, h) do { _Pragma("unroll") for (int n = 0; n < 2; ++n) _Pragma("unroll") for (int k = 0; k < 2; ++k) dst[n][k] = *(const LAS bf16x8*)(lds + PG8_SB(b, h) + boff + n * 2048 + k * 1024); } while (0)
; #define PG8_MMA(ai, bj, At, Bt) do { __builtin_amdgcn_s_setprio(1); _Pragma("unroll") for (int m = 0; m < 4; ++m) _Pragma("unroll") for (int n = 0; n < 2; ++n) _Pragma("unroll") for (int k = 0; k < 2; ++k) \
;         acc[ai][bj][m][n] = __builtin_amdgcn_mfma_f32_16x16x32_bf16(Bt[n][k], At[m][k], acc[ai][bj][m][n], 0, 0, 0); __builtin_amdgcn_s_setprio(0); } while (0)
; #define PG8_WAIT_V(n) asm volatile("s_waitcnt vmcnt(" #n ")" ::: "memory")
; #define PG8_WAIT_L(n) asm volatile("s_waitcnt lgkmcnt(" #n ")" ::: "memory")
; #define PG8_BAR __builtin_amdgcn_s_barrier()
; #define PG8_SCHED __builtin_amdgcn_sched_barrier(0)
; template <class Epi, bool ALIGN_EPI>
; DI void gemm_phase(lptr lds, const Gemm g, const StaticOrder& S, const Epi& E) {
;     ...
;             PG8_LDB(B0, 0, 0); PG8_LDB(B1, 0, 1); PG8_SCHED; PG8_LDA(At, 0, 0); PG8_STAGE(PG8_SA(1, 1), a1 + hstepA, voffA);
;             PG8_WAIT_V(8); PG8_WAIT_L(0); PG8_BAR; PG8_MMA(0, 0, At, B0); PG8_MMA(0, 1, At, B1); PG8_BAR; PG8_SCHED;
;             PG8_LDA(At, 0, 1); PG8_STAGE(PG8_SB(0, 0), b2, voffB); PG8_STAGE(PG8_SB(0, 1), b2 + hstepB, voffB); PG8_STAGE(PG8_SA(0, 0), a2, voffA);
;             PG8_WAIT_V(8); PG8_WAIT_L(0); PG8_BAR; PG8_MMA(1, 0, At, B0); PG8_MMA(1, 1, At, B1); PG8_BAR; PG8_SCHED;
.Lrx_ip_0b:
	s_waitcnt lgkmcnt(0)
	s_barrier
	s_setprio 1
	s_waitcnt lgkmcnt(0)
	v_mfma_f32_16x16x32_bf16 v[124:127], v[148:151], v[182:185], v[124:127]
	v_mfma_f32_16x16x32_bf16 v[120:123], v[158:161], v[182:185], v[120:123]
	v_mfma_f32_16x16x32_bf16 v[108:111], v[148:151], v[190:193], v[108:111]
	v_mfma_f32_16x16x32_bf16 v[104:107], v[158:161], v[190:193], v[104:107]
	v_mfma_f32_16x16x32_bf16 v[92:95], v[148:151], v[214:217], v[92:95]
	v_mfma_f32_16x16x32_bf16 v[88:91], v[158:161], v[214:217], v[88:91]
	v_mfma_f32_16x16x32_bf16 v[76:79], v[148:151], v[222:225], v[76:79]
	v_mfma_f32_16x16x32_bf16 v[72:75], v[158:161], v[222:225], v[72:75]
	v_mfma_f32_16x16x32_bf16 v[124:127], v[154:157], v[186:189], v[124:127]
	v_mfma_f32_16x16x32_bf16 v[120:123], v[162:165], v[186:189], v[120:123]
	v_mfma_f32_16x16x32_bf16 v[108:111], v[154:157], v[194:197], v[108:111]
	v_mfma_f32_16x16x32_bf16 v[104:107], v[162:165], v[194:197], v[104:107]
	v_mfma_f32_16x16x32_bf16 v[92:95], v[154:157], v[218:221], v[92:95]
	v_mfma_f32_16x16x32_bf16 v[88:91], v[162:165], v[218:221], v[88:91]
	v_mfma_f32_16x16x32_bf16 v[76:79], v[154:157], v[226:229], v[76:79]
	v_mfma_f32_16x16x32_bf16 v[72:75], v[162:165], v[226:229], v[72:75]
	s_setprio 0
	s_setprio 1
	v_mfma_f32_16x16x32_bf16 v[116:119], v[166:169], v[182:185], v[116:119]
	v_mfma_f32_16x16x32_bf16 v[112:115], v[174:177], v[182:185], v[112:115]
	v_mfma_f32_16x16x32_bf16 v[100:103], v[166:169], v[190:193], v[100:103]
	v_mfma_f32_16x16x32_bf16 v[96:99], v[174:177], v[190:193], v[96:99]
	v_mfma_f32_16x16x32_bf16 v[84:87], v[166:169], v[214:217], v[84:87]
	v_mfma_f32_16x16x32_bf16 v[80:83], v[174:177], v[214:217], v[80:83]
	v_mfma_f32_16x16x32_bf16 v[68:71], v[166:169], v[222:225], v[68:71]
	v_mfma_f32_16x16x32_bf16 v[64:67], v[174:177], v[222:225], v[64:67]
	v_mfma_f32_16x16x32_bf16 v[116:119], v[170:173], v[186:189], v[116:119]
	v_mfma_f32_16x16x32_bf16 v[112:115], v[178:181], v[186:189], v[112:115]
	v_mfma_f32_16x16x32_bf16 v[100:103], v[170:173], v[194:197], v[100:103]
	v_mfma_f32_16x16x32_bf16 v[96:99], v[178:181], v[194:197], v[96:99]
	v_mfma_f32_16x16x32_bf16 v[84:87], v[170:173], v[218:221], v[84:87]
	v_mfma_f32_16x16x32_bf16 v[80:83], v[178:181], v[218:221], v[80:83]
	v_mfma_f32_16x16x32_bf16 v[68:71], v[170:173], v[226:229], v[68:71]
	v_mfma_f32_16x16x32_bf16 v[64:67], v[178:181], v[226:229], v[64:67]
	s_setprio 0
	s_barrier
	s_add_i32 s38, s55, s41
	v_lshl_add_u64 v[198:199], s[6:7], 0, v[130:131]
	s_mov_b32 m0, s38
	ds_read_b128 v[182:185], v213 offset:16384
	ds_read_b128 v[186:189], v213 offset:17408
	ds_read_b128 v[190:193], v213 offset:18432
	ds_read_b128 v[194:197], v213 offset:19456
	ds_read_b128 v[214:217], v213 offset:20480
	ds_read_b128 v[218:221], v213 offset:21504
	ds_read_b128 v[222:225], v213 offset:22528
	ds_read_b128 v[226:229], v213 offset:23552
	global_load_lds_dwordx4 v[198:199], off
	s_add_i32 m0, s38, 0x2000
	s_add_u32 s38, s6, 0x40000
	v_lshl_add_u64 v[230:231], s[6:7], 0, v[134:135]
	s_addc_u32 s39, s7, 0
	s_add_i32 s58, s56, s41
	global_load_lds_dwordx4 v[230:231], off
	v_lshl_add_u64 v[232:233], s[38:39], 0, v[130:131]
	s_mov_b32 m0, s58
	v_lshl_add_u64 v[234:235], s[28:29], 0, v[132:133]
	global_load_lds_dwordx4 v[232:233], off
	v_lshl_add_u64 v[232:233], s[38:39], 0, v[134:135]
	s_add_i32 m0, s58, 0x2000
	s_nop 0
	global_load_lds_dwordx4 v[232:233], off
	v_lshl_add_u64 v[232:233], s[28:29], 0, v[128:129]
	s_mov_b32 m0, s42
	s_nop 0
	global_load_lds_dwordx4 v[232:233], off
	s_mov_b32 m0, s43
	s_nop 0
	global_load_lds_dwordx4 v[234:235], off
	s_cmp_eq_u32 s37, s99
	s_cbranch_scc1 .Lrx_ip_1
	s_waitcnt vmcnt(8)
.Lrx_ip_1b:
	s_waitcnt lgkmcnt(0)
	s_barrier
	s_setprio 1
	s_waitcnt lgkmcnt(0)
	v_mfma_f32_16x16x32_bf16 v[60:63], v[148:151], v[182:185], v[60:63]
	v_mfma_f32_16x16x32_bf16 v[56:59], v[158:161], v[182:185], v[56:59]
	v_mfma_f32_16x16x32_bf16 v[44:47], v[148:151], v[190:193], v[44:47]
	v_mfma_f32_16x16x32_bf16 v[40:43], v[158:161], v[190:193], v[40:43]
	v_mfma_f32_16x16x32_bf16 v[28:31], v[148:151], v[214:217], v[28:31]
	v_mfma_f32_16x16x32_bf16 v[24:27], v[158:161], v[214:217], v[24:27]
	v_mfma_f32_16x16x32_bf16 v[12:15], v[148:151], v[222:225], v[12:15]
	v_mfma_f32_16x16x32_bf16 v[8:11], v[158:161], v[222:225], v[8:11]
	v_mfma_f32_16x16x32_bf16 v[60:63], v[154:157], v[186:189], v[60:63]
	v_mfma_f32_16x16x32_bf16 v[56:59], v[162:165], v[186:189], v[56:59]
	v_mfma_f32_16x16x32_bf16 v[44:47], v[154:157], v[194:197], v[44:47]
	v_mfma_f32_16x16x32_bf16 v[40:43], v[162:165], v[194:197], v[40:43]
	v_mfma_f32_16x16x32_bf16 v[28:31], v[154:157], v[218:221], v[28:31]
	v_mfma_f32_16x16x32_bf16 v[24:27], v[162:165], v[218:221], v[24:27]
	v_mfma_f32_16x16x32_bf16 v[12:15], v[154:157], v[226:229], v[12:15]
	v_mfma_f32_16x16x32_bf16 v[8:11], v[162:165], v[226:229], v[8:11]
	s_setprio 0
	s_setprio 1
	v_mfma_f32_16x16x32_bf16 v[52:55], v[166:169], v[182:185], v[52:55]
	v_mfma_f32_16x16x32_bf16 v[48:51], v[174:177], v[182:185], v[48:51]
	v_mfma_f32_16x16x32_bf16 v[36:39], v[166:169], v[190:193], v[36:39]
	v_mfma_f32_16x16x32_bf16 v[32:35], v[174:177], v[190:193], v[32:35]
	v_mfma_f32_16x16x32_bf16 v[20:23], v[166:169], v[214:217], v[20:23]
	v_mfma_f32_16x16x32_bf16 v[16:19], v[174:177], v[214:217], v[16:19]
	v_mfma_f32_16x16x32_bf16 v[4:7], v[166:169], v[222:225], v[4:7]
	v_mfma_f32_16x16x32_bf16 v[0:3], v[174:177], v[222:225], v[0:3]
	v_mfma_f32_16x16x32_bf16 v[52:55], v[170:173], v[186:189], v[52:55]
	v_mfma_f32_16x16x32_bf16 v[48:51], v[178:181], v[186:189], v[48:51]
	v_mfma_f32_16x16x32_bf16 v[36:39], v[170:173], v[194:197], v[36:39]
	v_mfma_f32_16x16x32_bf16 v[32:35], v[178:181], v[194:197], v[32:35]
	v_mfma_f32_16x16x32_bf16 v[20:23], v[170:173], v[218:221], v[20:23]
	v_mfma_f32_16x16x32_bf16 v[16:19], v[178:181], v[218:221], v[16:19]
	v_mfma_f32_16x16x32_bf16 v[4:7], v[170:173], v[226:229], v[4:7]
	v_mfma_f32_16x16x32_bf16 v[0:3], v[178:181], v[226:229], v[0:3]
	s_setprio 0
	s_barrier
; #define PG8_STAGE(bufoff, gbase, voff) do { _Pragma("unroll") for (int _i = 0; _i < 2; ++_i) \
;         __builtin_amdgcn_global_load_lds((const unsigned*)((const char*)(gbase) + (voff)[_i]), (LAS unsigned*)(lds + (bufoff) + ldsw + _i * 8192), 16, 0, 0); } while (0)
; #define PG8_LDA(dst, b, h) do { _Pragma("unroll") for (int m = 0; m < 4; ++m) _Pragma("unroll") for (int k = 0; k < 2; ++k) dst[m][k] = *(const LAS bf16x8*)(lds + PG8_SA(b, h) + aoff + m * 2048 + k * 1024); } while (0)
; #define PG8_LDB(dst, b, h) do { _Pragma("unroll") for (int n = 0; n < 2; ++n) _Pragma("unroll") for (int k = 0; k < 2; ++k) dst[n][k] = *(const LAS bf16x8*)(lds + PG8_SB(b, h) + boff + n * 2048 + k * 1024); } while (0)
; #define PG8_MMA(ai, bj, At, Bt) do { __builtin_amdgcn_s_setprio(1); _Pragma("unroll") for (int m = 0; m < 4; ++m) _Pragma("unroll") for (int n = 0; n < 2; ++n) _Pragma("unroll") for (int k = 0; k < 2; ++k) \
;         acc[ai][bj][m][n] = __builtin_amdgcn_mfma_f32_16x16x32_bf16(Bt[n][k], At[m][k], acc[ai][bj][m][n], 0, 0, 0); __builtin_amdgcn_s_setprio(0); } while (0)
; #define PG8_WAIT_V(n) asm volatile("s_waitcnt vmcnt(" #n ")" ::: "memory")
; #define PG8_WAIT_L(n) asm volatile("s_waitcnt lgkmcnt(" #n ")" ::: "memory")
; #define PG8_BAR __builtin_amdgcn_s_barrier()
; #define PG8_SCHED __builtin_amdgcn_sched_barrier(0)
; template <class Epi, bool ALIGN_EPI>
; DI void gemm_phase(lptr lds, const Gemm g, const StaticOrder& S, const Epi& E) {
;     ...
;             PG8_LDB(B0, 1, 0); PG8_LDB(B1, 1, 1); PG8_SCHED; PG8_LDA(At, 1, 0); PG8_STAGE(PG8_SA(0, 1), a2 + hstepA, voffA);
;             PG8_WAIT_V(8); PG8_WAIT_L(0); PG8_BAR; PG8_MMA(0, 0, At, B0); PG8_MMA(0, 1, At, B1); PG8_BAR; PG8_SCHED;
	s_add_i32 s38, 0, 0x18000
	v_add_u32_e32 v136, s38, v209
	s_add_i32 s39, 0, 0x1c000
	ds_read_b128 v[148:151], v136
	ds_read_b128 v[154:157], v136 offset:1024
	ds_read_b128 v[158:161], v136 offset:2048
	ds_read_b128 v[162:165], v136 offset:3072
	v_add_u32_e32 v136, s39, v209
	ds_read_b128 v[166:169], v136
	ds_read_b128 v[170:173], v136 offset:1024
	ds_read_b128 v[174:177], v136 offset:2048
	ds_read_b128 v[178:181], v136 offset:3072
	s_add_u32 s28, s28, 0x40000
	s_addc_u32 s29, s29, 0
	s_mov_b32 m0, s44
	v_lshl_add_u64 v[236:237], s[28:29], 0, v[128:129]
	ds_read_b128 v[182:185], v213 offset:32768
	ds_read_b128 v[186:189], v213 offset:33792
	ds_read_b128 v[190:193], v213 offset:34816
	ds_read_b128 v[194:197], v213 offset:35840
	ds_read_b128 v[214:217], v213 offset:36864
	ds_read_b128 v[218:221], v213 offset:37888
	ds_read_b128 v[222:225], v213 offset:38912
	ds_read_b128 v[226:229], v213 offset:39936
	global_load_lds_dwordx4 v[236:237], off
	v_lshl_add_u64 v[236:237], s[28:29], 0, v[132:133]
	s_mov_b32 m0, s45
	s_nop 0
	global_load_lds_dwordx4 v[236:237], off
	s_waitcnt vmcnt(8)
	s_waitcnt lgkmcnt(0)
	s_barrier
	s_setprio 1
	s_waitcnt lgkmcnt(0)
	v_mfma_f32_16x16x32_bf16 v[124:127], v[148:151], v[182:185], v[124:127]
	v_mfma_f32_16x16x32_bf16 v[120:123], v[158:161], v[182:185], v[120:123]
	v_mfma_f32_16x16x32_bf16 v[108:111], v[148:151], v[190:193], v[108:111]
	v_mfma_f32_16x16x32_bf16 v[104:107], v[158:161], v[190:193], v[104:107]
	v_mfma_f32_16x16x32_bf16 v[92:95], v[148:151], v[214:217], v[92:95]
	v_mfma_f32_16x16x32_bf16 v[88:91], v[158:161], v[214:217], v[88:91]
	v_mfma_f32_16x16x32_bf16 v[76:79], v[148:151], v[222:225], v[76:79]
	v_mfma_f32_16x16x32_bf16 v[72:75], v[158:161], v[222:225], v[72:75]
	v_mfma_f32_16x16x32_bf16 v[124:127], v[154:157], v[186:189], v[124:127]
	v_mfma_f32_16x16x32_bf16 v[120:123], v[162:165], v[186:189], v[120:123]
	v_mfma_f32_16x16x32_bf16 v[108:111], v[154:157], v[194:197], v[108:111]
	v_mfma_f32_16x16x32_bf16 v[104:107], v[162:165], v[194:197], v[104:107]
	v_mfma_f32_16x16x32_bf16 v[92:95], v[154:157], v[218:221], v[92:95]
	v_mfma_f32_16x16x32_bf16 v[88:91], v[162:165], v[218:221], v[88:91]
	v_mfma_f32_16x16x32_bf16 v[76:79], v[154:157], v[226:229], v[76:79]
	v_mfma_f32_16x16x32_bf16 v[72:75], v[162:165], v[226:229], v[72:75]
	s_setprio 0
	s_setprio 1
	v_mfma_f32_16x16x32_bf16 v[116:119], v[166:169], v[182:185], v[116:119]
	v_mfma_f32_16x16x32_bf16 v[112:115], v[174:177], v[182:185], v[112:115]
	v_mfma_f32_16x16x32_bf16 v[100:103], v[166:169], v[190:193], v[100:103]
	v_mfma_f32_16x16x32_bf16 v[96:99], v[174:177], v[190:193], v[96:99]
	v_mfma_f32_16x16x32_bf16 v[84:87], v[166:169], v[214:217], v[84:87]
	v_mfma_f32_16x16x32_bf16 v[80:83], v[174:177], v[214:217], v[80:83]
	v_mfma_f32_16x16x32_bf16 v[68:71], v[166:169], v[222:225], v[68:71]
	v_mfma_f32_16x16x32_bf16 v[64:67], v[174:177], v[222:225], v[64:67]
	v_mfma_f32_16x16x32_bf16 v[116:119], v[170:173], v[186:189], v[116:119]
	v_mfma_f32_16x16x32_bf16 v[112:115], v[178:181], v[186:189], v[112:115]
	v_mfma_f32_16x16x32_bf16 v[100:103], v[170:173], v[194:197], v[100:103]
	v_mfma_f32_16x16x32_bf16 v[96:99], v[178:181], v[194:197], v[96:99]
	v_mfma_f32_16x16x32_bf16 v[84:87], v[170:173], v[218:221], v[84:87]
	v_mfma_f32_16x16x32_bf16 v[80:83], v[178:181], v[218:221], v[80:83]
	v_mfma_f32_16x16x32_bf16 v[68:71], v[170:173], v[226:229], v[68:71]
	v_mfma_f32_16x16x32_bf16 v[64:67], v[178:181], v[226:229], v[64:67]
	s_setprio 0
	s_barrier
; #define PG8_STAGE(bufoff, gbase, voff) do { _Pragma("unroll") for (int _i = 0; _i < 2; ++_i) \
;         __builtin_amdgcn_global_load_lds((const unsigned*)((const char*)(gbase) + (voff)[_i]), (LAS unsigned*)(lds + (bufoff) + ldsw + _i * 8192), 16, 0, 0); } while (0)
; #define PG8_LDA(dst, b, h) do { _Pragma("unroll") for (int m = 0; m < 4; ++m) _Pragma("unroll") for (int k = 0; k < 2; ++k) dst[m][k] = *(const LAS bf16x8*)(lds + PG8_SA(b, h) + aoff + m * 2048 + k * 1024); } while (0)
; #define PG8_MMA(ai, bj, At, Bt) do { __builtin_amdgcn_s_setprio(1); _Pragma("unroll") for (int m = 0; m < 4; ++m) _Pragma("unroll") for (int n = 0; n < 2; ++n) _Pragma("unroll") for (int k = 0; k < 2; ++k) \
;         acc[ai][bj][m][n] = __builtin_amdgcn_mfma_f32_16x16x32_bf16(Bt[n][k], At[m][k], acc[ai][bj][m][n], 0, 0, 0); __builtin_amdgcn_s_setprio(0); } while (0)
; #define PG8_WAIT_V(n) asm volatile("s_waitcnt vmcnt(" #n ")" ::: "memory")
; #define PG8_WAIT_L(n) asm volatile("s_waitcnt lgkmcnt(" #n ")" ::: "memory")
; #define PG8_BAR __builtin_amdgcn_s_barrier()
; #define PG8_SCHED __builtin_amdgcn_sched_barrier(0)
; template <class Epi, bool ALIGN_EPI>
; DI void gemm_phase(lptr lds, const Gemm g, const StaticOrder& S, const Epi& E) {
;     ...
;             PG8_LDA(At, 1, 1); PG8_STAGE(PG8_SB(1, 0), b3, voffB); PG8_STAGE(PG8_SB(1, 1), b3 + hstepB, voffB); PG8_STAGE(PG8_SA(1, 0), a3, voffA);
;             PG8_WAIT_V(8); PG8_WAIT_L(0); PG8_BAR; PG8_MMA(1, 0, At, B0); PG8_MMA(1, 1, At, B1); PG8_BAR; PG8_SCHED;
;         }
;     ...
;         E.template run<2>(acc, cur, wr, wc, fr, fq);
	s_add_i32 s28, s38, s41
	v_lshl_add_u64 v[198:199], v[198:199], 0, s[12:13]
	s_mov_b32 m0, s28
	ds_read_b128 v[182:185], v213 offset:49152
	ds_read_b128 v[186:189], v213 offset:50176
	ds_read_b128 v[190:193], v213 offset:51200
	ds_read_b128 v[194:197], v213 offset:52224
	ds_read_b128 v[214:217], v213 offset:53248
	ds_read_b128 v[218:221], v213 offset:54272
	ds_read_b128 v[222:225], v213 offset:55296
	ds_read_b128 v[226:229], v213 offset:56320
	global_load_lds_dwordx4 v[198:199], off
	s_add_i32 m0, s28, 0x2000
	s_add_u32 s6, s6, 0x40080
	v_lshl_add_u64 v[198:199], v[230:231], 0, s[12:13]
	s_addc_u32 s7, s7, 0
	s_add_i32 s28, s39, s41
	global_load_lds_dwordx4 v[198:199], off
	v_lshl_add_u64 v[198:199], s[6:7], 0, v[130:131]
	s_mov_b32 m0, s28
	s_nop 0
	global_load_lds_dwordx4 v[198:199], off
	v_lshl_add_u64 v[198:199], s[6:7], 0, v[134:135]
	s_add_i32 m0, s28, 0x2000
	s_nop 0
	global_load_lds_dwordx4 v[198:199], off
	v_lshl_add_u64 v[198:199], v[232:233], 0, s[12:13]
	s_mov_b32 m0, s49
	s_nop 0
	global_load_lds_dwordx4 v[198:199], off
	v_lshl_add_u64 v[198:199], v[234:235], 0, s[12:13]
	s_mov_b32 m0, s50
	s_nop 0
	global_load_lds_dwordx4 v[198:199], off
	s_waitcnt vmcnt(8)
	s_waitcnt lgkmcnt(0)
	s_barrier
	s_setprio 1
	s_waitcnt lgkmcnt(0)
	v_mfma_f32_16x16x32_bf16 v[60:63], v[148:151], v[182:185], v[60:63]
	v_mfma_f32_16x16x32_bf16 v[56:59], v[158:161], v[182:185], v[56:59]
	v_mfma_f32_16x16x32_bf16 v[44:47], v[148:151], v[190:193], v[44:47]
	v_mfma_f32_16x16x32_bf16 v[40:43], v[158:161], v[190:193], v[40:43]
	v_mfma_f32_16x16x32_bf16 v[28:31], v[148:151], v[214:217], v[28:31]
	v_mfma_f32_16x16x32_bf16 v[24:27], v[158:161], v[214:217], v[24:27]
	v_mfma_f32_16x16x32_bf16 v[12:15], v[148:151], v[222:225], v[12:15]
	v_mfma_f32_16x16x32_bf16 v[8:11], v[158:161], v[222:225], v[8:11]
	v_mfma_f32_16x16x32_bf16 v[60:63], v[154:157], v[186:189], v[60:63]
	v_mfma_f32_16x16x32_bf16 v[56:59], v[162:165], v[186:189], v[56:59]
	v_mfma_f32_16x16x32_bf16 v[44:47], v[154:157], v[194:197], v[44:47]
	v_mfma_f32_16x16x32_bf16 v[40:43], v[162:165], v[194:197], v[40:43]
	v_mfma_f32_16x16x32_bf16 v[28:31], v[154:157], v[218:221], v[28:31]
	v_mfma_f32_16x16x32_bf16 v[24:27], v[162:165], v[218:221], v[24:27]
	v_mfma_f32_16x16x32_bf16 v[12:15], v[154:157], v[226:229], v[12:15]
	v_mfma_f32_16x16x32_bf16 v[8:11], v[162:165], v[226:229], v[8:11]
	s_setprio 0
	s_setprio 1
	v_mfma_f32_16x16x32_bf16 v[52:55], v[166:169], v[182:185], v[52:55]
	v_mfma_f32_16x16x32_bf16 v[48:51], v[174:177], v[182:185], v[48:51]
	v_mfma_f32_16x16x32_bf16 v[36:39], v[166:169], v[190:193], v[36:39]
	v_mfma_f32_16x16x32_bf16 v[32:35], v[174:177], v[190:193], v[32:35]
	v_mfma_f32_16x16x32_bf16 v[20:23], v[166:169], v[214:217], v[20:23]
	v_mfma_f32_16x16x32_bf16 v[16:19], v[174:177], v[214:217], v[16:19]
	v_mfma_f32_16x16x32_bf16 v[4:7], v[166:169], v[222:225], v[4:7]
	v_mfma_f32_16x16x32_bf16 v[0:3], v[174:177], v[222:225], v[0:3]
	v_mfma_f32_16x16x32_bf16 v[52:55], v[170:173], v[186:189], v[52:55]
	v_mfma_f32_16x16x32_bf16 v[48:51], v[178:181], v[186:189], v[48:51]
	v_mfma_f32_16x16x32_bf16 v[36:39], v[170:173], v[194:197], v[36:39]
	v_mfma_f32_16x16x32_bf16 v[32:35], v[178:181], v[194:197], v[32:35]
	v_mfma_f32_16x16x32_bf16 v[20:23], v[170:173], v[218:221], v[20:23]
	v_mfma_f32_16x16x32_bf16 v[16:19], v[178:181], v[218:221], v[16:19]
	v_mfma_f32_16x16x32_bf16 v[4:7], v[170:173], v[226:229], v[4:7]
	v_mfma_f32_16x16x32_bf16 v[0:3], v[178:181], v[226:229], v[0:3]
	s_setprio 0
	s_barrier
	s_add_i32 s37, s37, 2
	s_add_u32 s4, s4, 0x100
	s_addc_u32 s5, s5, 0
	s_add_u32 s35, s35, 0x100
	s_addc_u32 s36, s36, 0
	s_cmp_gt_u32 s37, 13
	s_cbranch_scc0 .LBB0_225
	s_and_b64 vcc, exec, s[14:15]
	s_cbranch_vccnz .LBB0_276
	s_cmp_gt_i32 s34, 19
	s_mov_b64 s[4:5], -1
	s_cbranch_scc1 .LBB0_277

; #define PG8_BAR __builtin_amdgcn_s_barrier()
;     DI void prep(const Unit& u, int tid) const { if (tid < 256) *(LAS f32x4*)(tbl + (u.ui & 1) * 4096 + tid * 16) = factors(u.r0 + tid); }
; template <class Epi, bool ALIGN_EPI>
; DI void gemm_phase(lptr lds, const Gemm g, const StaticOrder& S, const Epi& E) {
;     ...
;         if (!has_next) break;
; #pragma unroll
;         for (int a = 0; a < 2; ++a)
; #pragma unroll
;             for (int b = 0; b < 2; ++b)
; #pragma unroll
;                 for (int m = 0; m < 4; ++m)
; #pragma unroll
;                     for (int n = 0; n < 2; ++n) acc[a][b][m][n] = (f32x4){0.f, 0.f, 0.f, 0.f};
;         cur = nxt; cA = nA; cB = nB; ++ui;
;         if constexpr (Epi::RESCALE) E.prep(cur, tid);
;         if constexpr (ALIGN_EPI) { if (wr == 1) PG8_BAR; }
.LBB0_275:
	s_mov_b32 s98, 1
	s_andn2_b64 vcc, exec, s[2:3]
	s_mov_b64 s[2:3], -1
	s_cbranch_vccnz .LBB0_217
	s_branch .LBB0_323

; #define PG8_MMA(ai, bj, At, Bt) do { __builtin_amdgcn_s_setprio(1); _Pragma("unroll") for (int m = 0; m < 4; ++m) _Pragma("unroll") for (int n = 0; n < 2; ++n) _Pragma("unroll") for (int k = 0; k < 2; ++k) \
;         acc[ai][bj][m][n] = __builtin_amdgcn_mfma_f32_16x16x32_bf16(Bt[n][k], At[m][k], acc[ai][bj][m][n], 0, 0, 0); __builtin_amdgcn_s_setprio(0); } while (0)
; #define PG8_WAIT_V(n) asm volatile("s_waitcnt vmcnt(" #n ")" ::: "memory")
; #define PG8_WAIT_L(n) asm volatile("s_waitcnt lgkmcnt(" #n ")" ::: "memory")
; #define PG8_BAR __builtin_amdgcn_s_barrier()
; #define PG8_SCHED __builtin_amdgcn_sched_barrier(0)
; template <class Epi, bool ALIGN_EPI>
; DI void gemm_phase(lptr lds, const Gemm g, const StaticOrder& S, const Epi& E) {
;     ...
;             PG8_WAIT_V(8); PG8_WAIT_L(0); PG8_BAR; PG8_MMA(0, 0, At, B0); PG8_MMA(0, 1, At, B1); PG8_BAR; PG8_SCHED;
.Lrx_ip_0:
	s_waitcnt vmcnt(32)
	s_branch .Lrx_ip_0b

; #define LAS __attribute__((address_space(3)))
; DI bf16x8 tr_pair(lptr p0, lptr p1) { const s16x4 a = ldstr(p0), b = ldstr(p1); return (bf16x8){a.x, a.y, a.z, a.w, b.x, b.y, b.z, b.w}; }
; DI u32x2 pack4(f32x4 a) { u32x2 w; w.x = cvt_pk_bf16(a.x, a.y); w.y = cvt_pk_bf16(a.z, a.w); return w; }
; DI f32x4 mfma16(bf16x8 a, bf16x8 b, f32x4 c) { return __builtin_amdgcn_mfma_f32_16x16x32_bf16(a, b, c, 0, 0, 0); }
; DI float ex2(float x) { return __builtin_amdgcn_exp2f(x); }
; DI void lds_barrier() { asm volatile("s_waitcnt lgkmcnt(0)" ::: "memory"); __builtin_amdgcn_s_barrier(); asm volatile("" ::: "memory"); }
;     ...
;     const float l2g = log2f(1.f - exp2f(-5.f - (float)h));
;     const float g64 = ex2(64.f * l2g);
;     const int nt = wave >> 1, mtb = 2 * (wave & 1);
;     const int vrow = tid >> 3, vch = tid & 7;
;     const float vdec = ex2((float)(63 - vrow) * l2g);
;     ...
;         if (pmode != 1) {
; #pragma unroll
;         for (int mt4 = 0; mt4 < 4; ++mt4)
; #pragma unroll
;             for (int ni = 0; ni < 2; ++ni) accSt[mt4][ni] = accSt[mt4][ni] * g64;
; #pragma unroll
;         for (int kk = 0; kk < 2; ++kk) { const int r0 = 32 * kk + 8 * g4 + (l15 >> 2);
;             bf16x8 bfr[2];
; #pragma unroll
;             for (int ni = 0; ni < 2; ++ni) { lptr k0 = L + R_KS + r0 * QP + (32 * wave + 16 * ni + 4 * (l15 & 3)) * 2; bfr[ni] = tr_pair(k0, k0 + 4 * QP); }
; #pragma unroll
;             for (int mt4 = 0; mt4 < 4; ++mt4) { lptr v0 = L + R_VD + r0 * VP + (16 * mt4 + 4 * (l15 & 3)) * 2; const bf16x8 afr = tr_pair(v0, v0 + 4 * VP);
; #pragma unroll
;                 for (int ni = 0; ni < 2; ++ni) accSt[mt4][ni] = mfma16(afr, bfr[ni], accSt[mt4][ni]); } }
;         }
;         lds_barrier();
; #pragma unroll
;         for (int mt4 = 0; mt4 < 4; ++mt4)
; #pragma unroll
;             for (int ni = 0; ni < 2; ++ni) *(LAS u32x2*)(L + R_ST + (32 * wave + 16 * ni + l15) * VP + (16 * mt4 + 4 * g4) * 2) = pack4(accSt[mt4][ni]);
.LBB0_561:
	v_cvt_f32_ubyte0_e32 v0, s33
	v_sub_f32_e32 v0, 0xc0a00000, v0
	v_cmp_gt_f32_e32 vcc, s23, v0
	s_and_b64 s[0:1], vcc, exec
	s_cselect_b32 s0, 0xffffffc0, 0
	v_cndmask_b32_e32 v2, 0, v212, vcc
	v_add_f32_e32 v0, v0, v2
	v_exp_f32_e32 v0, v0
	s_waitcnt vmcnt(0)
	v_cvt_pk_bf16_f32 v72, v68, v69
	v_cvt_pk_bf16_f32 v73, v70, v71
	ds_write_b64 v211, v[72:73] offset:2304
	v_ldexp_f32 v0, v0, s0
	v_sub_f32_e32 v0, 1.0, v0
	v_cmp_gt_f32_e32 vcc, s24, v0
	s_and_b64 s[0:1], vcc, exec
	s_cselect_b32 s0, 32, 0
	v_ldexp_f32 v0, v0, s0
	v_log_f32_e32 v0, v0
	v_cndmask_b32_e32 v2, 0, v213, vcc
	s_lshl_b32 s0, s6, 7
	s_and_b32 s0, s0, 0x180
	v_sub_f32_e32 v0, v0, v2
	v_mul_f32_e64 v72, |v171|, v0
	v_exp_f32_e32 v136, v72
	v_mul_f32_e64 v72, |v172|, v0
	v_exp_f32_e32 v137, v72
	v_mul_f32_e64 v72, |v173|, v0
	v_exp_f32_e32 v138, v72
	v_mul_f32_e64 v72, |v174|, v0
	v_exp_f32_e32 v139, v72
	v_mul_f32_e64 v72, |v175|, v0
	v_exp_f32_e32 v140, v72
	v_mul_f32_e64 v72, |v176|, v0
	v_exp_f32_e32 v141, v72
	v_mul_f32_e64 v72, |v177|, v0
	v_exp_f32_e32 v142, v72
	v_mul_f32_e64 v72, |v178|, v0
	v_exp_f32_e32 v143, v72
	v_mul_f32_e64 v72, |v179|, v0
	v_exp_f32_e32 v144, v72
	v_mul_f32_e64 v72, |v180|, v0
	v_exp_f32_e32 v145, v72
	v_mul_f32_e64 v72, |v181|, v0
	v_exp_f32_e32 v146, v72
	v_mul_f32_e64 v72, |v182|, v0
	v_exp_f32_e32 v147, v72
	v_mul_f32_e64 v72, |v183|, v0
	v_mul_f32_e32 v3, 0x42800000, v0
	v_mul_f32_e32 v74, v0, v168
	v_mul_f32_e32 v2, v0, v170
	v_exp_f32_e32 v148, v72
	v_mul_f32_e64 v72, |v184|, v0
	v_exp_f32_e32 v2, v2
	v_exp_f32_e32 v128, v3
	v_exp_f32_e32 v130, v74
	v_exp_f32_e32 v149, v72
	v_mul_f32_e64 v72, |v185|, v0
	v_mul_f32_e64 v0, |v186|, v0
	s_or_b32 s1, s0, s34
	v_exp_f32_e32 v150, v72
	v_exp_f32_e32 v151, v0
	s_or_b32 s6, s1, s31
	v_add_u32_e32 v0, s35, v169
	v_lshl_add_u64 v[156:157], s[6:7], 0, v[110:111]
	s_or_b32 s6, s34, s31
	v_lshlrev_b64 v[154:155], 4, v[0:1]
	s_or_b32 s0, s6, s0
	s_mov_b32 s1, s7
	s_mov_b32 s30, 0
	v_mov_b32_e32 v3, v2
	v_mov_b32_e32 v132, v2
	v_mov_b32_e32 v133, v2
	v_mov_b32_e32 v134, v128
	v_mov_b32_e32 v135, v128
	v_mov_b32_e32 v131, v130
	v_lshl_or_b32 v154, s33, 2, v154
	v_lshl_add_u64 v[158:159], s[0:1], 0, v[112:113]
	v_lshl_add_u64 v[160:161], s[6:7], 0, v[114:115]
	v_lshl_add_u64 v[162:163], s[6:7], 0, v[116:117]
	v_lshl_add_u64 v[164:165], s[6:7], 0, v[118:119]
	s_lshl_b32 s6, s29, 16
	s_mov_b32 s31, 1
	s_waitcnt vmcnt(2)
	s_branch .LBB0_563
.LBB0_562:
	s_or_b64 exec, exec, s[0:1]
	ds_read_b64_tr_b16 v[74:75], v207 offset:576
	s_waitcnt lgkmcnt(1)
	ds_read_b64_tr_b16 v[72:73], v207
	ds_read_b64_tr_b16 v[78:79], v206 offset:35904
	ds_read_b64_tr_b16 v[76:77], v206 offset:33792
	ds_read_b64_tr_b16 v[82:83], v206 offset:35936
	ds_read_b64_tr_b16 v[80:81], v206 offset:33824
	ds_read_b64_tr_b16 v[84:85], v207 offset:32
	ds_read_b64_tr_b16 v[88:89], v207 offset:64
	ds_read_b64_tr_b16 v[92:93], v207 offset:96
	ds_read_b64_tr_b16 v[86:87], v207 offset:608
	ds_read_b64_tr_b16 v[90:91], v207 offset:640
	ds_read_b64_tr_b16 v[94:95], v207 offset:672
	v_mov_b32_e32 v129, v128
	v_pk_mul_f32 v[62:63], v[128:129], v[62:63]
	v_pk_mul_f32 v[60:61], v[134:135], v[60:61]
	v_pk_mul_f32 v[46:47], v[128:129], v[46:47]
	v_pk_mul_f32 v[44:45], v[134:135], v[44:45]
	s_waitcnt lgkmcnt(8)
	v_mfma_f32_16x16x32_bf16 v[60:63], v[72:75], v[76:79], v[60:63]
	v_mul_f32_e64 v42, v128, v42
	v_mul_f32_e64 v43, v129, v43
	v_pk_mul_f32 v[40:41], v[134:135], v[40:41]
	v_pk_mul_f32 v[50:51], v[128:129], v[50:51]
	s_waitcnt lgkmcnt(2)
	v_mfma_f32_16x16x32_bf16 v[44:47], v[84:87], v[76:79], v[44:47]
	v_mul_f32_e64 v48, v134, v48
	v_mul_f32_e64 v49, v135, v49
	v_pk_mul_f32 v[54:55], v[128:129], v[54:55]
	v_pk_mul_f32 v[52:53], v[134:135], v[52:53]
	v_pk_mul_f32 v[58:59], v[128:129], v[58:59]
	v_pk_mul_f32 v[56:57], v[134:135], v[56:57]
	v_pk_mul_f32 v[66:67], v[128:129], v[66:67]
	v_pk_mul_f32 v[64:65], v[134:135], v[64:65]
	v_pk_mul_f32 v[70:71], v[128:129], v[70:71]
	v_pk_mul_f32 v[68:69], v[134:135], v[68:69]
	v_mfma_f32_16x16x32_bf16 v[40:43], v[72:75], v[80:83], v[40:43]
	v_add_u32_e32 v0, 0x800, v208
	s_add_i32 s30, s30, 0x10000
	s_add_i32 s31, s31, 1
	v_mfma_f32_16x16x32_bf16 v[48:51], v[84:87], v[80:83], v[48:51]
	v_lshl_add_u64 v[154:155], v[154:155], 0, s[8:9]
	v_lshl_add_u64 v[156:157], v[156:157], 0, s[10:11]
	v_lshl_add_u64 v[158:159], v[158:159], 0, s[10:11]
	s_waitcnt lgkmcnt(1)
	v_mfma_f32_16x16x32_bf16 v[52:55], v[88:91], v[76:79], v[52:55]
	v_lshl_add_u64 v[160:161], v[160:161], 0, s[10:11]
	v_lshl_add_u64 v[162:163], v[162:163], 0, s[10:11]
	s_cmp_lg_u32 s6, s30
	v_mfma_f32_16x16x32_bf16 v[56:59], v[88:91], v[80:83], v[56:59]
	v_lshl_add_u64 v[164:165], v[164:165], 0, s[10:11]
	s_waitcnt lgkmcnt(0)
	v_mfma_f32_16x16x32_bf16 v[64:67], v[92:95], v[76:79], v[64:67]
	v_mfma_f32_16x16x32_bf16 v[68:71], v[92:95], v[80:83], v[68:71]
	ds_read_b64_tr_b16 v[72:73], v207 offset:4608
	ds_read_b64_tr_b16 v[74:75], v207 offset:5184
	ds_read_b64_tr_b16 v[76:77], v206 offset:50688
	ds_read_b64_tr_b16 v[78:79], v206 offset:52800
	ds_read_b64_tr_b16 v[82:83], v206 offset:52832
	ds_read_b64_tr_b16 v[80:81], v206 offset:50720
	ds_read_b64_tr_b16 v[84:85], v207 offset:4640
	ds_read_b64_tr_b16 v[88:89], v207 offset:4672
	ds_read_b64_tr_b16 v[92:93], v207 offset:4704
	ds_read_b64_tr_b16 v[86:87], v207 offset:5216
	ds_read_b64_tr_b16 v[90:91], v207 offset:5248
	ds_read_b64_tr_b16 v[94:95], v207 offset:5280
	s_waitcnt lgkmcnt(0)
	s_barrier
	s_waitcnt lgkmcnt(8)
	v_mfma_f32_16x16x32_bf16 v[60:63], v[72:75], v[76:79], v[60:63]
	s_waitcnt lgkmcnt(2)
	v_mfma_f32_16x16x32_bf16 v[44:47], v[84:87], v[76:79], v[44:47]
	v_mfma_f32_16x16x32_bf16 v[40:43], v[72:75], v[80:83], v[40:43]
	s_nop 4
	v_cvt_pk_bf16_f32 v72, v60, v61
	v_cvt_pk_bf16_f32 v73, v62, v63
	v_mfma_f32_16x16x32_bf16 v[48:51], v[84:87], v[80:83], v[48:51]
	s_waitcnt lgkmcnt(1)
	v_mfma_f32_16x16x32_bf16 v[52:55], v[88:91], v[76:79], v[52:55]
	v_cvt_pk_bf16_f32 v74, v40, v41
	v_cvt_pk_bf16_f32 v75, v42, v43
	s_waitcnt lgkmcnt(0)
	v_mfma_f32_16x16x32_bf16 v[64:67], v[92:95], v[76:79], v[64:67]
	v_cvt_pk_bf16_f32 v76, v44, v45
	v_cvt_pk_bf16_f32 v77, v46, v47
	ds_write2_b64 v208, v[72:73], v[76:77] offset1:4
	v_mfma_f32_16x16x32_bf16 v[56:59], v[88:91], v[80:83], v[56:59]
	v_cvt_pk_bf16_f32 v72, v48, v49
	v_cvt_pk_bf16_f32 v73, v50, v51
	ds_write2_b64 v0, v[74:75], v[72:73] offset0:32 offset1:36
	v_mfma_f32_16x16x32_bf16 v[68:71], v[92:95], v[80:83], v[68:71]
	v_cvt_pk_bf16_f32 v72, v52, v53
	v_cvt_pk_bf16_f32 v73, v54, v55
	v_cvt_pk_bf16_f32 v76, v64, v65
	v_cvt_pk_bf16_f32 v77, v66, v67
	v_cvt_pk_bf16_f32 v74, v56, v57
	v_cvt_pk_bf16_f32 v75, v58, v59
	ds_write2_b64 v208, v[72:73], v[76:77] offset0:8 offset1:12
	s_nop 0
	v_cvt_pk_bf16_f32 v72, v68, v69
	v_cvt_pk_bf16_f32 v73, v70, v71
	ds_write2_b64 v0, v[74:75], v[72:73] offset0:40 offset1:44
	s_cbranch_scc0 .LBB0_534
	s_waitcnt vmcnt(5)
; #define LAS __attribute__((address_space(3)))
; DI float bf_lo(unsigned w) { return __uint_as_float(w << 16); }
; DI float bf_hi(unsigned w) { return __uint_as_float(w & 0xffff0000u); }
; DI bf16x8 pack8(f32x4 a, f32x4 b) { u32x4 w; w.x = cvt_pk_bf16(a.x, a.y); w.y = cvt_pk_bf16(a.z, a.w); w.z = cvt_pk_bf16(b.x, b.y); w.w = cvt_pk_bf16(b.z, b.w); return __builtin_bit_cast(bf16x8, w); }
; DI void lds_barrier() { asm volatile("s_waitcnt lgkmcnt(0)" ::: "memory"); __builtin_amdgcn_s_barrier(); asm volatile("" ::: "memory"); }
;     ...
;     auto gload = [&](int ch) {
;         const unsigned c0 = (unsigned)ch * 65536u;
; #pragma unroll
;         for (int k = 0; k < 4; ++k) { pq[k] = *(const u32x4*)(Qb + (c0 + qoff + k * 16384u)); pk[k] = *(const u32x4*)(Kb + (c0 + qoff + k * 16384u)); }
;         pv = *(const u32x4*)(Vb + (c0 + voff));
;     };
;     ...
; #pragma unroll
;         for (int k = 0; k < 4; ++k) { const int c = tid + 512 * k, row = c >> 5, cc = c & 31; *(LAS u32x4*)(L + R_QS + row * QP + cc * 16) = pq[k]; *(LAS u32x4*)(L + R_KS + row * QP + cc * 16) = pk[k]; }
;         *(LAS u32x4*)(L + R_VS + vrow * VP2 + vch * 16) = pv;
;         { f32x4 a, c2; a.x = bf_lo(pv.x) * vdec; a.y = bf_hi(pv.x) * vdec; a.z = bf_lo(pv.y) * vdec; a.w = bf_hi(pv.y) * vdec; c2.x = bf_lo(pv.z) * vdec; c2.y = bf_hi(pv.z) * vdec; c2.z = bf_lo(pv.w) * vdec; c2.w = bf_hi(pv.w) * vdec;
;           *(LAS bf16x8*)(L + R_VD + vrow * VP + vch * 16) = pack8(a, c2); }
;         lds_barrier();
;         if (ch + 1 < nch) gload(ch + 1);
.LBB0_563:
	v_lshlrev_b32_e32 v72, 16, v36
	v_and_b32_e32 v73, 0xffff0000, v36
	v_lshlrev_b32_e32 v74, 16, v37
	v_and_b32_e32 v75, 0xffff0000, v37
	v_lshlrev_b32_e32 v76, 16, v38
	v_and_b32_e32 v77, 0xffff0000, v38
	v_lshlrev_b32_e32 v78, 16, v39
	v_and_b32_e32 v79, 0xffff0000, v39
	v_pk_mul_f32 v[72:73], v[130:131], v[72:73]
	v_pk_mul_f32 v[74:75], v[130:131], v[74:75]
	v_pk_mul_f32 v[76:77], v[130:131], v[76:77]
	v_pk_mul_f32 v[78:79], v[130:131], v[78:79]
	v_cvt_pk_bf16_f32 v72, v72, v73
	v_cvt_pk_bf16_f32 v73, v74, v75
	v_cvt_pk_bf16_f32 v74, v76, v77
	v_cvt_pk_bf16_f32 v75, v78, v79
	ds_write_b128 v191, v[16:19]
	ds_write_b128 v191, v[4:7] offset:33792
	ds_write_b128 v192, v[8:11]
	ds_write_b128 v192, v[12:15] offset:33792
	ds_write_b128 v191, v[20:23] offset:16896
	ds_write_b128 v191, v[24:27] offset:50688
	ds_write_b128 v193, v[28:31]
	ds_write_b128 v193, v[32:35] offset:33792
	ds_write_b128 v194, v[36:39]
	ds_write_b128 v195, v[72:75]
	s_waitcnt lgkmcnt(0)
	s_barrier
	s_cmp_lt_u32 s31, s29
	s_cselect_b64 s[0:1], -1, 0
	s_cmp_ge_u32 s31, s29
	s_cbranch_scc1 .LBB0_565
	v_lshl_add_u64 v[28:29], s[94:95], 0, v[160:161]
	v_add_co_u32_e32 v4, vcc, 0x3020000, v28
	v_lshl_add_u64 v[8:9], s[94:95], 0, v[162:163]
	s_nop 0
	v_addc_co_u32_e32 v5, vcc, 0, v29, vcc
	v_add_co_u32_e32 v6, vcc, 0xb220000, v28
	v_lshl_add_u64 v[20:21], s[94:95], 0, v[164:165]
	s_nop 0
	v_addc_co_u32_e32 v7, vcc, 0, v29, vcc
	v_add_co_u32_e32 v10, vcc, 0x3000000, v8
	v_lshl_add_u64 v[36:37], s[94:95], 0, v[158:159]
	s_nop 0
	v_addc_co_u32_e32 v11, vcc, 0, v9, vcc
	v_add_co_u32_e32 v12, vcc, 0xb200000, v8
	global_load_dwordx4 v[16:19], v[4:5], off
	s_nop 0
	global_load_dwordx4 v[4:7], v[6:7], off
	v_addc_co_u32_e32 v13, vcc, 0, v9, vcc
	v_add_co_u32_e32 v22, vcc, 0x3000000, v20
	global_load_dwordx4 v[8:11], v[10:11], off
	s_nop 0
	global_load_dwordx4 v[12:15], v[12:13], off
	v_addc_co_u32_e32 v23, vcc, 0, v21, vcc
	v_add_co_u32_e32 v24, vcc, 0xb200000, v20
	s_nop 1
	v_addc_co_u32_e32 v25, vcc, 0, v21, vcc
	v_add_co_u32_e32 v30, vcc, 0x3038000, v28
	global_load_dwordx4 v[20:23], v[22:23], off
	s_nop 0
	global_load_dwordx4 v[24:27], v[24:25], off
	v_addc_co_u32_e32 v31, vcc, 0, v29, vcc
	v_add_co_u32_e32 v32, vcc, 0xb238000, v28
	s_nop 1
	v_addc_co_u32_e32 v33, vcc, 0, v29, vcc
	global_load_dwordx4 v[28:31], v[30:31], off
	s_nop 0
	global_load_dwordx4 v[32:35], v[32:33], off
	s_nop 0
	global_load_dwordx4 v[36:39], v[36:37], off

;     DI bool next(int i, Unit& u) const {
;         const long L = (long)i * G + c; if (L >= nwg) return false;
;         int wgid = (int)L; { const int q = nwg / NXCD, r = nwg % NXCD, xcd = wgid % NXCD, off = wgid / NXCD; wgid = (xcd < r ? xcd * (q + 1) : r * (q + 1) + (xcd - r) * q) + off; }
;         const int nig = WGM * nN, gid = wgid / nig, fm = gid * WGM, gsz = (nM - fm) < WGM ? (nM - fm) : WGM;
;         u.pm = fm + ((wgid % nig) % gsz); u.pn = (wgid % nig) / gsz; u.r0 = u.pm * BM; u.ui = i; return true;
; __global__ void __launch_bounds__(512, 2) fwd_mega(Params p) {
;     ...
;         pg8::Gemm g{P + G_RQ, DM, (const bf16_t*)(ws + WS_WCQ), MP, DM, DM}; pg8::StaticOrder S; S.init(MP, DM, G, cb);
;         EpiCq E{P, (const float*)(ws + WS_SSQ2)}; pg8::gemm_phase<EpiCq, true>(L, g, S, E);
.LBB0_955:
	s_cmp_lt_i32 s66, 7
	s_cselect_b64 s[2:3], -1, 0
	s_and_b64 s[4:5], s[2:3], s[0:1]
	s_andn2_b64 vcc, exec, s[4:5]
	s_cbranch_vccnz .LBB0_997
	s_mov_b32 s98, 0
	s_add_u32 s0, s94, 0x1680000
	s_addc_u32 s1, s95, 0
	s_add_u32 s6, s94, 0x104000
	s_addc_u32 s7, s95, 0
	v_lshrrev_b32_e32 v0, 1, v153
	v_readfirstlane_b32 s12, v153
	v_lshlrev_b32_e32 v161, 4, v153
	s_waitcnt vmcnt(0)
	v_lshrrev_b32_e32 v168, 3, v153
	v_and_b32_e32 v160, 15, v153
	s_cmpk_gt_i32 s64, 0x3ff
	v_and_b32_e32 v162, 24, v0
	s_cbranch_scc1 .LBB0_980
	s_ashr_i32 s30, s64, 31
	s_lshr_b32 s2, s30, 29
	s_add_i32 s9, s64, s2
	s_and_b32 s2, s9, -8
	s_sub_i32 s10, s64, s2
	s_cmp_gt_i32 s10, -1
	s_cbranch_scc0 .LBB0_959
	s_lshl_b32 s8, s10, 7
	s_cbranch_execz .LBB0_960
	s_branch .LBB0_961

; #define PG8_STAGE(bufoff, gbase, voff) do { _Pragma("unroll") for (int _i = 0; _i < 2; ++_i) \
;         __builtin_amdgcn_global_load_lds((const unsigned*)((const char*)(gbase) + (voff)[_i]), (LAS unsigned*)(lds + (bufoff) + ldsw + _i * 8192), 16, 0, 0); } while (0)
; #define PG8_LDA(dst, b, h) do { _Pragma("unroll") for (int m = 0; m < 4; ++m) _Pragma("unroll") for (int k = 0; k < 2; ++k) dst[m][k] = *(const LAS bf16x8*)(lds + PG8_SA(b, h) + aoff + m * 2048 + k * 1024); } while (0)
; #define PG8_BAR __builtin_amdgcn_s_barrier()
; template <class Epi, bool ALIGN_EPI>
; DI void gemm_phase(lptr lds, const Gemm g, const StaticOrder& S, const Epi& E) {
;     ...
;     const char* cA = (const char*)g.A + (size_t)cur.pm * tstepA; const char* cB = (const char*)g.Bt + (size_t)cur.pn * tstepB;
;     if constexpr (Epi::RESCALE) E.prep(cur, tid);
;     PG8_STAGE(PG8_SB(0, 0), cB, voffB); PG8_STAGE(PG8_SB(0, 1), cB + hstepB, voffB); PG8_STAGE(PG8_SA(0, 0), cA, voffA); PG8_STAGE(PG8_SA(0, 1), cA + hstepA, voffA);
;     if (wr == 1) PG8_BAR;
;     PG8_WAIT_V(2); PG8_BAR;
;     PG8_STAGE(PG8_SB(1, 0), cB + kstep, voffB); PG8_STAGE(PG8_SA(1, 0), cA + kstep, voffA); PG8_STAGE(PG8_SB(1, 1), cB + hstepB + kstep, voffB);
;     PG8_WAIT_V(6); PG8_BAR;
;     for (;;) {
;         const bool has_next = S.next(ui + 1, nxt);
;         const char* nA = has_next ? (const char*)g.A + (size_t)nxt.pm * tstepA : cA; const char* nB = has_next ? (const char*)g.Bt + (size_t)nxt.pn * tstepB : cB;
;         for (int t = 0; t < nt; t += 2) {
;             const bool last = (t == nt - 2);
;             if constexpr (Epi::RESCALE) { if (t == 4 || t == 8 || t == 12) E.rescale(acc, cur, t >> 2, wr, fr); }
;             const char* a1 = cA + (size_t)(t + 1) * kstep;
;             const char* a2 = last ? nA : cA + (size_t)(t + 2) * kstep; const char* b2 = last ? nB : cB + (size_t)(t + 2) * kstep;
;             const char* a3 = a2 + kstep; const char* b3 = b2 + kstep;
;             PG8_LDB(B0, 0, 0); PG8_LDB(B1, 0, 1); PG8_SCHED; PG8_LDA(At, 0, 0); PG8_STAGE(PG8_SA(1, 1), a1 + hstepA, voffA);
;             PG8_WAIT_V(8); PG8_WAIT_L(0); PG8_BAR; PG8_MMA(0, 0, At, B0); PG8_MMA(0, 1, At, B1); PG8_BAR; PG8_SCHED;
;     template <int NAI> DI void run(AccRef acc, const Unit& u, int wr, int wc, int fr, int fq) const {
;     ...
;             for (int m = 0; m < 4; ++m) rsv[ai][m] = ssq[EPI_ROW(ai, m)];
.LBB0_972:
	s_ashr_i32 s19, s18, 31
	s_lshl_b64 s[20:21], s[18:19], 19
	s_add_u32 s20, s82, s20
	s_addc_u32 s21, s83, s21
	s_and_b64 s[22:23], s[2:3], exec
	s_cselect_b32 s19, s21, s25
	s_cselect_b32 s47, s20, s24
	s_ashr_i32 s17, s16, 31
	s_lshl_b64 s[22:23], s[16:17], 19
	s_add_u32 s22, s0, s22
	s_addc_u32 s23, s1, s23
	s_and_b64 s[28:29], s[2:3], exec
	s_cselect_b32 s17, s23, s27
	s_cselect_b32 s48, s22, s26
	s_add_u32 s24, s24, 0x40080
	s_addc_u32 s25, s25, 0
	s_add_u32 s49, s26, 0x100
	v_mov_b32_e32 v0, 0
	s_addc_u32 s50, s27, 0
	s_mov_b32 s51, -2
	v_mov_b32_e32 v1, v0
	v_mov_b32_e32 v2, v0
	v_mov_b32_e32 v3, v0
	v_mov_b32_e32 v4, v0
	v_mov_b32_e32 v5, v0
	v_mov_b32_e32 v6, v0
	v_mov_b32_e32 v7, v0
	v_mov_b32_e32 v12, v0
	v_mov_b32_e32 v13, v0
	v_mov_b32_e32 v14, v0
	v_mov_b32_e32 v15, v0
	v_mov_b32_e32 v20, v0
	v_mov_b32_e32 v21, v0
	v_mov_b32_e32 v22, v0
	v_mov_b32_e32 v23, v0
	v_mov_b32_e32 v28, v0
	v_mov_b32_e32 v29, v0
	v_mov_b32_e32 v30, v0
	v_mov_b32_e32 v31, v0
	v_mov_b32_e32 v36, v0
	v_mov_b32_e32 v37, v0
	v_mov_b32_e32 v38, v0
	v_mov_b32_e32 v39, v0
	v_mov_b32_e32 v44, v0
	v_mov_b32_e32 v45, v0
	v_mov_b32_e32 v46, v0
	v_mov_b32_e32 v47, v0
	v_mov_b32_e32 v52, v0
	v_mov_b32_e32 v53, v0
	v_mov_b32_e32 v54, v0
	v_mov_b32_e32 v55, v0
	v_mov_b32_e32 v8, v0
	v_mov_b32_e32 v9, v0
	v_mov_b32_e32 v10, v0
	v_mov_b32_e32 v11, v0
	v_mov_b32_e32 v16, v0
	v_mov_b32_e32 v17, v0
	v_mov_b32_e32 v18, v0
	v_mov_b32_e32 v19, v0
	v_mov_b32_e32 v24, v0
	v_mov_b32_e32 v25, v0
	v_mov_b32_e32 v26, v0
	v_mov_b32_e32 v27, v0
	v_mov_b32_e32 v32, v0
	v_mov_b32_e32 v33, v0
	v_mov_b32_e32 v34, v0
	v_mov_b32_e32 v35, v0
	v_mov_b32_e32 v40, v0
	v_mov_b32_e32 v41, v0
	v_mov_b32_e32 v42, v0
	v_mov_b32_e32 v43, v0
	v_mov_b32_e32 v48, v0
	v_mov_b32_e32 v49, v0
	v_mov_b32_e32 v50, v0
	v_mov_b32_e32 v51, v0
	v_mov_b32_e32 v56, v0
	v_mov_b32_e32 v57, v0
	v_mov_b32_e32 v58, v0
	v_mov_b32_e32 v59, v0
	v_mov_b32_e32 v60, v0
	v_mov_b32_e32 v61, v0
	v_mov_b32_e32 v62, v0
	v_mov_b32_e32 v63, v0
	v_mov_b32_e32 v64, v0
	v_mov_b32_e32 v65, v0
	v_mov_b32_e32 v66, v0
	v_mov_b32_e32 v67, v0
	v_mov_b32_e32 v68, v0
	v_mov_b32_e32 v69, v0
	v_mov_b32_e32 v70, v0
	v_mov_b32_e32 v71, v0
	v_mov_b32_e32 v76, v0
	v_mov_b32_e32 v77, v0
	v_mov_b32_e32 v78, v0
	v_mov_b32_e32 v79, v0
	v_mov_b32_e32 v84, v0
	v_mov_b32_e32 v85, v0
	v_mov_b32_e32 v86, v0
	v_mov_b32_e32 v87, v0
	v_mov_b32_e32 v92, v0
	v_mov_b32_e32 v93, v0
	v_mov_b32_e32 v94, v0
	v_mov_b32_e32 v95, v0
	v_mov_b32_e32 v100, v0
	v_mov_b32_e32 v101, v0
	v_mov_b32_e32 v102, v0
	v_mov_b32_e32 v103, v0
	v_mov_b32_e32 v104, v0
	v_mov_b32_e32 v105, v0
	v_mov_b32_e32 v106, v0
	v_mov_b32_e32 v107, v0
	v_mov_b32_e32 v108, v0
	v_mov_b32_e32 v109, v0
	v_mov_b32_e32 v110, v0
	v_mov_b32_e32 v111, v0
	v_mov_b32_e32 v72, v0
	v_mov_b32_e32 v73, v0
	v_mov_b32_e32 v74, v0
	v_mov_b32_e32 v75, v0
	v_mov_b32_e32 v80, v0
	v_mov_b32_e32 v81, v0
	v_mov_b32_e32 v82, v0
	v_mov_b32_e32 v83, v0
	v_mov_b32_e32 v88, v0
	v_mov_b32_e32 v89, v0
	v_mov_b32_e32 v90, v0
	v_mov_b32_e32 v91, v0
	v_mov_b32_e32 v96, v0
	v_mov_b32_e32 v97, v0
	v_mov_b32_e32 v98, v0
	v_mov_b32_e32 v99, v0
	v_mov_b32_e32 v112, v0
	v_mov_b32_e32 v113, v0
	v_mov_b32_e32 v114, v0
	v_mov_b32_e32 v115, v0
	v_mov_b32_e32 v116, v0
	v_mov_b32_e32 v117, v0
	v_mov_b32_e32 v118, v0
	v_mov_b32_e32 v119, v0
	v_mov_b32_e32 v120, v0
	v_mov_b32_e32 v121, v0
	v_mov_b32_e32 v122, v0
	v_mov_b32_e32 v123, v0
	v_mov_b32_e32 v124, v0
	v_mov_b32_e32 v125, v0
	v_mov_b32_e32 v126, v0
	v_mov_b32_e32 v127, v0
	v_add_u32_e32 v232, s45, v156
	v_lshlrev_b32_e32 v232, 2, v232
	global_load_dword v233, v232, s[6:7]
	global_load_dword v234, v232, s[6:7] offset:64
	global_load_dword v235, v232, s[6:7] offset:128
	global_load_dword v236, v232, s[6:7] offset:192
	global_load_dword v237, v232, s[6:7] offset:512
	global_load_dword v238, v232, s[6:7] offset:576
	global_load_dword v239, v232, s[6:7] offset:640
	global_load_dword v240, v232, s[6:7] offset:704
	s_cmp_lg_u32 s98, 0
	s_cselect_b32 s99, -2, 0x7fffff00
.LBB0_973:
	ds_read_b128 v[144:147], v159
	ds_read_b128 v[148:151], v159 offset:1024
	ds_read_b128 v[170:173], v159 offset:2048
	ds_read_b128 v[174:177], v159 offset:3072
	ds_read_b128 v[178:181], v163
	ds_read_b128 v[182:185], v163 offset:1024
	ds_read_b128 v[186:189], v163 offset:2048
	ds_read_b128 v[190:193], v163 offset:3072
	s_add_u32 s26, s24, 0xfffc0080
	s_addc_u32 s27, s25, -1
	s_cmp_eq_u32 s51, 12
	s_cselect_b32 s29, s19, s27
	s_cselect_b32 s28, s47, s26
	s_cselect_b32 s27, s17, s50
	s_cselect_b32 s26, s48, s49
	v_lshl_add_u64 v[154:155], s[24:25], 0, v[136:137]
	s_add_i32 m0, s33, 0xc000
	ds_read_b128 v[194:197], v164
	ds_read_b128 v[198:201], v164 offset:1024
	ds_read_b128 v[202:205], v164 offset:2048
	ds_read_b128 v[206:209], v164 offset:3072
	ds_read_b128 v[210:213], v164 offset:4096
	ds_read_b128 v[214:217], v164 offset:5120
	ds_read_b128 v[218:221], v164 offset:6144
	ds_read_b128 v[222:225], v164 offset:7168
	global_load_lds_dwordx4 v[154:155], off
	v_lshl_add_u64 v[154:155], s[24:25], 0, v[138:139]
	s_add_i32 m0, s33, 0xe000
	s_nop 0
	global_load_lds_dwordx4 v[154:155], off
	s_cmp_eq_u32 s51, s99
	s_cbranch_scc1 .Lrx_cq_0
	s_waitcnt vmcnt(8)
; #define PG8_STAGE(bufoff, gbase, voff) do { _Pragma("unroll") for (int _i = 0; _i < 2; ++_i) \
;         __builtin_amdgcn_global_load_lds((const unsigned*)((const char*)(gbase) + (voff)[_i]), (LAS unsigned*)(lds + (bufoff) + ldsw + _i * 8192), 16, 0, 0); } while (0)
; #define PG8_LDA(dst, b, h) do { _Pragma("unroll") for (int m = 0; m < 4; ++m) _Pragma("unroll") for (int k = 0; k < 2; ++k) dst[m][k] = *(const LAS bf16x8*)(lds + PG8_SA(b, h) + aoff + m * 2048 + k * 1024); } while (0)
; #define PG8_LDB(dst, b, h) do { _Pragma("unroll") for (int n = 0; n < 2; ++n) _Pragma("unroll") for (int k = 0; k < 2; ++k) dst[n][k] = *(const LAS bf16x8*)(lds + PG8_SB(b, h) + boff + n * 2048 + k * 1024); } while (0)
; #define PG8_MMA(ai, bj, At, Bt) do { __builtin_amdgcn_s_setprio(1); _Pragma("unroll") for (int m = 0; m < 4; ++m) _Pragma("unroll") for (int n = 0; n < 2; ++n) _Pragma("unroll") for (int k = 0; k < 2; ++k) \
;         acc[ai][bj][m][n] = __builtin_amdgcn_mfma_f32_16x16x32_bf16(Bt[n][k], At[m][k], acc[ai][bj][m][n], 0, 0, 0); __builtin_amdgcn_s_setprio(0); } while (0)
; #define PG8_WAIT_V(n) asm volatile("s_waitcnt vmcnt(" #n ")" ::: "memory")
; #define PG8_WAIT_L(n) asm volatile("s_waitcnt lgkmcnt(" #n ")" ::: "memory")
; #define PG8_BAR __builtin_amdgcn_s_barrier()
; #define PG8_SCHED __builtin_amdgcn_sched_barrier(0)
; template <class Epi, bool ALIGN_EPI>
; DI void gemm_phase(lptr lds, const Gemm g, const StaticOrder& S, const Epi& E) {
;     ...
;             PG8_LDB(B0, 0, 0); PG8_LDB(B1, 0, 1); PG8_SCHED; PG8_LDA(At, 0, 0); PG8_STAGE(PG8_SA(1, 1), a1 + hstepA, voffA);
;             PG8_WAIT_V(8); PG8_WAIT_L(0); PG8_BAR; PG8_MMA(0, 0, At, B0); PG8_MMA(0, 1, At, B1); PG8_BAR; PG8_SCHED;
;             PG8_LDA(At, 0, 1); PG8_STAGE(PG8_SB(0, 0), b2, voffB); PG8_STAGE(PG8_SB(0, 1), b2 + hstepB, voffB); PG8_STAGE(PG8_SA(0, 0), a2, voffA);
;             PG8_WAIT_V(8); PG8_WAIT_L(0); PG8_BAR; PG8_MMA(1, 0, At, B0); PG8_MMA(1, 1, At, B1); PG8_BAR; PG8_SCHED;
.Lrx_cq_0b:
	s_waitcnt lgkmcnt(0)
	s_barrier
	s_setprio 1
	s_waitcnt lgkmcnt(0)
	v_mfma_f32_16x16x32_bf16 v[124:127], v[144:147], v[194:197], v[124:127]
	v_mfma_f32_16x16x32_bf16 v[120:123], v[170:173], v[194:197], v[120:123]
	v_mfma_f32_16x16x32_bf16 v[116:119], v[144:147], v[202:205], v[116:119]
	v_mfma_f32_16x16x32_bf16 v[112:115], v[170:173], v[202:205], v[112:115]
	v_mfma_f32_16x16x32_bf16 v[96:99], v[144:147], v[210:213], v[96:99]
	v_mfma_f32_16x16x32_bf16 v[88:91], v[170:173], v[210:213], v[88:91]
	v_mfma_f32_16x16x32_bf16 v[80:83], v[144:147], v[218:221], v[80:83]
	v_mfma_f32_16x16x32_bf16 v[72:75], v[170:173], v[218:221], v[72:75]
	v_mfma_f32_16x16x32_bf16 v[124:127], v[148:151], v[198:201], v[124:127]
	v_mfma_f32_16x16x32_bf16 v[120:123], v[174:177], v[198:201], v[120:123]
	v_mfma_f32_16x16x32_bf16 v[116:119], v[148:151], v[206:209], v[116:119]
	v_mfma_f32_16x16x32_bf16 v[112:115], v[174:177], v[206:209], v[112:115]
	v_mfma_f32_16x16x32_bf16 v[96:99], v[148:151], v[214:217], v[96:99]
	v_mfma_f32_16x16x32_bf16 v[88:91], v[174:177], v[214:217], v[88:91]
	v_mfma_f32_16x16x32_bf16 v[80:83], v[148:151], v[222:225], v[80:83]
	v_mfma_f32_16x16x32_bf16 v[72:75], v[174:177], v[222:225], v[72:75]
	s_setprio 0
	s_setprio 1
	v_mfma_f32_16x16x32_bf16 v[108:111], v[178:181], v[194:197], v[108:111]
	v_mfma_f32_16x16x32_bf16 v[104:107], v[186:189], v[194:197], v[104:107]
	v_mfma_f32_16x16x32_bf16 v[100:103], v[178:181], v[202:205], v[100:103]
	v_mfma_f32_16x16x32_bf16 v[92:95], v[186:189], v[202:205], v[92:95]
	v_mfma_f32_16x16x32_bf16 v[84:87], v[178:181], v[210:213], v[84:87]
	v_mfma_f32_16x16x32_bf16 v[76:79], v[186:189], v[210:213], v[76:79]
	v_mfma_f32_16x16x32_bf16 v[68:71], v[178:181], v[218:221], v[68:71]
	v_mfma_f32_16x16x32_bf16 v[64:67], v[186:189], v[218:221], v[64:67]
	v_mfma_f32_16x16x32_bf16 v[108:111], v[182:185], v[198:201], v[108:111]
	v_mfma_f32_16x16x32_bf16 v[104:107], v[190:193], v[198:201], v[104:107]
	v_mfma_f32_16x16x32_bf16 v[100:103], v[182:185], v[206:209], v[100:103]
	v_mfma_f32_16x16x32_bf16 v[92:95], v[190:193], v[206:209], v[92:95]
	v_mfma_f32_16x16x32_bf16 v[84:87], v[182:185], v[214:217], v[84:87]
	v_mfma_f32_16x16x32_bf16 v[76:79], v[190:193], v[214:217], v[76:79]
	v_mfma_f32_16x16x32_bf16 v[68:71], v[182:185], v[222:225], v[68:71]
	v_mfma_f32_16x16x32_bf16 v[64:67], v[190:193], v[222:225], v[64:67]
	s_setprio 0
	s_barrier
	s_add_i32 s52, s41, s31
	v_lshl_add_u64 v[154:155], s[26:27], 0, v[130:131]
	s_mov_b32 m0, s52
	ds_read_b128 v[194:197], v164 offset:16384
	ds_read_b128 v[198:201], v164 offset:17408
	ds_read_b128 v[202:205], v164 offset:18432
	ds_read_b128 v[206:209], v164 offset:19456
	ds_read_b128 v[210:213], v164 offset:20480
	ds_read_b128 v[214:217], v164 offset:21504
	ds_read_b128 v[218:221], v164 offset:22528
	ds_read_b128 v[222:225], v164 offset:23552
	global_load_lds_dwordx4 v[154:155], off
	s_add_i32 m0, s52, 0x2000
	s_add_u32 s52, s26, 0x40000
	v_lshl_add_u64 v[166:167], s[26:27], 0, v[134:135]
	s_addc_u32 s53, s27, 0
	s_add_i32 s54, s42, s31
	global_load_lds_dwordx4 v[166:167], off
	v_lshl_add_u64 v[226:227], s[52:53], 0, v[130:131]
	s_mov_b32 m0, s54
	v_lshl_add_u64 v[228:229], s[28:29], 0, v[132:133]
	global_load_lds_dwordx4 v[226:227], off
	v_lshl_add_u64 v[226:227], s[52:53], 0, v[134:135]
	s_add_i32 m0, s54, 0x2000
	s_nop 0
	global_load_lds_dwordx4 v[226:227], off
	v_lshl_add_u64 v[226:227], s[28:29], 0, v[128:129]
	s_mov_b32 m0, s33
	s_nop 0
	global_load_lds_dwordx4 v[226:227], off
	s_mov_b32 m0, s34
	s_nop 0
	global_load_lds_dwordx4 v[228:229], off
	s_cmp_eq_u32 s51, s99
	s_cbranch_scc1 .Lrx_cq_1
	s_waitcnt vmcnt(8)
.Lrx_cq_1b:
	s_waitcnt lgkmcnt(0)
	s_barrier
	s_setprio 1
	s_waitcnt lgkmcnt(0)
	v_mfma_f32_16x16x32_bf16 v[60:63], v[144:147], v[194:197], v[60:63]
	v_mfma_f32_16x16x32_bf16 v[56:59], v[170:173], v[194:197], v[56:59]
	v_mfma_f32_16x16x32_bf16 v[48:51], v[144:147], v[202:205], v[48:51]
	v_mfma_f32_16x16x32_bf16 v[40:43], v[170:173], v[202:205], v[40:43]
	v_mfma_f32_16x16x32_bf16 v[32:35], v[144:147], v[210:213], v[32:35]
	v_mfma_f32_16x16x32_bf16 v[24:27], v[170:173], v[210:213], v[24:27]
	v_mfma_f32_16x16x32_bf16 v[16:19], v[144:147], v[218:221], v[16:19]
	v_mfma_f32_16x16x32_bf16 v[8:11], v[170:173], v[218:221], v[8:11]
	v_mfma_f32_16x16x32_bf16 v[60:63], v[148:151], v[198:201], v[60:63]
	v_mfma_f32_16x16x32_bf16 v[56:59], v[174:177], v[198:201], v[56:59]
	v_mfma_f32_16x16x32_bf16 v[48:51], v[148:151], v[206:209], v[48:51]
	v_mfma_f32_16x16x32_bf16 v[40:43], v[174:177], v[206:209], v[40:43]
	v_mfma_f32_16x16x32_bf16 v[32:35], v[148:151], v[214:217], v[32:35]
	v_mfma_f32_16x16x32_bf16 v[24:27], v[174:177], v[214:217], v[24:27]
	v_mfma_f32_16x16x32_bf16 v[16:19], v[148:151], v[222:225], v[16:19]
	v_mfma_f32_16x16x32_bf16 v[8:11], v[174:177], v[222:225], v[8:11]
	s_setprio 0
	s_setprio 1
	v_mfma_f32_16x16x32_bf16 v[52:55], v[178:181], v[194:197], v[52:55]
	v_mfma_f32_16x16x32_bf16 v[44:47], v[186:189], v[194:197], v[44:47]
	v_mfma_f32_16x16x32_bf16 v[36:39], v[178:181], v[202:205], v[36:39]
	v_mfma_f32_16x16x32_bf16 v[28:31], v[186:189], v[202:205], v[28:31]
	v_mfma_f32_16x16x32_bf16 v[20:23], v[178:181], v[210:213], v[20:23]
	v_mfma_f32_16x16x32_bf16 v[12:15], v[186:189], v[210:213], v[12:15]
	v_mfma_f32_16x16x32_bf16 v[4:7], v[178:181], v[218:221], v[4:7]
	v_mfma_f32_16x16x32_bf16 v[0:3], v[186:189], v[218:221], v[0:3]
	v_mfma_f32_16x16x32_bf16 v[52:55], v[182:185], v[198:201], v[52:55]
	v_mfma_f32_16x16x32_bf16 v[44:47], v[190:193], v[198:201], v[44:47]
	v_mfma_f32_16x16x32_bf16 v[36:39], v[182:185], v[206:209], v[36:39]
	v_mfma_f32_16x16x32_bf16 v[28:31], v[190:193], v[206:209], v[28:31]
	v_mfma_f32_16x16x32_bf16 v[20:23], v[182:185], v[214:217], v[20:23]
	v_mfma_f32_16x16x32_bf16 v[12:15], v[190:193], v[214:217], v[12:15]
	v_mfma_f32_16x16x32_bf16 v[4:7], v[182:185], v[222:225], v[4:7]
	v_mfma_f32_16x16x32_bf16 v[0:3], v[190:193], v[222:225], v[0:3]
	s_setprio 0
	s_barrier
; #define PG8_STAGE(bufoff, gbase, voff) do { _Pragma("unroll") for (int _i = 0; _i < 2; ++_i) \
;         __builtin_amdgcn_global_load_lds((const unsigned*)((const char*)(gbase) + (voff)[_i]), (LAS unsigned*)(lds + (bufoff) + ldsw + _i * 8192), 16, 0, 0); } while (0)
; #define PG8_LDA(dst, b, h) do { _Pragma("unroll") for (int m = 0; m < 4; ++m) _Pragma("unroll") for (int k = 0; k < 2; ++k) dst[m][k] = *(const LAS bf16x8*)(lds + PG8_SA(b, h) + aoff + m * 2048 + k * 1024); } while (0)
; #define PG8_LDB(dst, b, h) do { _Pragma("unroll") for (int n = 0; n < 2; ++n) _Pragma("unroll") for (int k = 0; k < 2; ++k) dst[n][k] = *(const LAS bf16x8*)(lds + PG8_SB(b, h) + boff + n * 2048 + k * 1024); } while (0)
; #define PG8_MMA(ai, bj, At, Bt) do { __builtin_amdgcn_s_setprio(1); _Pragma("unroll") for (int m = 0; m < 4; ++m) _Pragma("unroll") for (int n = 0; n < 2; ++n) _Pragma("unroll") for (int k = 0; k < 2; ++k) \
;         acc[ai][bj][m][n] = __builtin_amdgcn_mfma_f32_16x16x32_bf16(Bt[n][k], At[m][k], acc[ai][bj][m][n], 0, 0, 0); __builtin_amdgcn_s_setprio(0); } while (0)
; #define PG8_WAIT_V(n) asm volatile("s_waitcnt vmcnt(" #n ")" ::: "memory")
; #define PG8_WAIT_L(n) asm volatile("s_waitcnt lgkmcnt(" #n ")" ::: "memory")
; #define PG8_BAR __builtin_amdgcn_s_barrier()
; #define PG8_SCHED __builtin_amdgcn_sched_barrier(0)
; template <class Epi, bool ALIGN_EPI>
; DI void gemm_phase(lptr lds, const Gemm g, const StaticOrder& S, const Epi& E) {
;     ...
;             PG8_LDB(B0, 1, 0); PG8_LDB(B1, 1, 1); PG8_SCHED; PG8_LDA(At, 1, 0); PG8_STAGE(PG8_SA(0, 1), a2 + hstepA, voffA);
;             PG8_WAIT_V(8); PG8_WAIT_L(0); PG8_BAR; PG8_MMA(0, 0, At, B0); PG8_MMA(0, 1, At, B1); PG8_BAR; PG8_SCHED;
;             PG8_LDA(At, 1, 1); PG8_STAGE(PG8_SB(1, 0), b3, voffB); PG8_STAGE(PG8_SB(1, 1), b3 + hstepB, voffB); PG8_STAGE(PG8_SA(1, 0), a3, voffA);
;             PG8_WAIT_V(8); PG8_WAIT_L(0); PG8_BAR; PG8_MMA(1, 0, At, B0); PG8_MMA(1, 1, At, B1); PG8_BAR; PG8_SCHED;
	s_add_i32 s52, 0, 0x18000
	v_add_u32_e32 v169, s52, v157
	s_add_i32 s53, 0, 0x1c000
	ds_read_b128 v[144:147], v169
	ds_read_b128 v[148:151], v169 offset:1024
	ds_read_b128 v[170:173], v169 offset:2048
	ds_read_b128 v[174:177], v169 offset:3072
	v_add_u32_e32 v169, s53, v157
	ds_read_b128 v[178:181], v169
	ds_read_b128 v[182:185], v169 offset:1024
	ds_read_b128 v[186:189], v169 offset:2048
	ds_read_b128 v[190:193], v169 offset:3072
	s_add_u32 s28, s28, 0x40000
	s_addc_u32 s29, s29, 0
	s_mov_b32 m0, s35
	v_lshl_add_u64 v[230:231], s[28:29], 0, v[128:129]
	ds_read_b128 v[194:197], v164 offset:32768
	ds_read_b128 v[198:201], v164 offset:33792
	ds_read_b128 v[202:205], v164 offset:34816
	ds_read_b128 v[206:209], v164 offset:35840
	ds_read_b128 v[210:213], v164 offset:36864
	ds_read_b128 v[214:217], v164 offset:37888
	ds_read_b128 v[218:221], v164 offset:38912
	ds_read_b128 v[222:225], v164 offset:39936
	global_load_lds_dwordx4 v[230:231], off
	v_lshl_add_u64 v[230:231], s[28:29], 0, v[132:133]
	s_mov_b32 m0, s36
	s_nop 0
	global_load_lds_dwordx4 v[230:231], off
	s_waitcnt vmcnt(8)
	s_waitcnt lgkmcnt(0)
	s_barrier
	s_setprio 1
	s_waitcnt lgkmcnt(0)
	v_mfma_f32_16x16x32_bf16 v[124:127], v[144:147], v[194:197], v[124:127]
	v_mfma_f32_16x16x32_bf16 v[120:123], v[170:173], v[194:197], v[120:123]
	v_mfma_f32_16x16x32_bf16 v[116:119], v[144:147], v[202:205], v[116:119]
	v_mfma_f32_16x16x32_bf16 v[112:115], v[170:173], v[202:205], v[112:115]
	v_mfma_f32_16x16x32_bf16 v[96:99], v[144:147], v[210:213], v[96:99]
	v_mfma_f32_16x16x32_bf16 v[88:91], v[170:173], v[210:213], v[88:91]
	v_mfma_f32_16x16x32_bf16 v[80:83], v[144:147], v[218:221], v[80:83]
	v_mfma_f32_16x16x32_bf16 v[72:75], v[170:173], v[218:221], v[72:75]
	v_mfma_f32_16x16x32_bf16 v[124:127], v[148:151], v[198:201], v[124:127]
	v_mfma_f32_16x16x32_bf16 v[120:123], v[174:177], v[198:201], v[120:123]
	v_mfma_f32_16x16x32_bf16 v[116:119], v[148:151], v[206:209], v[116:119]
	v_mfma_f32_16x16x32_bf16 v[112:115], v[174:177], v[206:209], v[112:115]
	v_mfma_f32_16x16x32_bf16 v[96:99], v[148:151], v[214:217], v[96:99]
	v_mfma_f32_16x16x32_bf16 v[88:91], v[174:177], v[214:217], v[88:91]
	v_mfma_f32_16x16x32_bf16 v[80:83], v[148:151], v[222:225], v[80:83]
	v_mfma_f32_16x16x32_bf16 v[72:75], v[174:177], v[222:225], v[72:75]
	s_setprio 0
	s_setprio 1
	v_mfma_f32_16x16x32_bf16 v[108:111], v[178:181], v[194:197], v[108:111]
	v_mfma_f32_16x16x32_bf16 v[104:107], v[186:189], v[194:197], v[104:107]
	v_mfma_f32_16x16x32_bf16 v[100:103], v[178:181], v[202:205], v[100:103]
	v_mfma_f32_16x16x32_bf16 v[92:95], v[186:189], v[202:205], v[92:95]
	v_mfma_f32_16x16x32_bf16 v[84:87], v[178:181], v[210:213], v[84:87]
	v_mfma_f32_16x16x32_bf16 v[76:79], v[186:189], v[210:213], v[76:79]
	v_mfma_f32_16x16x32_bf16 v[68:71], v[178:181], v[218:221], v[68:71]
	v_mfma_f32_16x16x32_bf16 v[64:67], v[186:189], v[218:221], v[64:67]
	v_mfma_f32_16x16x32_bf16 v[108:111], v[182:185], v[198:201], v[108:111]
	v_mfma_f32_16x16x32_bf16 v[104:107], v[190:193], v[198:201], v[104:107]
	v_mfma_f32_16x16x32_bf16 v[100:103], v[182:185], v[206:209], v[100:103]
	v_mfma_f32_16x16x32_bf16 v[92:95], v[190:193], v[206:209], v[92:95]
	v_mfma_f32_16x16x32_bf16 v[84:87], v[182:185], v[214:217], v[84:87]
	v_mfma_f32_16x16x32_bf16 v[76:79], v[190:193], v[214:217], v[76:79]
	v_mfma_f32_16x16x32_bf16 v[68:71], v[182:185], v[222:225], v[68:71]
	v_mfma_f32_16x16x32_bf16 v[64:67], v[190:193], v[222:225], v[64:67]
	s_setprio 0
	s_barrier
	s_add_i32 s28, s52, s31
	v_lshl_add_u64 v[154:155], v[154:155], 0, s[10:11]
	s_mov_b32 m0, s28
	ds_read_b128 v[194:197], v164 offset:49152
	ds_read_b128 v[198:201], v164 offset:50176
	ds_read_b128 v[202:205], v164 offset:51200
	ds_read_b128 v[206:209], v164 offset:52224
	ds_read_b128 v[210:213], v164 offset:53248
	ds_read_b128 v[214:217], v164 offset:54272
	ds_read_b128 v[218:221], v164 offset:55296
	ds_read_b128 v[222:225], v164 offset:56320
	global_load_lds_dwordx4 v[154:155], off
	s_add_i32 m0, s28, 0x2000
	s_add_u32 s26, s26, 0x40080
	v_lshl_add_u64 v[154:155], v[166:167], 0, s[10:11]
	s_addc_u32 s27, s27, 0
	s_add_i32 s28, s53, s31
	global_load_lds_dwordx4 v[154:155], off
	v_lshl_add_u64 v[154:155], s[26:27], 0, v[130:131]
	s_mov_b32 m0, s28
	s_nop 0
	global_load_lds_dwordx4 v[154:155], off
	v_lshl_add_u64 v[154:155], s[26:27], 0, v[134:135]
	s_add_i32 m0, s28, 0x2000
	s_nop 0
	global_load_lds_dwordx4 v[154:155], off
	v_lshl_add_u64 v[154:155], v[226:227], 0, s[10:11]
	s_mov_b32 m0, s38
	s_nop 0
	global_load_lds_dwordx4 v[154:155], off
	v_lshl_add_u64 v[154:155], v[228:229], 0, s[10:11]
	s_mov_b32 m0, s39
	s_nop 0
	global_load_lds_dwordx4 v[154:155], off
	s_waitcnt vmcnt(8)
	s_waitcnt lgkmcnt(0)
	s_barrier
; DI void st8(bf16_t* p, f32x4 a, f32x4 b) { u32x4 w; w.x = cvt_pk_bf16(a.x, a.y); w.y = cvt_pk_bf16(a.z, a.w); w.z = cvt_pk_bf16(b.x, b.y); w.w = cvt_pk_bf16(b.z, b.w); *(u32x4*)p = w; }
; #define PG8_MMA(ai, bj, At, Bt) do { __builtin_amdgcn_s_setprio(1); _Pragma("unroll") for (int m = 0; m < 4; ++m) _Pragma("unroll") for (int n = 0; n < 2; ++n) _Pragma("unroll") for (int k = 0; k < 2; ++k) \
;         acc[ai][bj][m][n] = __builtin_amdgcn_mfma_f32_16x16x32_bf16(Bt[n][k], At[m][k], acc[ai][bj][m][n], 0, 0, 0); __builtin_amdgcn_s_setprio(0); } while (0)
; #define PG8_WAIT_V(n) asm volatile("s_waitcnt vmcnt(" #n ")" ::: "memory")
; #define PG8_WAIT_L(n) asm volatile("s_waitcnt lgkmcnt(" #n ")" ::: "memory")
; #define PG8_BAR __builtin_amdgcn_s_barrier()
; #define PG8_SCHED __builtin_amdgcn_sched_barrier(0)
; template <class Epi, bool ALIGN_EPI>
; DI void gemm_phase(lptr lds, const Gemm g, const StaticOrder& S, const Epi& E) {
;     ...
;             PG8_WAIT_V(8); PG8_WAIT_L(0); PG8_BAR; PG8_MMA(1, 0, At, B0); PG8_MMA(1, 1, At, B1); PG8_BAR; PG8_SCHED;
;         }
;         if constexpr (ALIGN_EPI) { if (wr == 0) PG8_BAR; }
;         E.template run<2>(acc, cur, wr, wc, fr, fq);
;     template <int NAI> DI void run(AccRef acc, const Unit& u, int wr, int wc, int fr, int fq) const {
;         const int cl = u.pn * 256 + wc * 32 + fq * 8;
;         float rsv[2][4];
; #pragma unroll
;         for (int ai = 0; ai < NAI; ++ai)
; #pragma unroll
;             for (int m = 0; m < 4; ++m) rsv[ai][m] = ssq[EPI_ROW(ai, m)];
; #pragma unroll
;         for (int ai = 0; ai < NAI; ++ai)
; #pragma unroll
;             for (int m = 0; m < 4; ++m) {
;                 const int row = EPI_ROW(ai, m); const float rs = 0.0625f * __builtin_amdgcn_rsqf(rsv[ai][m] * (1.f / DM) + EPS);
; #pragma unroll
;                 for (int bj = 0; bj < 2; ++bj) st8(P + G_RK + (size_t)row * 1024 + cl + bj * 128, acc[ai][bj][m][0] * rs, acc[ai][bj][m][1] * rs);
	s_setprio 1
	s_waitcnt lgkmcnt(0)
	v_mfma_f32_16x16x32_bf16 v[60:63], v[144:147], v[194:197], v[60:63]
	v_mfma_f32_16x16x32_bf16 v[56:59], v[170:173], v[194:197], v[56:59]
	v_mfma_f32_16x16x32_bf16 v[48:51], v[144:147], v[202:205], v[48:51]
	v_mfma_f32_16x16x32_bf16 v[40:43], v[170:173], v[202:205], v[40:43]
	v_mfma_f32_16x16x32_bf16 v[32:35], v[144:147], v[210:213], v[32:35]
	v_mfma_f32_16x16x32_bf16 v[24:27], v[170:173], v[210:213], v[24:27]
	v_mfma_f32_16x16x32_bf16 v[16:19], v[144:147], v[218:221], v[16:19]
	v_mfma_f32_16x16x32_bf16 v[8:11], v[170:173], v[218:221], v[8:11]
	v_mfma_f32_16x16x32_bf16 v[60:63], v[148:151], v[198:201], v[60:63]
	v_mfma_f32_16x16x32_bf16 v[56:59], v[174:177], v[198:201], v[56:59]
	v_mfma_f32_16x16x32_bf16 v[48:51], v[148:151], v[206:209], v[48:51]
	v_mfma_f32_16x16x32_bf16 v[40:43], v[174:177], v[206:209], v[40:43]
	v_mfma_f32_16x16x32_bf16 v[32:35], v[148:151], v[214:217], v[32:35]
	v_mfma_f32_16x16x32_bf16 v[24:27], v[174:177], v[214:217], v[24:27]
	v_mfma_f32_16x16x32_bf16 v[16:19], v[148:151], v[222:225], v[16:19]
	v_mfma_f32_16x16x32_bf16 v[8:11], v[174:177], v[222:225], v[8:11]
	s_setprio 0
	s_setprio 1
	v_mfma_f32_16x16x32_bf16 v[52:55], v[178:181], v[194:197], v[52:55]
	v_mfma_f32_16x16x32_bf16 v[44:47], v[186:189], v[194:197], v[44:47]
	v_mfma_f32_16x16x32_bf16 v[36:39], v[178:181], v[202:205], v[36:39]
	v_mfma_f32_16x16x32_bf16 v[28:31], v[186:189], v[202:205], v[28:31]
	v_mfma_f32_16x16x32_bf16 v[20:23], v[178:181], v[210:213], v[20:23]
	v_mfma_f32_16x16x32_bf16 v[12:15], v[186:189], v[210:213], v[12:15]
	v_mfma_f32_16x16x32_bf16 v[4:7], v[178:181], v[218:221], v[4:7]
	v_mfma_f32_16x16x32_bf16 v[0:3], v[186:189], v[218:221], v[0:3]
	v_mfma_f32_16x16x32_bf16 v[52:55], v[182:185], v[198:201], v[52:55]
	v_mfma_f32_16x16x32_bf16 v[44:47], v[190:193], v[198:201], v[44:47]
	v_mfma_f32_16x16x32_bf16 v[36:39], v[182:185], v[206:209], v[36:39]
	v_mfma_f32_16x16x32_bf16 v[28:31], v[190:193], v[206:209], v[28:31]
	v_mfma_f32_16x16x32_bf16 v[20:23], v[182:185], v[214:217], v[20:23]
	v_mfma_f32_16x16x32_bf16 v[12:15], v[190:193], v[214:217], v[12:15]
	v_mfma_f32_16x16x32_bf16 v[4:7], v[182:185], v[222:225], v[4:7]
	v_mfma_f32_16x16x32_bf16 v[0:3], v[190:193], v[222:225], v[0:3]
	s_setprio 0
	s_barrier
	s_add_i32 s51, s51, 2
	s_add_u32 s24, s24, 0x100
	s_addc_u32 s25, s25, 0
	s_add_u32 s49, s49, 0x100
	s_addc_u32 s50, s50, 0
	s_cmp_gt_u32 s51, 13
	s_cbranch_scc0 .LBB0_973
	s_and_b64 vcc, exec, s[12:13]
	s_cbranch_vccz .LBB0_976
	s_barrier
.LBB0_976:
	s_mov_b32 s98, 1
	v_add_u32_e32 v144, s45, v156
	v_ashrrev_i32_e32 v145, 31, v144
	v_add_u32_e32 v166, 16, v144
	v_lshl_add_u64 v[146:147], v[144:145], 2, s[6:7]
	v_ashrrev_i32_e32 v167, 31, v166
	v_add_u32_e32 v170, 32, v144
	v_mov_b32_e32 v169, v233
	v_lshl_add_u64 v[146:147], v[166:167], 2, s[6:7]
	v_ashrrev_i32_e32 v171, 31, v170
	v_lshl_add_u64 v[148:149], v[170:171], 2, s[6:7]
	v_mov_b32_e32 v188, v234
	v_mov_b32_e32 v189, v235
	v_lshl_or_b32 v172, s46, 8, v158
	v_add_u32_e32 v174, 48, v144
	v_add_u32_e32 v146, 0xb0, v144
	v_add_u32_e32 v154, 0x80, v144
	v_add_u32_e32 v150, 0x90, v144
	v_add_u32_e32 v148, 0xa0, v144
	v_ashrrev_i32_e32 v173, 31, v172
	v_ashrrev_i32_e32 v175, 31, v174
	v_ashrrev_i32_e32 v147, 31, v146
	v_ashrrev_i32_e32 v155, 31, v154
	v_ashrrev_i32_e32 v151, 31, v150
	v_ashrrev_i32_e32 v149, 31, v148
	v_lshlrev_b64 v[176:177], 11, v[144:145]
	v_lshlrev_b64 v[144:145], 1, v[172:173]
	v_lshl_add_u64 v[172:173], v[174:175], 2, s[6:7]
	v_lshl_add_u64 v[184:185], v[146:147], 2, s[6:7]
	v_lshl_add_u64 v[178:179], v[154:155], 2, s[6:7]
	v_lshl_add_u64 v[180:181], v[150:151], 2, s[6:7]
	v_lshl_add_u64 v[182:183], v[148:149], 2, s[6:7]
	v_mov_b32_e32 v190, v236
	v_mov_b32_e32 v191, v237
	v_mov_b32_e32 v192, v238
	v_mov_b32_e32 v193, v239
	s_nop 0
	v_mov_b32_e32 v185, v240
	v_lshl_add_u64 v[186:187], s[14:15], 0, v[176:177]
	v_lshl_add_u64 v[176:177], s[82:83], 0, v[176:177]
	v_lshlrev_b64 v[166:167], 11, v[166:167]
	v_lshl_add_u64 v[176:177], v[176:177], 0, v[144:145]
	v_lshl_add_u64 v[172:173], v[186:187], 0, v[144:145]
	v_lshl_add_u64 v[178:179], s[14:15], 0, v[166:167]
	v_lshl_add_u64 v[166:167], s[82:83], 0, v[166:167]
	v_add_co_u32_e32 v176, vcc, s43, v176
	v_lshl_add_u64 v[178:179], v[178:179], 0, v[144:145]
	s_nop 0
	v_addc_co_u32_e32 v177, vcc, 0, v177, vcc
	v_lshl_add_u64 v[166:167], v[166:167], 0, v[144:145]
	v_fmamk_f32 v169, v169, 0x3a800000, v165
	v_rsq_f32_e32 v169, v169
	v_fmamk_f32 v180, v188, 0x3a800000, v165
	v_rsq_f32_e32 v184, v180
	v_fmamk_f32 v181, v189, 0x3a800000, v165
	v_mul_f32_e32 v180, 0x3d800000, v169
	v_rsq_f32_e32 v186, v181
	v_mul_f32_e32 v184, 0x3d800000, v184
	v_pk_mul_f32 v[126:127], v[126:127], v[180:181] op_sel_hi:[1,0]
	v_pk_mul_f32 v[124:125], v[124:125], v[180:181] op_sel_hi:[1,0]
	v_pk_mul_f32 v[122:123], v[122:123], v[180:181] op_sel_hi:[1,0]
	v_pk_mul_f32 v[120:121], v[120:121], v[180:181] op_sel_hi:[1,0]
	v_pk_mul_f32 v[110:111], v[110:111], v[180:181] op_sel_hi:[1,0]
	v_pk_mul_f32 v[108:109], v[108:109], v[180:181] op_sel_hi:[1,0]
	v_pk_mul_f32 v[182:183], v[106:107], v[180:181] op_sel_hi:[1,0]
	v_pk_mul_f32 v[180:181], v[104:105], v[180:181] op_sel_hi:[1,0]
	v_cvt_pk_bf16_f32 v104, v124, v125
	v_cvt_pk_bf16_f32 v105, v126, v127
	v_cvt_pk_bf16_f32 v106, v120, v121
	v_cvt_pk_bf16_f32 v107, v122, v123
	v_cvt_pk_bf16_f32 v108, v108, v109
	v_cvt_pk_bf16_f32 v109, v110, v111
	v_cvt_pk_bf16_f32 v110, v180, v181
	v_pk_mul_f32 v[118:119], v[118:119], v[184:185] op_sel_hi:[1,0]
	v_pk_mul_f32 v[116:117], v[116:117], v[184:185] op_sel_hi:[1,0]
	v_pk_mul_f32 v[114:115], v[114:115], v[184:185] op_sel_hi:[1,0]
; DI void st8(bf16_t* p, f32x4 a, f32x4 b) { u32x4 w; w.x = cvt_pk_bf16(a.x, a.y); w.y = cvt_pk_bf16(a.z, a.w); w.z = cvt_pk_bf16(b.x, b.y); w.w = cvt_pk_bf16(b.z, b.w); *(u32x4*)p = w; }
;     template <int NAI> DI void run(AccRef acc, const Unit& u, int wr, int wc, int fr, int fq) const {
;     ...
;         for (int ai = 0; ai < NAI; ++ai)
; #pragma unroll
;             for (int m = 0; m < 4; ++m) {
;                 const int row = EPI_ROW(ai, m); const float rs = 0.0625f * __builtin_amdgcn_rsqf(rsv[ai][m] * (1.f / DM) + EPS);
; #pragma unroll
;                 for (int bj = 0; bj < 2; ++bj) st8(P + G_RK + (size_t)row * 1024 + cl + bj * 128, acc[ai][bj][m][0] * rs, acc[ai][bj][m][1] * rs);
;             }
	v_pk_mul_f32 v[112:113], v[112:113], v[184:185] op_sel_hi:[1,0]
	v_pk_mul_f32 v[120:121], v[94:95], v[184:185] op_sel_hi:[1,0]
	v_pk_mul_f32 v[122:123], v[92:93], v[184:185] op_sel_hi:[1,0]
	v_cvt_pk_bf16_f32 v92, v116, v117
	v_cvt_pk_bf16_f32 v93, v118, v119
	v_cvt_pk_bf16_f32 v94, v112, v113
	v_cvt_pk_bf16_f32 v95, v114, v115
	v_cvt_pk_bf16_f32 v111, v182, v183
	v_pk_mul_f32 v[102:103], v[102:103], v[184:185] op_sel_hi:[1,0]
	v_pk_mul_f32 v[100:101], v[100:101], v[184:185] op_sel_hi:[1,0]
	global_store_dwordx4 v[172:173], v[104:107], off
	global_store_dwordx4 v[176:177], v[108:111], off offset:256
	global_store_dwordx4 v[178:179], v[92:95], off
	v_cvt_pk_bf16_f32 v100, v100, v101
	v_cvt_pk_bf16_f32 v101, v102, v103
	v_add_co_u32_e32 v92, vcc, s43, v166
	v_cvt_pk_bf16_f32 v102, v122, v123
	v_cvt_pk_bf16_f32 v103, v120, v121
	v_addc_co_u32_e32 v93, vcc, 0, v167, vcc
	global_store_dwordx4 v[92:93], v[100:103], off offset:256
	v_mul_f32_e32 v92, 0x3d800000, v186
	v_lshlrev_b64 v[94:95], 11, v[170:171]
	v_lshl_add_u64 v[100:101], s[14:15], 0, v[94:95]
	v_pk_mul_f32 v[98:99], v[98:99], v[92:93] op_sel_hi:[1,0]
	v_pk_mul_f32 v[96:97], v[96:97], v[92:93] op_sel_hi:[1,0]
	v_pk_mul_f32 v[102:103], v[90:91], v[92:93] op_sel_hi:[1,0]
	v_pk_mul_f32 v[90:91], v[88:89], v[92:93] op_sel_hi:[1,0]
	v_lshl_add_u64 v[100:101], v[100:101], 0, v[144:145]
	v_cvt_pk_bf16_f32 v88, v96, v97
	v_cvt_pk_bf16_f32 v89, v98, v99
	v_cvt_pk_bf16_f32 v90, v90, v91
	v_cvt_pk_bf16_f32 v91, v102, v103
	v_pk_mul_f32 v[84:85], v[84:85], v[92:93] op_sel_hi:[1,0]
	global_store_dwordx4 v[100:101], v[88:91], off
	v_pk_mul_f32 v[86:87], v[86:87], v[92:93] op_sel_hi:[1,0]
	s_nop 0
	v_pk_mul_f32 v[90:91], v[78:79], v[92:93] op_sel_hi:[1,0]
	v_pk_mul_f32 v[78:79], v[76:77], v[92:93] op_sel_hi:[1,0]
	v_cvt_pk_bf16_f32 v76, v84, v85
	v_fmamk_f32 v84, v190, 0x3a800000, v165
	v_lshl_add_u64 v[88:89], s[82:83], 0, v[94:95]
	v_cvt_pk_bf16_f32 v77, v86, v87
	v_rsq_f32_e32 v86, v84
	v_lshl_add_u64 v[88:89], v[88:89], 0, v[144:145]
	v_add_co_u32_e32 v84, vcc, s43, v88
	v_cvt_pk_bf16_f32 v78, v78, v79
	v_cvt_pk_bf16_f32 v79, v90, v91
	v_addc_co_u32_e32 v85, vcc, 0, v89, vcc
	global_store_dwordx4 v[84:85], v[76:79], off offset:256
	s_nop 1
	v_mul_f32_e32 v76, 0x3d800000, v86
	v_lshlrev_b64 v[78:79], 11, v[174:175]
	v_lshl_add_u64 v[84:85], s[14:15], 0, v[78:79]
	v_pk_mul_f32 v[82:83], v[82:83], v[76:77] op_sel_hi:[1,0]
	v_pk_mul_f32 v[80:81], v[80:81], v[76:77] op_sel_hi:[1,0]
	v_pk_mul_f32 v[86:87], v[74:75], v[76:77] op_sel_hi:[1,0]
	v_pk_mul_f32 v[74:75], v[72:73], v[76:77] op_sel_hi:[1,0]
	v_lshl_add_u64 v[84:85], v[84:85], 0, v[144:145]
	v_cvt_pk_bf16_f32 v72, v80, v81
	v_cvt_pk_bf16_f32 v73, v82, v83
	v_cvt_pk_bf16_f32 v74, v74, v75
	v_cvt_pk_bf16_f32 v75, v86, v87
	v_pk_mul_f32 v[68:69], v[68:69], v[76:77] op_sel_hi:[1,0]
	global_store_dwordx4 v[84:85], v[72:75], off
	v_pk_mul_f32 v[70:71], v[70:71], v[76:77] op_sel_hi:[1,0]
	s_nop 0
	v_pk_mul_f32 v[74:75], v[66:67], v[76:77] op_sel_hi:[1,0]
	v_pk_mul_f32 v[66:67], v[64:65], v[76:77] op_sel_hi:[1,0]
	v_cvt_pk_bf16_f32 v64, v68, v69
	v_fmamk_f32 v68, v191, 0x3a800000, v165
	v_lshl_add_u64 v[72:73], s[82:83], 0, v[78:79]
	v_cvt_pk_bf16_f32 v65, v70, v71
	v_rsq_f32_e32 v70, v68
	v_lshl_add_u64 v[72:73], v[72:73], 0, v[144:145]
	v_add_co_u32_e32 v68, vcc, s43, v72
	v_cvt_pk_bf16_f32 v66, v66, v67
	v_cvt_pk_bf16_f32 v67, v74, v75
	v_addc_co_u32_e32 v69, vcc, 0, v73, vcc
	global_store_dwordx4 v[68:69], v[64:67], off offset:256
	s_nop 1
	v_mul_f32_e32 v64, 0x3d800000, v70
	v_lshlrev_b64 v[66:67], 11, v[154:155]
	v_lshl_add_u64 v[68:69], s[14:15], 0, v[66:67]
	v_pk_mul_f32 v[62:63], v[62:63], v[64:65] op_sel_hi:[1,0]
	v_pk_mul_f32 v[60:61], v[60:61], v[64:65] op_sel_hi:[1,0]
	v_pk_mul_f32 v[70:71], v[58:59], v[64:65] op_sel_hi:[1,0]
	v_pk_mul_f32 v[58:59], v[56:57], v[64:65] op_sel_hi:[1,0]
	v_lshl_add_u64 v[68:69], v[68:69], 0, v[144:145]
	v_cvt_pk_bf16_f32 v56, v60, v61
	v_cvt_pk_bf16_f32 v57, v62, v63
	v_cvt_pk_bf16_f32 v58, v58, v59
	v_cvt_pk_bf16_f32 v59, v70, v71
	v_pk_mul_f32 v[52:53], v[52:53], v[64:65] op_sel_hi:[1,0]
	global_store_dwordx4 v[68:69], v[56:59], off
	v_pk_mul_f32 v[54:55], v[54:55], v[64:65] op_sel_hi:[1,0]
	s_nop 0
	v_pk_mul_f32 v[58:59], v[46:47], v[64:65] op_sel_hi:[1,0]
	v_pk_mul_f32 v[46:47], v[44:45], v[64:65] op_sel_hi:[1,0]
; DI void st8(bf16_t* p, f32x4 a, f32x4 b) { u32x4 w; w.x = cvt_pk_bf16(a.x, a.y); w.y = cvt_pk_bf16(a.z, a.w); w.z = cvt_pk_bf16(b.x, b.y); w.w = cvt_pk_bf16(b.z, b.w); *(u32x4*)p = w; }
; #define PG8_BAR __builtin_amdgcn_s_barrier()
;     DI void prep(const Unit& u, int tid) const { if (tid < 256) *(LAS f32x4*)(tbl + (u.ui & 1) * 4096 + tid * 16) = factors(u.r0 + tid); }
; template <class Epi, bool ALIGN_EPI>
; DI void gemm_phase(lptr lds, const Gemm g, const StaticOrder& S, const Epi& E) {
;     ...
;         if (!has_next) break;
; #pragma unroll
;         for (int a = 0; a < 2; ++a)
; #pragma unroll
;             for (int b = 0; b < 2; ++b)
; #pragma unroll
;                 for (int m = 0; m < 4; ++m)
; #pragma unroll
;                     for (int n = 0; n < 2; ++n) acc[a][b][m][n] = (f32x4){0.f, 0.f, 0.f, 0.f};
;         cur = nxt; cA = nA; cB = nB; ++ui;
;         if constexpr (Epi::RESCALE) E.prep(cur, tid);
;         if constexpr (ALIGN_EPI) { if (wr == 1) PG8_BAR; }
;     template <int NAI> DI void run(AccRef acc, const Unit& u, int wr, int wc, int fr, int fq) const {
;     ...
;         for (int ai = 0; ai < NAI; ++ai)
; #pragma unroll
;             for (int m = 0; m < 4; ++m) {
;                 const int row = EPI_ROW(ai, m); const float rs = 0.0625f * __builtin_amdgcn_rsqf(rsv[ai][m] * (1.f / DM) + EPS);
; #pragma unroll
;                 for (int bj = 0; bj < 2; ++bj) st8(P + G_RK + (size_t)row * 1024 + cl + bj * 128, acc[ai][bj][m][0] * rs, acc[ai][bj][m][1] * rs);
;             }
	v_cvt_pk_bf16_f32 v44, v52, v53
	v_fmamk_f32 v52, v192, 0x3a800000, v165
	v_lshl_add_u64 v[56:57], s[82:83], 0, v[66:67]
	v_cvt_pk_bf16_f32 v45, v54, v55
	v_rsq_f32_e32 v54, v52
	v_lshl_add_u64 v[56:57], v[56:57], 0, v[144:145]
	v_add_co_u32_e32 v52, vcc, s43, v56
	v_cvt_pk_bf16_f32 v46, v46, v47
	v_cvt_pk_bf16_f32 v47, v58, v59
	v_addc_co_u32_e32 v53, vcc, 0, v57, vcc
	global_store_dwordx4 v[52:53], v[44:47], off offset:256
	s_nop 1
	v_mul_f32_e32 v44, 0x3d800000, v54
	v_lshlrev_b64 v[46:47], 11, v[150:151]
	v_lshl_add_u64 v[52:53], s[14:15], 0, v[46:47]
	v_pk_mul_f32 v[50:51], v[50:51], v[44:45] op_sel_hi:[1,0]
	v_pk_mul_f32 v[48:49], v[48:49], v[44:45] op_sel_hi:[1,0]
	v_pk_mul_f32 v[54:55], v[42:43], v[44:45] op_sel_hi:[1,0]
	v_pk_mul_f32 v[42:43], v[40:41], v[44:45] op_sel_hi:[1,0]
	v_lshl_add_u64 v[52:53], v[52:53], 0, v[144:145]
	v_cvt_pk_bf16_f32 v40, v48, v49
	v_cvt_pk_bf16_f32 v41, v50, v51
	v_cvt_pk_bf16_f32 v42, v42, v43
	v_cvt_pk_bf16_f32 v43, v54, v55
	v_pk_mul_f32 v[36:37], v[36:37], v[44:45] op_sel_hi:[1,0]
	global_store_dwordx4 v[52:53], v[40:43], off
	v_pk_mul_f32 v[38:39], v[38:39], v[44:45] op_sel_hi:[1,0]
	s_nop 0
	v_pk_mul_f32 v[42:43], v[30:31], v[44:45] op_sel_hi:[1,0]
	v_pk_mul_f32 v[30:31], v[28:29], v[44:45] op_sel_hi:[1,0]
	v_cvt_pk_bf16_f32 v28, v36, v37
	v_fmamk_f32 v36, v193, 0x3a800000, v165
	v_lshl_add_u64 v[40:41], s[82:83], 0, v[46:47]
	v_cvt_pk_bf16_f32 v29, v38, v39
	v_rsq_f32_e32 v38, v36
	v_lshl_add_u64 v[40:41], v[40:41], 0, v[144:145]
	v_add_co_u32_e32 v36, vcc, s43, v40
	v_cvt_pk_bf16_f32 v30, v30, v31
	v_cvt_pk_bf16_f32 v31, v42, v43
	v_addc_co_u32_e32 v37, vcc, 0, v41, vcc
	global_store_dwordx4 v[36:37], v[28:31], off offset:256
	s_nop 1
	v_mul_f32_e32 v28, 0x3d800000, v38
	v_lshlrev_b64 v[30:31], 11, v[148:149]
	v_lshl_add_u64 v[36:37], s[14:15], 0, v[30:31]
	v_pk_mul_f32 v[34:35], v[34:35], v[28:29] op_sel_hi:[1,0]
	v_pk_mul_f32 v[32:33], v[32:33], v[28:29] op_sel_hi:[1,0]
	v_pk_mul_f32 v[38:39], v[26:27], v[28:29] op_sel_hi:[1,0]
	v_pk_mul_f32 v[26:27], v[24:25], v[28:29] op_sel_hi:[1,0]
	v_lshl_add_u64 v[36:37], v[36:37], 0, v[144:145]
	v_cvt_pk_bf16_f32 v24, v32, v33
	v_cvt_pk_bf16_f32 v25, v34, v35
	v_cvt_pk_bf16_f32 v26, v26, v27
	v_cvt_pk_bf16_f32 v27, v38, v39
	v_pk_mul_f32 v[20:21], v[20:21], v[28:29] op_sel_hi:[1,0]
	global_store_dwordx4 v[36:37], v[24:27], off
	v_pk_mul_f32 v[22:23], v[22:23], v[28:29] op_sel_hi:[1,0]
	s_nop 0
	v_pk_mul_f32 v[26:27], v[14:15], v[28:29] op_sel_hi:[1,0]
	v_pk_mul_f32 v[14:15], v[12:13], v[28:29] op_sel_hi:[1,0]
	v_cvt_pk_bf16_f32 v12, v20, v21
	v_fmamk_f32 v20, v185, 0x3a800000, v165
	v_lshl_add_u64 v[24:25], s[82:83], 0, v[30:31]
	v_cvt_pk_bf16_f32 v13, v22, v23
	v_rsq_f32_e32 v22, v20
	v_lshl_add_u64 v[24:25], v[24:25], 0, v[144:145]
	v_add_co_u32_e32 v20, vcc, s43, v24
	v_cvt_pk_bf16_f32 v14, v14, v15
	v_cvt_pk_bf16_f32 v15, v26, v27
	v_addc_co_u32_e32 v21, vcc, 0, v25, vcc
	global_store_dwordx4 v[20:21], v[12:15], off offset:256
	s_nop 1
	v_mul_f32_e32 v12, 0x3d800000, v22
	v_lshlrev_b64 v[14:15], 11, v[146:147]
	v_lshl_add_u64 v[20:21], s[14:15], 0, v[14:15]
	v_pk_mul_f32 v[18:19], v[18:19], v[12:13] op_sel_hi:[1,0]
	v_pk_mul_f32 v[16:17], v[16:17], v[12:13] op_sel_hi:[1,0]
	v_pk_mul_f32 v[22:23], v[10:11], v[12:13] op_sel_hi:[1,0]
	v_pk_mul_f32 v[10:11], v[8:9], v[12:13] op_sel_hi:[1,0]
	v_lshl_add_u64 v[20:21], v[20:21], 0, v[144:145]
	v_cvt_pk_bf16_f32 v8, v16, v17
	v_cvt_pk_bf16_f32 v9, v18, v19
	v_cvt_pk_bf16_f32 v10, v10, v11
	v_cvt_pk_bf16_f32 v11, v22, v23
	global_store_dwordx4 v[20:21], v[8:11], off
	v_pk_mul_f32 v[4:5], v[4:5], v[12:13] op_sel_hi:[1,0]
	v_pk_mul_f32 v[6:7], v[6:7], v[12:13] op_sel_hi:[1,0]
	v_lshl_add_u64 v[8:9], s[82:83], 0, v[14:15]
	v_lshl_add_u64 v[8:9], v[8:9], 0, v[144:145]
	v_pk_mul_f32 v[10:11], v[2:3], v[12:13] op_sel_hi:[1,0]
	v_pk_mul_f32 v[2:3], v[0:1], v[12:13] op_sel_hi:[1,0]
	v_cvt_pk_bf16_f32 v0, v4, v5
	v_add_co_u32_e32 v4, vcc, 0x8200000, v8
	v_cvt_pk_bf16_f32 v1, v6, v7
	s_nop 0
	v_addc_co_u32_e32 v5, vcc, 0, v9, vcc
	v_cvt_pk_bf16_f32 v2, v2, v3
	v_cvt_pk_bf16_f32 v3, v10, v11
	s_andn2_b64 vcc, exec, s[2:3]
	s_mov_b64 s[2:3], -1
	global_store_dwordx4 v[4:5], v[0:3], off offset:256
	s_cbranch_vccnz .LBB0_965
	s_andn2_b64 vcc, exec, s[8:9]
	s_cbranch_vccnz .LBB0_964
	s_barrier
	s_branch .LBB0_964

; #define PG8_STAGE(bufoff, gbase, voff) do { _Pragma("unroll") for (int _i = 0; _i < 2; ++_i) \
;         __builtin_amdgcn_global_load_lds((const unsigned*)((const char*)(gbase) + (voff)[_i]), (LAS unsigned*)(lds + (bufoff) + ldsw + _i * 8192), 16, 0, 0); } while (0)
; #define PG8_WAIT_V(n) asm volatile("s_waitcnt vmcnt(" #n ")" ::: "memory")
; #define PG8_BAR __builtin_amdgcn_s_barrier()
; template <class Epi, bool ALIGN_EPI>
; DI void gemm_phase(lptr lds, const Gemm g, const StaticOrder& S, const Epi& E) {
;     const int tid = threadIdx.x, wid = __builtin_amdgcn_readfirstlane(tid >> 6), lane = tid & 63, wr = wid >> 2, wc = wid & 3, fr = lane & 15, fq = lane >> 4;
;     const int K = g.K, nt = K / BK, lda = g.lda;
;     unsigned voffA[2], voffB[2];
; #pragma unroll
;     for (int i = 0; i < 2; ++i) { int R, C; stage_rc(tid * 16 + i * 8192, R, C); const int Rb = (R & ~31) + perm32(R & 31);
;         voffA[i] = (unsigned)(R * lda + C) * 2u; voffB[i] = (unsigned)(Rb * K + C) * 2u; }
;     const size_t kstep = (size_t)(BK * 2);
;     const size_t hstepA = (size_t)HALF * lda * 2, hstepB = (size_t)HALF * K * 2, tstepA = 2 * hstepA, tstepB = 2 * hstepB;
;     const unsigned ldsw = (unsigned)wid * 1024u;
;     const int aoff = lds_byte(wr * 64 + fr, fq * 8), boff = lds_byte(wc * 32 + fr, fq * 8);
;     ...
;     Unit cur, nxt; int ui = 0;
;     if (!S.next(0, cur)) return;
;     f32x4 acc[2][2][4][2];
; #pragma unroll
;     for (int a = 0; a < 2; ++a)
; #pragma unroll
;         for (int b = 0; b < 2; ++b)
; #pragma unroll
;             for (int m = 0; m < 4; ++m)
; #pragma unroll
;                 for (int n = 0; n < 2; ++n) acc[a][b][m][n] = (f32x4){0.f, 0.f, 0.f, 0.f};
;     bf16x8 At[4][2], B0[2][2], B1[2][2];
;     const char* cA = (const char*)g.A + (size_t)cur.pm * tstepA; const char* cB = (const char*)g.Bt + (size_t)cur.pn * tstepB;
;     if constexpr (Epi::RESCALE) E.prep(cur, tid);
;     PG8_STAGE(PG8_SB(0, 0), cB, voffB); PG8_STAGE(PG8_SB(0, 1), cB + hstepB, voffB); PG8_STAGE(PG8_SA(0, 0), cA, voffA); PG8_STAGE(PG8_SA(0, 1), cA + hstepA, voffA);
;     if (wr == 1) PG8_BAR;
;     PG8_WAIT_V(2); PG8_BAR;
;     PG8_STAGE(PG8_SB(1, 0), cB + kstep, voffB); PG8_STAGE(PG8_SA(1, 0), cA + kstep, voffA); PG8_STAGE(PG8_SB(1, 1), cB + hstepB + kstep, voffB);
.Lstg9_done:
	s_mov_b32 s98, 0
	s_add_u32 s0, s94, 0x1e80000
	s_addc_u32 s1, s95, 0
	s_add_u32 s6, s94, 0x145000
	s_addc_u32 s7, s95, 0
	s_waitcnt vmcnt(0)
	v_lshrrev_b32_e32 v0, 1, v153
	v_readfirstlane_b32 s3, v153
	v_lshlrev_b32_e32 v162, 4, v153
	v_lshrrev_b32_e32 v168, 3, v153
	v_and_b32_e32 v161, 15, v153
	s_cmpk_gt_i32 s64, 0x15ff
	v_and_b32_e32 v160, 24, v0
	s_cbranch_scc1 .LBB0_1288
	v_lshrrev_b32_e32 v0, 5, v153
	v_and_b32_e32 v0, 4, v0
	s_waitcnt lgkmcnt(0)
	v_bfe_u32 v1, v153, 2, 2
	v_add_u32_e32 v8, 0x2000, v162
	v_or3_b32 v0, v0, v1, v160
	v_lshrrev_b32_e32 v1, 7, v8
	s_movk_i32 s2, 0xe0
	v_and_or_b32 v2, v1, s2, v0
	v_and_b32_e32 v3, 32, v153
	v_bfe_u32 v11, v153, 2, 4
	s_movk_i32 s2, 0xf0
	v_bitop3_b32 v9, v162, v3, 48 bitop3:0x6c
	v_and_b32_e32 v10, 64, v153
	v_and_or_b32 v1, v1, s2, v11
	s_movk_i32 s2, 0x60
	v_or_b32_e32 v3, v9, v10
	v_and_or_b32 v0, v168, s2, v0
	s_movk_i32 s2, 0x70
	s_ashr_i32 s31, s64, 31
	v_lshl_or_b32 v132, v0, 11, v3
	v_and_or_b32 v0, v168, s2, v11
	s_lshr_b32 s2, s31, 29
	s_add_i32 s2, s64, s2
	s_lshr_b32 s13, s3, 6
	s_ashr_i32 s8, s2, 3
	s_and_b32 s2, s2, -8
	s_lshr_b32 s12, s3, 8
	s_lshl_b32 s30, s13, 10
	s_sub_i32 s2, s64, s2
	s_cmp_lt_i32 s2, 0
	s_movk_i32 s34, 0x2c1
	s_cselect_b32 s9, s34, 0x2c0
	s_mul_i32 s2, s2, s9
	s_add_i32 s2, s2, s8
	s_mul_hi_i32 s8, s2, 0x2e8ba2e9
	s_lshr_b32 s9, s8, 31
	s_ashr_i32 s8, s8, 5
	s_add_i32 s8, s8, s9
	s_lshl_b32 s9, s8, 3
	s_mulk_i32 s8, 0xb0
	s_sub_i32 s8, s2, s8
	s_sext_i32_i16 s2, s8
	s_bfe_u32 s2, s2, 0x3001c
	s_add_i32 s10, s8, s2
	s_sext_i32_i16 s2, s10
	s_and_b32 s10, s10, 0xfff8
	s_sub_i32 s8, s8, s10
	s_sext_i32_i16 s8, s8
	s_lshr_b32 s2, s2, 3
	s_add_i32 s10, s9, s8
	s_ashr_i32 s11, s10, 31
	s_bfe_i64 s[14:15], s[2:3], 0x100000
	s_lshl_b64 s[8:9], s[10:11], 19
	s_lshl_b64 s[14:15], s[14:15], 19
	s_add_u32 s26, s0, s14
	s_addc_u32 s27, s1, s15
	s_add_i32 s35, s30, 0
	s_add_i32 m0, s35, 0x10000
	v_lshl_or_b32 v128, v2, 11, v3
	global_load_lds_dwordx4 v132, s[26:27]
	s_add_i32 m0, s35, 0x12000
	s_add_u32 s14, s26, 0x40000
	global_load_lds_dwordx4 v128, s[26:27]
	s_addc_u32 s15, s27, 0
	s_add_i32 m0, s35, 0x14000
	v_lshl_or_b32 v134, v0, 11, v3
	global_load_lds_dwordx4 v132, s[14:15]
	s_add_i32 m0, s35, 0x16000
	s_add_u32 s24, s82, s8
	s_addc_u32 s25, s83, s9
	s_add_i32 s36, s35, 0x2000
	global_load_lds_dwordx4 v128, s[14:15]
	s_mov_b32 m0, s35
	s_add_u32 s8, s24, 0x40000
	v_lshl_or_b32 v130, v1, 11, v3
	global_load_lds_dwordx4 v134, s[24:25]
	s_mov_b32 m0, s36
	s_addc_u32 s9, s25, 0
	s_add_i32 s37, s35, 0x4000
	global_load_lds_dwordx4 v130, s[24:25]
	s_mov_b32 m0, s37
	s_add_i32 s38, s35, 0x6000
	global_load_lds_dwordx4 v134, s[8:9]
	s_mov_b32 m0, s38
	v_mov_b32_e32 v133, 0
	global_load_lds_dwordx4 v130, s[8:9]
	v_mov_b32_e32 v129, v133
	v_mov_b32_e32 v135, v133
	v_mov_b32_e32 v131, v133
	s_cmp_eq_u32 s12, 1
	s_mov_b32 s39, 0
	v_lshl_add_u64 v[6:7], s[26:27], 0, v[132:133]
	v_lshl_add_u64 v[4:5], s[26:27], 0, v[128:129]
	v_lshl_add_u64 v[0:1], s[24:25], 0, v[134:135]
	s_cselect_b64 s[8:9], -1, 0
	s_cmp_lg_u32 s12, 1
	v_lshl_add_u64 v[2:3], s[24:25], 0, v[130:131]
	s_cbranch_scc1 .LBB0_1275
	s_barrier

; #define PG8_STAGE(bufoff, gbase, voff) do { _Pragma("unroll") for (int _i = 0; _i < 2; ++_i) \
;         __builtin_amdgcn_global_load_lds((const unsigned*)((const char*)(gbase) + (voff)[_i]), (LAS unsigned*)(lds + (bufoff) + ldsw + _i * 8192), 16, 0, 0); } while (0)
; #define PG8_LDA(dst, b, h) do { _Pragma("unroll") for (int m = 0; m < 4; ++m) _Pragma("unroll") for (int k = 0; k < 2; ++k) dst[m][k] = *(const LAS bf16x8*)(lds + PG8_SA(b, h) + aoff + m * 2048 + k * 1024); } while (0)
; #define PG8_LDB(dst, b, h) do { _Pragma("unroll") for (int n = 0; n < 2; ++n) _Pragma("unroll") for (int k = 0; k < 2; ++k) dst[n][k] = *(const LAS bf16x8*)(lds + PG8_SB(b, h) + boff + n * 2048 + k * 1024); } while (0)
; #define PG8_WAIT_V(n) asm volatile("s_waitcnt vmcnt(" #n ")" ::: "memory")
; #define PG8_WAIT_L(n) asm volatile("s_waitcnt lgkmcnt(" #n ")" ::: "memory")
; #define PG8_BAR __builtin_amdgcn_s_barrier()
; #define PG8_SCHED __builtin_amdgcn_sched_barrier(0)
; template <class Epi, bool ALIGN_EPI>
; DI void gemm_phase(lptr lds, const Gemm g, const StaticOrder& S, const Epi& E) {
;     ...
;     for (;;) {
;         const bool has_next = S.next(ui + 1, nxt);
;         const char* nA = has_next ? (const char*)g.A + (size_t)nxt.pm * tstepA : cA; const char* nB = has_next ? (const char*)g.Bt + (size_t)nxt.pn * tstepB : cB;
;         for (int t = 0; t < nt; t += 2) {
;             const bool last = (t == nt - 2);
;             if constexpr (Epi::RESCALE) { if (t == 4 || t == 8 || t == 12) E.rescale(acc, cur, t >> 2, wr, fr); }
;             const char* a1 = cA + (size_t)(t + 1) * kstep;
;             const char* a2 = last ? nA : cA + (size_t)(t + 2) * kstep; const char* b2 = last ? nB : cB + (size_t)(t + 2) * kstep;
;             const char* a3 = a2 + kstep; const char* b3 = b2 + kstep;
;             PG8_LDB(B0, 0, 0); PG8_LDB(B1, 0, 1); PG8_SCHED; PG8_LDA(At, 0, 0); PG8_STAGE(PG8_SA(1, 1), a1 + hstepA, voffA);
;             PG8_WAIT_V(8); PG8_WAIT_L(0); PG8_BAR; PG8_MMA(0, 0, At, B0); PG8_MMA(0, 1, At, B1); PG8_BAR; PG8_SCHED;
;     template <int NAI> DI void run(AccRef acc, const Unit& u, int wr, int wc, int fr, int fq) const {
;     ...
;         float rsv[2][4];
; #pragma unroll
;         for (int ai = 0; ai < NAI; ++ai)
; #pragma unroll
;             for (int m = 0; m < 4; ++m) rsv[ai][m] = ssq[EPI_ROW(ai, m)];
.LBB0_1280:
	s_ashr_i32 s19, s18, 31
	s_lshl_b64 s[20:21], s[18:19], 19
	s_add_u32 s20, s82, s20
	s_addc_u32 s21, s83, s21
	s_and_b64 s[22:23], s[2:3], exec
	s_cselect_b32 s19, s21, s25
	s_cselect_b32 s48, s20, s24
	s_ashr_i32 s17, s16, 31
	s_lshl_b64 s[22:23], s[16:17], 19
	s_add_u32 s22, s0, s22
	s_addc_u32 s23, s1, s23
	s_and_b64 s[28:29], s[2:3], exec
	s_cselect_b32 s17, s23, s27
	s_cselect_b32 s49, s22, s26
	s_add_u32 s24, s24, 0x40080
	s_addc_u32 s25, s25, 0
	s_add_u32 s50, s26, 0x100
	v_mov_b32_e32 v0, 0
	s_addc_u32 s51, s27, 0
	s_mov_b32 s52, -2
	v_mov_b32_e32 v1, v0
	v_mov_b32_e32 v2, v0
	v_mov_b32_e32 v3, v0
	v_mov_b32_e32 v4, v0
	v_mov_b32_e32 v5, v0
	v_mov_b32_e32 v6, v0
	v_mov_b32_e32 v7, v0
	v_mov_b32_e32 v16, v0
	v_mov_b32_e32 v17, v0
	v_mov_b32_e32 v18, v0
	v_mov_b32_e32 v19, v0
	v_mov_b32_e32 v20, v0
	v_mov_b32_e32 v21, v0
	v_mov_b32_e32 v22, v0
	v_mov_b32_e32 v23, v0
	v_mov_b32_e32 v32, v0
	v_mov_b32_e32 v33, v0
	v_mov_b32_e32 v34, v0
	v_mov_b32_e32 v35, v0
	v_mov_b32_e32 v36, v0
	v_mov_b32_e32 v37, v0
	v_mov_b32_e32 v38, v0
	v_mov_b32_e32 v39, v0
	v_mov_b32_e32 v48, v0
	v_mov_b32_e32 v49, v0
	v_mov_b32_e32 v50, v0
	v_mov_b32_e32 v51, v0
	v_mov_b32_e32 v52, v0
	v_mov_b32_e32 v53, v0
	v_mov_b32_e32 v54, v0
	v_mov_b32_e32 v55, v0
	v_mov_b32_e32 v8, v0
	v_mov_b32_e32 v9, v0
	v_mov_b32_e32 v10, v0
	v_mov_b32_e32 v11, v0
	v_mov_b32_e32 v12, v0
	v_mov_b32_e32 v13, v0
	v_mov_b32_e32 v14, v0
	v_mov_b32_e32 v15, v0
	v_mov_b32_e32 v24, v0
	v_mov_b32_e32 v25, v0
	v_mov_b32_e32 v26, v0
	v_mov_b32_e32 v27, v0
	v_mov_b32_e32 v28, v0
	v_mov_b32_e32 v29, v0
	v_mov_b32_e32 v30, v0
	v_mov_b32_e32 v31, v0
	v_mov_b32_e32 v40, v0
	v_mov_b32_e32 v41, v0
	v_mov_b32_e32 v42, v0
	v_mov_b32_e32 v43, v0
	v_mov_b32_e32 v44, v0
	v_mov_b32_e32 v45, v0
	v_mov_b32_e32 v46, v0
	v_mov_b32_e32 v47, v0
	v_mov_b32_e32 v56, v0
	v_mov_b32_e32 v57, v0
	v_mov_b32_e32 v58, v0
	v_mov_b32_e32 v59, v0
	v_mov_b32_e32 v60, v0
	v_mov_b32_e32 v61, v0
	v_mov_b32_e32 v62, v0
	v_mov_b32_e32 v63, v0
	v_mov_b32_e32 v64, v0
	v_mov_b32_e32 v65, v0
	v_mov_b32_e32 v66, v0
	v_mov_b32_e32 v67, v0
	v_mov_b32_e32 v68, v0
	v_mov_b32_e32 v69, v0
	v_mov_b32_e32 v70, v0
	v_mov_b32_e32 v71, v0
	v_mov_b32_e32 v80, v0
	v_mov_b32_e32 v81, v0
	v_mov_b32_e32 v82, v0
	v_mov_b32_e32 v83, v0
	v_mov_b32_e32 v84, v0
	v_mov_b32_e32 v85, v0
	v_mov_b32_e32 v86, v0
	v_mov_b32_e32 v87, v0
	v_mov_b32_e32 v96, v0
	v_mov_b32_e32 v97, v0
	v_mov_b32_e32 v98, v0
	v_mov_b32_e32 v99, v0
	v_mov_b32_e32 v100, v0
	v_mov_b32_e32 v101, v0
	v_mov_b32_e32 v102, v0
	v_mov_b32_e32 v103, v0
	v_mov_b32_e32 v104, v0
	v_mov_b32_e32 v105, v0
	v_mov_b32_e32 v106, v0
	v_mov_b32_e32 v107, v0
	v_mov_b32_e32 v108, v0
	v_mov_b32_e32 v109, v0
	v_mov_b32_e32 v110, v0
	v_mov_b32_e32 v111, v0
	v_mov_b32_e32 v72, v0
	v_mov_b32_e32 v73, v0
	v_mov_b32_e32 v74, v0
	v_mov_b32_e32 v75, v0
	v_mov_b32_e32 v76, v0
	v_mov_b32_e32 v77, v0
	v_mov_b32_e32 v78, v0
	v_mov_b32_e32 v79, v0
	v_mov_b32_e32 v88, v0
	v_mov_b32_e32 v89, v0
	v_mov_b32_e32 v90, v0
	v_mov_b32_e32 v91, v0
	v_mov_b32_e32 v92, v0
	v_mov_b32_e32 v93, v0
	v_mov_b32_e32 v94, v0
	v_mov_b32_e32 v95, v0
	v_mov_b32_e32 v112, v0
	v_mov_b32_e32 v113, v0
	v_mov_b32_e32 v114, v0
	v_mov_b32_e32 v115, v0
	v_mov_b32_e32 v116, v0
	v_mov_b32_e32 v117, v0
	v_mov_b32_e32 v118, v0
	v_mov_b32_e32 v119, v0
	v_mov_b32_e32 v120, v0
	v_mov_b32_e32 v121, v0
	v_mov_b32_e32 v122, v0
	v_mov_b32_e32 v123, v0
	v_mov_b32_e32 v124, v0
	v_mov_b32_e32 v125, v0
	v_mov_b32_e32 v126, v0
	v_mov_b32_e32 v127, v0
	v_add_u32_e32 v232, s46, v163
	v_lshlrev_b32_e32 v232, 2, v232
	global_load_dword v233, v232, s[6:7]
	global_load_dword v234, v232, s[6:7] offset:64
	global_load_dword v235, v232, s[6:7] offset:128
	global_load_dword v236, v232, s[6:7] offset:192
	global_load_dword v237, v232, s[6:7] offset:512
	global_load_dword v238, v232, s[6:7] offset:576
	global_load_dword v239, v232, s[6:7] offset:640
	global_load_dword v240, v232, s[6:7] offset:704
	s_cmp_lg_u32 s98, 0
	s_cselect_b32 s99, -2, 0x7fffff00
.LBB0_1281:
	ds_read_b128 v[144:147], v166
	ds_read_b128 v[148:151], v166 offset:1024
	ds_read_b128 v[154:157], v166 offset:2048
	ds_read_b128 v[172:175], v166 offset:3072
	ds_read_b128 v[176:179], v167
	ds_read_b128 v[180:183], v167 offset:1024
	ds_read_b128 v[184:187], v167 offset:2048
	ds_read_b128 v[188:191], v167 offset:3072
	s_add_u32 s26, s24, 0xfffc0080
	s_addc_u32 s27, s25, -1
	s_cmp_eq_u32 s52, 12
	s_cselect_b32 s29, s19, s27
	s_cselect_b32 s28, s48, s26
	s_cselect_b32 s27, s17, s51
	s_cselect_b32 s26, s49, s50
	v_lshl_add_u64 v[158:159], s[24:25], 0, v[136:137]
	s_add_i32 m0, s35, 0xc000
	ds_read_b128 v[192:195], v169
	ds_read_b128 v[196:199], v169 offset:1024
	ds_read_b128 v[200:203], v169 offset:2048
	ds_read_b128 v[204:207], v169 offset:3072
	ds_read_b128 v[208:211], v169 offset:4096
	ds_read_b128 v[212:215], v169 offset:5120
	ds_read_b128 v[216:219], v169 offset:6144
	ds_read_b128 v[220:223], v169 offset:7168
	global_load_lds_dwordx4 v[158:159], off
	v_lshl_add_u64 v[158:159], s[24:25], 0, v[138:139]
	s_add_i32 m0, s35, 0xe000
	s_nop 0
	global_load_lds_dwordx4 v[158:159], off
	s_cmp_eq_u32 s52, s99
	s_cbranch_scc1 .Lrx_gu_0
	s_waitcnt vmcnt(8)
; #define PG8_STAGE(bufoff, gbase, voff) do { _Pragma("unroll") for (int _i = 0; _i < 2; ++_i) \
;         __builtin_amdgcn_global_load_lds((const unsigned*)((const char*)(gbase) + (voff)[_i]), (LAS unsigned*)(lds + (bufoff) + ldsw + _i * 8192), 16, 0, 0); } while (0)
; #define PG8_LDA(dst, b, h) do { _Pragma("unroll") for (int m = 0; m < 4; ++m) _Pragma("unroll") for (int k = 0; k < 2; ++k) dst[m][k] = *(const LAS bf16x8*)(lds + PG8_SA(b, h) + aoff + m * 2048 + k * 1024); } while (0)
; #define PG8_MMA(ai, bj, At, Bt) do { __builtin_amdgcn_s_setprio(1); _Pragma("unroll") for (int m = 0; m < 4; ++m) _Pragma("unroll") for (int n = 0; n < 2; ++n) _Pragma("unroll") for (int k = 0; k < 2; ++k) \
;         acc[ai][bj][m][n] = __builtin_amdgcn_mfma_f32_16x16x32_bf16(Bt[n][k], At[m][k], acc[ai][bj][m][n], 0, 0, 0); __builtin_amdgcn_s_setprio(0); } while (0)
; #define PG8_WAIT_V(n) asm volatile("s_waitcnt vmcnt(" #n ")" ::: "memory")
; #define PG8_WAIT_L(n) asm volatile("s_waitcnt lgkmcnt(" #n ")" ::: "memory")
; #define PG8_BAR __builtin_amdgcn_s_barrier()
; #define PG8_SCHED __builtin_amdgcn_sched_barrier(0)
; template <class Epi, bool ALIGN_EPI>
; DI void gemm_phase(lptr lds, const Gemm g, const StaticOrder& S, const Epi& E) {
;     ...
;             PG8_WAIT_V(8); PG8_WAIT_L(0); PG8_BAR; PG8_MMA(0, 0, At, B0); PG8_MMA(0, 1, At, B1); PG8_BAR; PG8_SCHED;
;             PG8_LDA(At, 0, 1); PG8_STAGE(PG8_SB(0, 0), b2, voffB); PG8_STAGE(PG8_SB(0, 1), b2 + hstepB, voffB); PG8_STAGE(PG8_SA(0, 0), a2, voffA);
;             PG8_WAIT_V(8); PG8_WAIT_L(0); PG8_BAR; PG8_MMA(1, 0, At, B0); PG8_MMA(1, 1, At, B1); PG8_BAR; PG8_SCHED;
.Lrx_gu_0b:
	s_waitcnt lgkmcnt(0)
	s_barrier
	s_setprio 1
	s_waitcnt lgkmcnt(0)
	v_mfma_f32_16x16x32_bf16 v[124:127], v[144:147], v[192:195], v[124:127]
	v_mfma_f32_16x16x32_bf16 v[120:123], v[154:157], v[192:195], v[120:123]
	v_mfma_f32_16x16x32_bf16 v[116:119], v[144:147], v[200:203], v[116:119]
	v_mfma_f32_16x16x32_bf16 v[112:115], v[154:157], v[200:203], v[112:115]
	v_mfma_f32_16x16x32_bf16 v[92:95], v[144:147], v[208:211], v[92:95]
	v_mfma_f32_16x16x32_bf16 v[88:91], v[154:157], v[208:211], v[88:91]
	v_mfma_f32_16x16x32_bf16 v[76:79], v[144:147], v[216:219], v[76:79]
	v_mfma_f32_16x16x32_bf16 v[72:75], v[154:157], v[216:219], v[72:75]
	v_mfma_f32_16x16x32_bf16 v[124:127], v[148:151], v[196:199], v[124:127]
	v_mfma_f32_16x16x32_bf16 v[120:123], v[172:175], v[196:199], v[120:123]
	v_mfma_f32_16x16x32_bf16 v[116:119], v[148:151], v[204:207], v[116:119]
	v_mfma_f32_16x16x32_bf16 v[112:115], v[172:175], v[204:207], v[112:115]
	v_mfma_f32_16x16x32_bf16 v[92:95], v[148:151], v[212:215], v[92:95]
	v_mfma_f32_16x16x32_bf16 v[88:91], v[172:175], v[212:215], v[88:91]
	v_mfma_f32_16x16x32_bf16 v[76:79], v[148:151], v[220:223], v[76:79]
	v_mfma_f32_16x16x32_bf16 v[72:75], v[172:175], v[220:223], v[72:75]
	s_setprio 0
	s_setprio 1
	v_mfma_f32_16x16x32_bf16 v[108:111], v[176:179], v[192:195], v[108:111]
	v_mfma_f32_16x16x32_bf16 v[104:107], v[184:187], v[192:195], v[104:107]
	v_mfma_f32_16x16x32_bf16 v[100:103], v[176:179], v[200:203], v[100:103]
	v_mfma_f32_16x16x32_bf16 v[96:99], v[184:187], v[200:203], v[96:99]
	v_mfma_f32_16x16x32_bf16 v[84:87], v[176:179], v[208:211], v[84:87]
	v_mfma_f32_16x16x32_bf16 v[80:83], v[184:187], v[208:211], v[80:83]
	v_mfma_f32_16x16x32_bf16 v[68:71], v[176:179], v[216:219], v[68:71]
	v_mfma_f32_16x16x32_bf16 v[64:67], v[184:187], v[216:219], v[64:67]
	v_mfma_f32_16x16x32_bf16 v[108:111], v[180:183], v[196:199], v[108:111]
	v_mfma_f32_16x16x32_bf16 v[104:107], v[188:191], v[196:199], v[104:107]
	v_mfma_f32_16x16x32_bf16 v[100:103], v[180:183], v[204:207], v[100:103]
	v_mfma_f32_16x16x32_bf16 v[96:99], v[188:191], v[204:207], v[96:99]
	v_mfma_f32_16x16x32_bf16 v[84:87], v[180:183], v[212:215], v[84:87]
	v_mfma_f32_16x16x32_bf16 v[80:83], v[188:191], v[212:215], v[80:83]
	v_mfma_f32_16x16x32_bf16 v[68:71], v[180:183], v[220:223], v[68:71]
	v_mfma_f32_16x16x32_bf16 v[64:67], v[188:191], v[220:223], v[64:67]
	s_setprio 0
	s_barrier
	s_add_i32 s53, s42, s30
	v_lshl_add_u64 v[158:159], s[26:27], 0, v[132:133]
	s_mov_b32 m0, s53
	ds_read_b128 v[192:195], v169 offset:16384
	ds_read_b128 v[196:199], v169 offset:17408
	ds_read_b128 v[200:203], v169 offset:18432
	ds_read_b128 v[204:207], v169 offset:19456
	ds_read_b128 v[208:211], v169 offset:20480
	ds_read_b128 v[212:215], v169 offset:21504
	ds_read_b128 v[216:219], v169 offset:22528
	ds_read_b128 v[220:223], v169 offset:23552
	global_load_lds_dwordx4 v[158:159], off
	s_add_i32 m0, s53, 0x2000
	s_add_u32 s54, s26, 0x40000
	v_lshl_add_u64 v[224:225], s[26:27], 0, v[128:129]
	s_addc_u32 s55, s27, 0
	s_add_i32 s53, s43, s30
	global_load_lds_dwordx4 v[224:225], off
	v_lshl_add_u64 v[226:227], s[54:55], 0, v[132:133]
	s_mov_b32 m0, s53
	v_lshl_add_u64 v[228:229], s[28:29], 0, v[130:131]
	global_load_lds_dwordx4 v[226:227], off
	v_lshl_add_u64 v[226:227], s[54:55], 0, v[128:129]
	s_add_i32 m0, s53, 0x2000
	s_nop 0
	global_load_lds_dwordx4 v[226:227], off
	v_lshl_add_u64 v[226:227], s[28:29], 0, v[134:135]
	s_mov_b32 m0, s35
	s_nop 0
	global_load_lds_dwordx4 v[226:227], off
	s_mov_b32 m0, s36
	s_nop 0
	global_load_lds_dwordx4 v[228:229], off
	s_cmp_eq_u32 s52, s99
	s_cbranch_scc1 .Lrx_gu_1
	s_waitcnt vmcnt(8)
.Lrx_gu_1b:
	s_waitcnt lgkmcnt(0)
	s_barrier
	s_setprio 1
	s_waitcnt lgkmcnt(0)
	v_mfma_f32_16x16x32_bf16 v[60:63], v[144:147], v[192:195], v[60:63]
	v_mfma_f32_16x16x32_bf16 v[56:59], v[154:157], v[192:195], v[56:59]
	v_mfma_f32_16x16x32_bf16 v[44:47], v[144:147], v[200:203], v[44:47]
	v_mfma_f32_16x16x32_bf16 v[40:43], v[154:157], v[200:203], v[40:43]
	v_mfma_f32_16x16x32_bf16 v[28:31], v[144:147], v[208:211], v[28:31]
	v_mfma_f32_16x16x32_bf16 v[24:27], v[154:157], v[208:211], v[24:27]
	v_mfma_f32_16x16x32_bf16 v[12:15], v[144:147], v[216:219], v[12:15]
	v_mfma_f32_16x16x32_bf16 v[8:11], v[154:157], v[216:219], v[8:11]
	v_mfma_f32_16x16x32_bf16 v[60:63], v[148:151], v[196:199], v[60:63]
	v_mfma_f32_16x16x32_bf16 v[56:59], v[172:175], v[196:199], v[56:59]
	v_mfma_f32_16x16x32_bf16 v[44:47], v[148:151], v[204:207], v[44:47]
	v_mfma_f32_16x16x32_bf16 v[40:43], v[172:175], v[204:207], v[40:43]
	v_mfma_f32_16x16x32_bf16 v[28:31], v[148:151], v[212:215], v[28:31]
	v_mfma_f32_16x16x32_bf16 v[24:27], v[172:175], v[212:215], v[24:27]
	v_mfma_f32_16x16x32_bf16 v[12:15], v[148:151], v[220:223], v[12:15]
	v_mfma_f32_16x16x32_bf16 v[8:11], v[172:175], v[220:223], v[8:11]
	s_setprio 0
	s_setprio 1
	v_mfma_f32_16x16x32_bf16 v[52:55], v[176:179], v[192:195], v[52:55]
	v_mfma_f32_16x16x32_bf16 v[48:51], v[184:187], v[192:195], v[48:51]
	v_mfma_f32_16x16x32_bf16 v[36:39], v[176:179], v[200:203], v[36:39]
	v_mfma_f32_16x16x32_bf16 v[32:35], v[184:187], v[200:203], v[32:35]
	v_mfma_f32_16x16x32_bf16 v[20:23], v[176:179], v[208:211], v[20:23]
	v_mfma_f32_16x16x32_bf16 v[16:19], v[184:187], v[208:211], v[16:19]
	v_mfma_f32_16x16x32_bf16 v[4:7], v[176:179], v[216:219], v[4:7]
	v_mfma_f32_16x16x32_bf16 v[0:3], v[184:187], v[216:219], v[0:3]
	v_mfma_f32_16x16x32_bf16 v[52:55], v[180:183], v[196:199], v[52:55]
	v_mfma_f32_16x16x32_bf16 v[48:51], v[188:191], v[196:199], v[48:51]
	v_mfma_f32_16x16x32_bf16 v[36:39], v[180:183], v[204:207], v[36:39]
	v_mfma_f32_16x16x32_bf16 v[32:35], v[188:191], v[204:207], v[32:35]
	v_mfma_f32_16x16x32_bf16 v[20:23], v[180:183], v[212:215], v[20:23]
	v_mfma_f32_16x16x32_bf16 v[16:19], v[188:191], v[212:215], v[16:19]
	v_mfma_f32_16x16x32_bf16 v[4:7], v[180:183], v[220:223], v[4:7]
	v_mfma_f32_16x16x32_bf16 v[0:3], v[188:191], v[220:223], v[0:3]
	s_setprio 0
	s_barrier
; #define PG8_STAGE(bufoff, gbase, voff) do { _Pragma("unroll") for (int _i = 0; _i < 2; ++_i) \
;         __builtin_amdgcn_global_load_lds((const unsigned*)((const char*)(gbase) + (voff)[_i]), (LAS unsigned*)(lds + (bufoff) + ldsw + _i * 8192), 16, 0, 0); } while (0)
; #define PG8_LDA(dst, b, h) do { _Pragma("unroll") for (int m = 0; m < 4; ++m) _Pragma("unroll") for (int k = 0; k < 2; ++k) dst[m][k] = *(const LAS bf16x8*)(lds + PG8_SA(b, h) + aoff + m * 2048 + k * 1024); } while (0)
; #define PG8_LDB(dst, b, h) do { _Pragma("unroll") for (int n = 0; n < 2; ++n) _Pragma("unroll") for (int k = 0; k < 2; ++k) dst[n][k] = *(const LAS bf16x8*)(lds + PG8_SB(b, h) + boff + n * 2048 + k * 1024); } while (0)
; #define PG8_MMA(ai, bj, At, Bt) do { __builtin_amdgcn_s_setprio(1); _Pragma("unroll") for (int m = 0; m < 4; ++m) _Pragma("unroll") for (int n = 0; n < 2; ++n) _Pragma("unroll") for (int k = 0; k < 2; ++k) \
;         acc[ai][bj][m][n] = __builtin_amdgcn_mfma_f32_16x16x32_bf16(Bt[n][k], At[m][k], acc[ai][bj][m][n], 0, 0, 0); __builtin_amdgcn_s_setprio(0); } while (0)
; #define PG8_WAIT_V(n) asm volatile("s_waitcnt vmcnt(" #n ")" ::: "memory")
; #define PG8_WAIT_L(n) asm volatile("s_waitcnt lgkmcnt(" #n ")" ::: "memory")
; #define PG8_BAR __builtin_amdgcn_s_barrier()
; #define PG8_SCHED __builtin_amdgcn_sched_barrier(0)
; template <class Epi, bool ALIGN_EPI>
; DI void gemm_phase(lptr lds, const Gemm g, const StaticOrder& S, const Epi& E) {
;     ...
;             PG8_LDB(B0, 1, 0); PG8_LDB(B1, 1, 1); PG8_SCHED; PG8_LDA(At, 1, 0); PG8_STAGE(PG8_SA(0, 1), a2 + hstepA, voffA);
;             PG8_WAIT_V(8); PG8_WAIT_L(0); PG8_BAR; PG8_MMA(0, 0, At, B0); PG8_MMA(0, 1, At, B1); PG8_BAR; PG8_SCHED;
;             PG8_LDA(At, 1, 1); PG8_STAGE(PG8_SB(1, 0), b3, voffB); PG8_STAGE(PG8_SB(1, 1), b3 + hstepB, voffB); PG8_STAGE(PG8_SA(1, 0), a3, voffA);
;             PG8_WAIT_V(8); PG8_WAIT_L(0); PG8_BAR; PG8_MMA(1, 0, At, B0); PG8_MMA(1, 1, At, B1); PG8_BAR; PG8_SCHED;
	s_add_i32 s53, 0, 0x18000
	v_add_u32_e32 v171, s53, v164
	s_add_i32 s54, 0, 0x1c000
	ds_read_b128 v[144:147], v171
	ds_read_b128 v[148:151], v171 offset:1024
	ds_read_b128 v[154:157], v171 offset:2048
	ds_read_b128 v[172:175], v171 offset:3072
	v_add_u32_e32 v171, s54, v164
	ds_read_b128 v[176:179], v171
	ds_read_b128 v[180:183], v171 offset:1024
	ds_read_b128 v[184:187], v171 offset:2048
	ds_read_b128 v[188:191], v171 offset:3072
	s_add_u32 s28, s28, 0x40000
	s_addc_u32 s29, s29, 0
	s_mov_b32 m0, s37
	v_lshl_add_u64 v[230:231], s[28:29], 0, v[134:135]
	ds_read_b128 v[192:195], v169 offset:32768
	ds_read_b128 v[196:199], v169 offset:33792
	ds_read_b128 v[200:203], v169 offset:34816
	ds_read_b128 v[204:207], v169 offset:35840
	ds_read_b128 v[208:211], v169 offset:36864
	ds_read_b128 v[212:215], v169 offset:37888
	ds_read_b128 v[216:219], v169 offset:38912
	ds_read_b128 v[220:223], v169 offset:39936
	global_load_lds_dwordx4 v[230:231], off
	v_lshl_add_u64 v[230:231], s[28:29], 0, v[130:131]
	s_mov_b32 m0, s38
	s_nop 0
	global_load_lds_dwordx4 v[230:231], off
	s_waitcnt vmcnt(8)
	s_waitcnt lgkmcnt(0)
	s_barrier
	s_setprio 1
	s_waitcnt lgkmcnt(0)
	v_mfma_f32_16x16x32_bf16 v[124:127], v[144:147], v[192:195], v[124:127]
	v_mfma_f32_16x16x32_bf16 v[120:123], v[154:157], v[192:195], v[120:123]
	v_mfma_f32_16x16x32_bf16 v[116:119], v[144:147], v[200:203], v[116:119]
	v_mfma_f32_16x16x32_bf16 v[112:115], v[154:157], v[200:203], v[112:115]
	v_mfma_f32_16x16x32_bf16 v[92:95], v[144:147], v[208:211], v[92:95]
	v_mfma_f32_16x16x32_bf16 v[88:91], v[154:157], v[208:211], v[88:91]
	v_mfma_f32_16x16x32_bf16 v[76:79], v[144:147], v[216:219], v[76:79]
	v_mfma_f32_16x16x32_bf16 v[72:75], v[154:157], v[216:219], v[72:75]
	v_mfma_f32_16x16x32_bf16 v[124:127], v[148:151], v[196:199], v[124:127]
	v_mfma_f32_16x16x32_bf16 v[120:123], v[172:175], v[196:199], v[120:123]
	v_mfma_f32_16x16x32_bf16 v[116:119], v[148:151], v[204:207], v[116:119]
	v_mfma_f32_16x16x32_bf16 v[112:115], v[172:175], v[204:207], v[112:115]
	v_mfma_f32_16x16x32_bf16 v[92:95], v[148:151], v[212:215], v[92:95]
	v_mfma_f32_16x16x32_bf16 v[88:91], v[172:175], v[212:215], v[88:91]
	v_mfma_f32_16x16x32_bf16 v[76:79], v[148:151], v[220:223], v[76:79]
	v_mfma_f32_16x16x32_bf16 v[72:75], v[172:175], v[220:223], v[72:75]
	s_setprio 0
	s_setprio 1
	v_mfma_f32_16x16x32_bf16 v[108:111], v[176:179], v[192:195], v[108:111]
	v_mfma_f32_16x16x32_bf16 v[104:107], v[184:187], v[192:195], v[104:107]
	v_mfma_f32_16x16x32_bf16 v[100:103], v[176:179], v[200:203], v[100:103]
	v_mfma_f32_16x16x32_bf16 v[96:99], v[184:187], v[200:203], v[96:99]
	v_mfma_f32_16x16x32_bf16 v[84:87], v[176:179], v[208:211], v[84:87]
	v_mfma_f32_16x16x32_bf16 v[80:83], v[184:187], v[208:211], v[80:83]
	v_mfma_f32_16x16x32_bf16 v[68:71], v[176:179], v[216:219], v[68:71]
	v_mfma_f32_16x16x32_bf16 v[64:67], v[184:187], v[216:219], v[64:67]
	v_mfma_f32_16x16x32_bf16 v[108:111], v[180:183], v[196:199], v[108:111]
	v_mfma_f32_16x16x32_bf16 v[104:107], v[188:191], v[196:199], v[104:107]
	v_mfma_f32_16x16x32_bf16 v[100:103], v[180:183], v[204:207], v[100:103]
	v_mfma_f32_16x16x32_bf16 v[96:99], v[188:191], v[204:207], v[96:99]
	v_mfma_f32_16x16x32_bf16 v[84:87], v[180:183], v[212:215], v[84:87]
	v_mfma_f32_16x16x32_bf16 v[80:83], v[188:191], v[212:215], v[80:83]
	v_mfma_f32_16x16x32_bf16 v[68:71], v[180:183], v[220:223], v[68:71]
	v_mfma_f32_16x16x32_bf16 v[64:67], v[188:191], v[220:223], v[64:67]
	s_setprio 0
	s_barrier
	s_add_i32 s28, s53, s30
	v_lshl_add_u64 v[158:159], v[158:159], 0, s[10:11]
	s_mov_b32 m0, s28
	ds_read_b128 v[192:195], v169 offset:49152
	ds_read_b128 v[196:199], v169 offset:50176
	ds_read_b128 v[200:203], v169 offset:51200
	ds_read_b128 v[204:207], v169 offset:52224
	ds_read_b128 v[208:211], v169 offset:53248
	ds_read_b128 v[212:215], v169 offset:54272
	ds_read_b128 v[216:219], v169 offset:55296
	ds_read_b128 v[220:223], v169 offset:56320
	global_load_lds_dwordx4 v[158:159], off
	s_add_i32 m0, s28, 0x2000
	s_add_u32 s26, s26, 0x40080
	v_lshl_add_u64 v[158:159], v[224:225], 0, s[10:11]
	s_addc_u32 s27, s27, 0
	s_add_i32 s28, s54, s30
	global_load_lds_dwordx4 v[158:159], off
	v_lshl_add_u64 v[158:159], s[26:27], 0, v[132:133]
	s_mov_b32 m0, s28
	s_nop 0
	global_load_lds_dwordx4 v[158:159], off
	v_lshl_add_u64 v[158:159], s[26:27], 0, v[128:129]
	s_add_i32 m0, s28, 0x2000
	s_nop 0
	global_load_lds_dwordx4 v[158:159], off
	v_lshl_add_u64 v[158:159], v[226:227], 0, s[10:11]
	s_mov_b32 m0, s33
	s_nop 0
	global_load_lds_dwordx4 v[158:159], off
	v_lshl_add_u64 v[158:159], v[228:229], 0, s[10:11]
	s_mov_b32 m0, s40
	s_nop 0
	global_load_lds_dwordx4 v[158:159], off
	s_waitcnt vmcnt(8)
	s_waitcnt lgkmcnt(0)
	s_barrier
; DI void st8(bf16_t* p, f32x4 a, f32x4 b) { u32x4 w; w.x = cvt_pk_bf16(a.x, a.y); w.y = cvt_pk_bf16(a.z, a.w); w.z = cvt_pk_bf16(b.x, b.y); w.w = cvt_pk_bf16(b.z, b.w); *(u32x4*)p = w; }
; DI f32x4 sigm4(f32x4 v) { f32x4 r; r.x = sigm(v.x); r.y = sigm(v.y); r.z = sigm(v.z); r.w = sigm(v.w); return r; }
; #define PG8_MMA(ai, bj, At, Bt) do { __builtin_amdgcn_s_setprio(1); _Pragma("unroll") for (int m = 0; m < 4; ++m) _Pragma("unroll") for (int n = 0; n < 2; ++n) _Pragma("unroll") for (int k = 0; k < 2; ++k) \
;         acc[ai][bj][m][n] = __builtin_amdgcn_mfma_f32_16x16x32_bf16(Bt[n][k], At[m][k], acc[ai][bj][m][n], 0, 0, 0); __builtin_amdgcn_s_setprio(0); } while (0)
; #define PG8_WAIT_V(n) asm volatile("s_waitcnt vmcnt(" #n ")" ::: "memory")
; #define PG8_WAIT_L(n) asm volatile("s_waitcnt lgkmcnt(" #n ")" ::: "memory")
; #define PG8_BAR __builtin_amdgcn_s_barrier()
; #define PG8_SCHED __builtin_amdgcn_sched_barrier(0)
; template <class Epi, bool ALIGN_EPI>
; DI void gemm_phase(lptr lds, const Gemm g, const StaticOrder& S, const Epi& E) {
;     ...
;             PG8_WAIT_V(8); PG8_WAIT_L(0); PG8_BAR; PG8_MMA(1, 0, At, B0); PG8_MMA(1, 1, At, B1); PG8_BAR; PG8_SCHED;
;         }
;         if constexpr (ALIGN_EPI) { if (wr == 0) PG8_BAR; }
;         E.template run<2>(acc, cur, wr, wc, fr, fq);
;     template <int NAI> DI void run(AccRef acc, const Unit& u, int wr, int wc, int fr, int fq) const {
;     ...
;         for (int ai = 0; ai < NAI; ++ai)
; #pragma unroll
;             for (int m = 0; m < 4; ++m) {
;                 const int row = EPI_ROW(ai, m); const float rs = __builtin_amdgcn_rsqf(rsv[ai][m] * (1.f / DM) + EPS);
;                 const f32x4 g0 = acc[ai][0][m][0] * rs, g1 = acc[ai][0][m][1] * rs, u0 = acc[ai][1][m][0] * rs, u1 = acc[ai][1][m][1] * rs;
;                 st8(P + G_RV + (size_t)row * DFF + cl, g0 * sigm4(g0) * u0, g1 * sigm4(g1) * u1);
;             }
	s_setprio 1
	s_waitcnt lgkmcnt(0)
	v_mfma_f32_16x16x32_bf16 v[60:63], v[144:147], v[192:195], v[60:63]
	v_mfma_f32_16x16x32_bf16 v[56:59], v[154:157], v[192:195], v[56:59]
	v_mfma_f32_16x16x32_bf16 v[44:47], v[144:147], v[200:203], v[44:47]
	v_mfma_f32_16x16x32_bf16 v[40:43], v[154:157], v[200:203], v[40:43]
	v_mfma_f32_16x16x32_bf16 v[28:31], v[144:147], v[208:211], v[28:31]
	v_mfma_f32_16x16x32_bf16 v[24:27], v[154:157], v[208:211], v[24:27]
	v_mfma_f32_16x16x32_bf16 v[12:15], v[144:147], v[216:219], v[12:15]
	v_mfma_f32_16x16x32_bf16 v[8:11], v[154:157], v[216:219], v[8:11]
	v_mfma_f32_16x16x32_bf16 v[60:63], v[148:151], v[196:199], v[60:63]
	v_mfma_f32_16x16x32_bf16 v[56:59], v[172:175], v[196:199], v[56:59]
	v_mfma_f32_16x16x32_bf16 v[44:47], v[148:151], v[204:207], v[44:47]
	v_mfma_f32_16x16x32_bf16 v[40:43], v[172:175], v[204:207], v[40:43]
	v_mfma_f32_16x16x32_bf16 v[28:31], v[148:151], v[212:215], v[28:31]
	v_mfma_f32_16x16x32_bf16 v[24:27], v[172:175], v[212:215], v[24:27]
	v_mfma_f32_16x16x32_bf16 v[12:15], v[148:151], v[220:223], v[12:15]
	v_mfma_f32_16x16x32_bf16 v[8:11], v[172:175], v[220:223], v[8:11]
	s_setprio 0
	s_setprio 1
	v_mfma_f32_16x16x32_bf16 v[52:55], v[176:179], v[192:195], v[52:55]
	v_mfma_f32_16x16x32_bf16 v[48:51], v[184:187], v[192:195], v[48:51]
	v_mfma_f32_16x16x32_bf16 v[36:39], v[176:179], v[200:203], v[36:39]
	v_mfma_f32_16x16x32_bf16 v[32:35], v[184:187], v[200:203], v[32:35]
	v_mfma_f32_16x16x32_bf16 v[20:23], v[176:179], v[208:211], v[20:23]
	v_mfma_f32_16x16x32_bf16 v[16:19], v[184:187], v[208:211], v[16:19]
	v_mfma_f32_16x16x32_bf16 v[4:7], v[176:179], v[216:219], v[4:7]
	v_mfma_f32_16x16x32_bf16 v[0:3], v[184:187], v[216:219], v[0:3]
	v_mfma_f32_16x16x32_bf16 v[52:55], v[180:183], v[196:199], v[52:55]
	v_mfma_f32_16x16x32_bf16 v[48:51], v[188:191], v[196:199], v[48:51]
	v_mfma_f32_16x16x32_bf16 v[36:39], v[180:183], v[204:207], v[36:39]
	v_mfma_f32_16x16x32_bf16 v[32:35], v[188:191], v[204:207], v[32:35]
	v_mfma_f32_16x16x32_bf16 v[20:23], v[180:183], v[212:215], v[20:23]
	v_mfma_f32_16x16x32_bf16 v[16:19], v[188:191], v[212:215], v[16:19]
	v_mfma_f32_16x16x32_bf16 v[4:7], v[180:183], v[220:223], v[4:7]
	v_mfma_f32_16x16x32_bf16 v[0:3], v[188:191], v[220:223], v[0:3]
	s_setprio 0
	s_barrier
	s_add_i32 s52, s52, 2
	s_add_u32 s24, s24, 0x100
	s_addc_u32 s25, s25, 0
	s_add_u32 s50, s50, 0x100
	s_addc_u32 s51, s51, 0
	s_cmp_gt_u32 s52, 13
	s_cbranch_scc0 .LBB0_1281
	s_and_b64 vcc, exec, s[12:13]
	s_cbranch_vccz .LBB0_1284
	s_barrier
.LBB0_1284:
	s_mov_b32 s98, 1
	v_add_u32_e32 v148, s46, v163
	v_ashrrev_i32_e32 v149, 31, v148
	v_lshl_add_u64 v[144:145], v[148:149], 2, s[6:7]
	v_add_u32_e32 v172, 16, v148
	v_mov_b32_e32 v171, v233
	v_ashrrev_i32_e32 v173, 31, v172
	v_lshl_add_u64 v[144:145], v[172:173], 2, s[6:7]
	v_mov_b32_e32 v173, v234
	v_lshl_or_b32 v174, s47, 7, v165
	v_add_u32_e32 v176, 32, v148
	v_mov_b64_e32 v[144:145], s[14:15]
	v_add_u32_e32 v158, 48, v148
	v_add_u32_e32 v156, 0x80, v148
	v_add_u32_e32 v154, 0x90, v148
	v_add_u32_e32 v150, 0xa0, v148
	v_add_u32_e32 v146, 0xb0, v148
	v_ashrrev_i32_e32 v175, 31, v174
	v_ashrrev_i32_e32 v177, 31, v176
	v_mad_i64_i32 v[178:179], s[24:25], v148, s44, v[144:145]
	v_ashrrev_i32_e32 v159, 31, v158
	v_ashrrev_i32_e32 v157, 31, v156
	v_ashrrev_i32_e32 v155, 31, v154
	v_ashrrev_i32_e32 v151, 31, v150
	v_ashrrev_i32_e32 v147, 31, v146
	v_lshlrev_b64 v[148:149], 1, v[174:175]
	v_lshl_add_u64 v[174:175], v[176:177], 2, s[6:7]
	v_lshl_add_u64 v[180:181], v[158:159], 2, s[6:7]
	v_lshl_add_u64 v[182:183], v[156:157], 2, s[6:7]
	v_lshl_add_u64 v[184:185], v[154:155], 2, s[6:7]
	v_lshl_add_u64 v[186:187], v[150:151], 2, s[6:7]
	v_lshl_add_u64 v[188:189], v[146:147], 2, s[6:7]
	v_mov_b32_e32 v155, v235
	v_mov_b32_e32 v157, v236
	v_mov_b32_e32 v159, v237
	v_mov_b32_e32 v177, v238
	v_mov_b32_e32 v151, v239
	v_mov_b32_e32 v147, v240
	v_lshl_add_u64 v[178:179], v[178:179], 0, v[148:149]
	s_andn2_b64 vcc, exec, s[2:3]
	s_mov_b64 s[2:3], -1
	v_fmamk_f32 v171, v171, 0x3a800000, v170
	v_rsq_f32_e32 v174, v171
	v_fmamk_f32 v171, v173, 0x3a800000, v170
	v_rsq_f32_e32 v180, v171
	v_pk_mul_f32 v[126:127], v[126:127], v[174:175] op_sel_hi:[1,0]
	v_pk_mul_f32 v[124:125], v[124:125], v[174:175] op_sel_hi:[1,0]
	v_pk_mul_f32 v[122:123], v[122:123], v[174:175] op_sel_hi:[1,0]
	v_pk_mul_f32 v[120:121], v[120:121], v[174:175] op_sel_hi:[1,0]
	v_mul_f32_e32 v171, 0xbfb8aa3b, v124
	v_mul_f32_e32 v173, 0xbfb8aa3b, v125
	v_mul_f32_e32 v181, 0xbfb8aa3b, v126
	v_mul_f32_e32 v184, 0xbfb8aa3b, v127
	v_mul_f32_e32 v185, 0xbfb8aa3b, v120
	v_mul_f32_e32 v186, 0xbfb8aa3b, v121
	v_mul_f32_e32 v187, 0xbfb8aa3b, v122
	v_mul_f32_e32 v188, 0xbfb8aa3b, v123
	v_pk_mul_f32 v[108:109], v[108:109], v[174:175] op_sel_hi:[1,0]
	v_pk_mul_f32 v[110:111], v[110:111], v[174:175] op_sel_hi:[1,0]
	v_pk_mul_f32 v[104:105], v[104:105], v[174:175] op_sel_hi:[1,0]
	v_pk_mul_f32 v[106:107], v[106:107], v[174:175] op_sel_hi:[1,0]
	v_pk_mul_f32 v[118:119], v[118:119], v[180:181] op_sel_hi:[1,0]
	v_pk_mul_f32 v[116:117], v[116:117], v[180:181] op_sel_hi:[1,0]
	v_pk_mul_f32 v[114:115], v[114:115], v[180:181] op_sel_hi:[1,0]
	v_pk_mul_f32 v[112:113], v[112:113], v[180:181] op_sel_hi:[1,0]
	v_pk_mul_f32 v[174:175], v[100:101], v[180:181] op_sel_hi:[1,0]
	v_pk_mul_f32 v[182:183], v[102:103], v[180:181] op_sel_hi:[1,0]
	v_pk_mul_f32 v[96:97], v[96:97], v[180:181] op_sel_hi:[1,0]
	v_exp_f32_e32 v100, v171
	v_exp_f32_e32 v101, v173
	v_exp_f32_e32 v102, v181
	v_exp_f32_e32 v103, v184
	v_exp_f32_e32 v171, v185
	v_exp_f32_e32 v173, v186
	v_exp_f32_e32 v181, v187
	v_exp_f32_e32 v184, v188
	v_add_f32_e32 v100, 1.0, v100
; DI void st8(bf16_t* p, f32x4 a, f32x4 b) { u32x4 w; w.x = cvt_pk_bf16(a.x, a.y); w.y = cvt_pk_bf16(a.z, a.w); w.z = cvt_pk_bf16(b.x, b.y); w.w = cvt_pk_bf16(b.z, b.w); *(u32x4*)p = w; }
; DI f32x4 sigm4(f32x4 v) { f32x4 r; r.x = sigm(v.x); r.y = sigm(v.y); r.z = sigm(v.z); r.w = sigm(v.w); return r; }
;     template <int NAI> DI void run(AccRef acc, const Unit& u, int wr, int wc, int fr, int fq) const {
;     ...
;         for (int ai = 0; ai < NAI; ++ai)
; #pragma unroll
;             for (int m = 0; m < 4; ++m) {
;                 const int row = EPI_ROW(ai, m); const float rs = __builtin_amdgcn_rsqf(rsv[ai][m] * (1.f / DM) + EPS);
;                 const f32x4 g0 = acc[ai][0][m][0] * rs, g1 = acc[ai][0][m][1] * rs, u0 = acc[ai][1][m][0] * rs, u1 = acc[ai][1][m][1] * rs;
;                 st8(P + G_RV + (size_t)row * DFF + cl, g0 * sigm4(g0) * u0, g1 * sigm4(g1) * u1);
;             }
	v_add_f32_e32 v101, 1.0, v101
	v_add_f32_e32 v102, 1.0, v102
	v_add_f32_e32 v103, 1.0, v103
	v_add_f32_e32 v171, 1.0, v171
	v_add_f32_e32 v173, 1.0, v173
	v_add_f32_e32 v181, 1.0, v181
	v_add_f32_e32 v187, 1.0, v184
	v_rcp_f32_e32 v100, v100
	v_rcp_f32_e32 v101, v101
	v_rcp_f32_e32 v102, v102
	v_rcp_f32_e32 v103, v103
	v_rcp_f32_e32 v184, v171
	v_rcp_f32_e32 v185, v173
	v_rcp_f32_e32 v186, v181
	v_rcp_f32_e32 v187, v187
	v_pk_mul_f32 v[100:101], v[124:125], v[100:101]
	v_pk_mul_f32 v[102:103], v[126:127], v[102:103]
	v_pk_mul_f32 v[120:121], v[120:121], v[184:185]
	v_pk_mul_f32 v[122:123], v[122:123], v[186:187]
	v_pk_mul_f32 v[102:103], v[110:111], v[102:103]
	v_pk_mul_f32 v[100:101], v[108:109], v[100:101]
	v_pk_mul_f32 v[106:107], v[106:107], v[122:123]
	v_pk_mul_f32 v[104:105], v[104:105], v[120:121]
	v_cvt_pk_bf16_f32 v100, v100, v101
	v_cvt_pk_bf16_f32 v101, v102, v103
	v_cvt_pk_bf16_f32 v102, v104, v105
	v_cvt_pk_bf16_f32 v103, v106, v107
	global_store_dwordx4 v[178:179], v[100:103], off
	v_mul_f32_e32 v106, 0xbfb8aa3b, v112
	v_mul_f32_e32 v107, 0xbfb8aa3b, v113
	v_mul_f32_e32 v102, 0xbfb8aa3b, v116
	v_mul_f32_e32 v103, 0xbfb8aa3b, v117
	v_exp_f32_e32 v102, v102
	v_exp_f32_e32 v103, v103
	v_mul_f32_e32 v108, 0xbfb8aa3b, v114
	v_mul_f32_e32 v109, 0xbfb8aa3b, v115
	v_exp_f32_e32 v106, v106
	v_exp_f32_e32 v107, v107
	v_exp_f32_e32 v108, v108
	v_exp_f32_e32 v109, v109
	v_add_f32_e32 v102, 1.0, v102
	v_add_f32_e32 v103, 1.0, v103
	v_mul_f32_e32 v104, 0xbfb8aa3b, v118
	v_mul_f32_e32 v105, 0xbfb8aa3b, v119
	v_rcp_f32_e32 v102, v102
	v_exp_f32_e32 v104, v104
	v_exp_f32_e32 v105, v105
	v_rcp_f32_e32 v103, v103
	v_add_f32_e32 v106, 1.0, v106
	v_add_f32_e32 v107, 1.0, v107
	v_add_f32_e32 v108, 1.0, v108
	v_add_f32_e32 v109, 1.0, v109
	v_rcp_f32_e32 v106, v106
	v_rcp_f32_e32 v107, v107
	v_rcp_f32_e32 v108, v108
	v_rcp_f32_e32 v109, v109
	v_add_f32_e32 v104, 1.0, v104
	v_add_f32_e32 v105, 1.0, v105
	v_pk_mul_f32 v[102:103], v[116:117], v[102:103]
	v_pk_mul_f32 v[98:99], v[98:99], v[180:181] op_sel_hi:[1,0]
	v_rcp_f32_e32 v104, v104
	v_rcp_f32_e32 v105, v105
	v_pk_mul_f32 v[102:103], v[174:175], v[102:103]
	v_pk_mul_f32 v[106:107], v[112:113], v[106:107]
	v_pk_mul_f32 v[108:109], v[114:115], v[108:109]
	v_pk_mul_f32 v[104:105], v[118:119], v[104:105]
	v_pk_mul_f32 v[108:109], v[98:99], v[108:109]
	v_pk_mul_f32 v[98:99], v[96:97], v[106:107]
	v_cvt_pk_bf16_f32 v96, v102, v103
	v_fmamk_f32 v102, v155, 0x3a800000, v170
	v_rsq_f32_e32 v102, v102
	v_mad_i64_i32 v[100:101], s[24:25], v172, s44, v[144:145]
	v_pk_mul_f32 v[104:105], v[182:183], v[104:105]
	v_lshl_add_u64 v[100:101], v[100:101], 0, v[148:149]
	v_cvt_pk_bf16_f32 v97, v104, v105
	v_cvt_pk_bf16_f32 v98, v98, v99
	v_cvt_pk_bf16_f32 v99, v108, v109
	v_pk_mul_f32 v[94:95], v[94:95], v[102:103] op_sel_hi:[1,0]
	v_pk_mul_f32 v[92:93], v[92:93], v[102:103] op_sel_hi:[1,0]
	global_store_dwordx4 v[100:101], v[96:99], off
	v_mul_f32_e32 v100, 0xbfb8aa3b, v94
	v_mul_f32_e32 v101, 0xbfb8aa3b, v95
	v_mul_f32_e32 v98, 0xbfb8aa3b, v92
	v_mul_f32_e32 v99, 0xbfb8aa3b, v93
	v_exp_f32_e32 v98, v98
	v_exp_f32_e32 v99, v99
	v_exp_f32_e32 v100, v100
	v_exp_f32_e32 v101, v101
	v_add_f32_e32 v98, 1.0, v98
	v_add_f32_e32 v99, 1.0, v99
	v_add_f32_e32 v100, 1.0, v100
	v_add_f32_e32 v101, 1.0, v101
	v_rcp_f32_e32 v98, v98
	v_rcp_f32_e32 v99, v99
	v_rcp_f32_e32 v100, v100
	v_rcp_f32_e32 v101, v101
	v_pk_mul_f32 v[90:91], v[90:91], v[102:103] op_sel_hi:[1,0]
	v_pk_mul_f32 v[88:89], v[88:89], v[102:103] op_sel_hi:[1,0]
	v_pk_mul_f32 v[92:93], v[92:93], v[98:99]
	v_mul_f32_e32 v98, 0xbfb8aa3b, v88
	v_mul_f32_e32 v99, 0xbfb8aa3b, v89
	v_pk_mul_f32 v[94:95], v[94:95], v[100:101]
	v_mul_f32_e32 v100, 0xbfb8aa3b, v90
	v_mul_f32_e32 v101, 0xbfb8aa3b, v91
	v_exp_f32_e32 v98, v98
	v_exp_f32_e32 v99, v99
	v_exp_f32_e32 v100, v100
	v_exp_f32_e32 v101, v101
	v_add_f32_e32 v98, 1.0, v98
	v_add_f32_e32 v99, 1.0, v99
	v_add_f32_e32 v100, 1.0, v100
	v_add_f32_e32 v101, 1.0, v101
	v_rcp_f32_e32 v98, v98
	v_rcp_f32_e32 v99, v99
	v_rcp_f32_e32 v100, v100
	v_rcp_f32_e32 v101, v101
	v_pk_mul_f32 v[84:85], v[84:85], v[102:103] op_sel_hi:[1,0]
	v_pk_mul_f32 v[80:81], v[80:81], v[102:103] op_sel_hi:[1,0]
	v_pk_mul_f32 v[82:83], v[82:83], v[102:103] op_sel_hi:[1,0]
	v_pk_mul_f32 v[84:85], v[84:85], v[92:93]
	v_pk_mul_f32 v[88:89], v[88:89], v[98:99]
	v_pk_mul_f32 v[90:91], v[90:91], v[100:101]
	v_pk_mul_f32 v[86:87], v[86:87], v[102:103] op_sel_hi:[1,0]
	v_pk_mul_f32 v[90:91], v[82:83], v[90:91]
	v_pk_mul_f32 v[82:83], v[80:81], v[88:89]
	v_cvt_pk_bf16_f32 v80, v84, v85
	v_fmamk_f32 v84, v157, 0x3a800000, v170
	v_rsq_f32_e32 v84, v84
	v_mad_i64_i32 v[96:97], s[24:25], v176, s44, v[144:145]
	v_pk_mul_f32 v[86:87], v[86:87], v[94:95]
	v_lshl_add_u64 v[96:97], v[96:97], 0, v[148:149]
	v_cvt_pk_bf16_f32 v81, v86, v87
	v_cvt_pk_bf16_f32 v82, v82, v83
	v_cvt_pk_bf16_f32 v83, v90, v91
	v_pk_mul_f32 v[78:79], v[78:79], v[84:85] op_sel_hi:[1,0]
	v_pk_mul_f32 v[76:77], v[76:77], v[84:85] op_sel_hi:[1,0]
	global_store_dwordx4 v[96:97], v[80:83], off
	v_pk_mul_f32 v[74:75], v[74:75], v[84:85] op_sel_hi:[1,0]
	v_pk_mul_f32 v[72:73], v[72:73], v[84:85] op_sel_hi:[1,0]
	v_pk_mul_f32 v[68:69], v[68:69], v[84:85] op_sel_hi:[1,0]
	v_pk_mul_f32 v[70:71], v[70:71], v[84:85] op_sel_hi:[1,0]
	v_pk_mul_f32 v[64:65], v[64:65], v[84:85] op_sel_hi:[1,0]
	v_pk_mul_f32 v[66:67], v[66:67], v[84:85] op_sel_hi:[1,0]
	v_mul_f32_e32 v82, 0xbfb8aa3b, v76
	v_mul_f32_e32 v83, 0xbfb8aa3b, v77
	v_mul_f32_e32 v84, 0xbfb8aa3b, v78
	v_mul_f32_e32 v85, 0xbfb8aa3b, v79
	v_exp_f32_e32 v82, v82
	v_exp_f32_e32 v83, v83
	v_exp_f32_e32 v84, v84
	v_exp_f32_e32 v85, v85
	v_add_f32_e32 v82, 1.0, v82
; DI void st8(bf16_t* p, f32x4 a, f32x4 b) { u32x4 w; w.x = cvt_pk_bf16(a.x, a.y); w.y = cvt_pk_bf16(a.z, a.w); w.z = cvt_pk_bf16(b.x, b.y); w.w = cvt_pk_bf16(b.z, b.w); *(u32x4*)p = w; }
; DI f32x4 sigm4(f32x4 v) { f32x4 r; r.x = sigm(v.x); r.y = sigm(v.y); r.z = sigm(v.z); r.w = sigm(v.w); return r; }
;     template <int NAI> DI void run(AccRef acc, const Unit& u, int wr, int wc, int fr, int fq) const {
;     ...
;         for (int ai = 0; ai < NAI; ++ai)
; #pragma unroll
;             for (int m = 0; m < 4; ++m) {
;                 const int row = EPI_ROW(ai, m); const float rs = __builtin_amdgcn_rsqf(rsv[ai][m] * (1.f / DM) + EPS);
;                 const f32x4 g0 = acc[ai][0][m][0] * rs, g1 = acc[ai][0][m][1] * rs, u0 = acc[ai][1][m][0] * rs, u1 = acc[ai][1][m][1] * rs;
;                 st8(P + G_RV + (size_t)row * DFF + cl, g0 * sigm4(g0) * u0, g1 * sigm4(g1) * u1);
;             }
	v_add_f32_e32 v83, 1.0, v83
	v_add_f32_e32 v84, 1.0, v84
	v_add_f32_e32 v85, 1.0, v85
	v_rcp_f32_e32 v82, v82
	v_rcp_f32_e32 v83, v83
	v_rcp_f32_e32 v84, v84
	v_rcp_f32_e32 v85, v85
	v_mad_i64_i32 v[80:81], s[24:25], v158, s44, v[144:145]
	v_pk_mul_f32 v[76:77], v[76:77], v[82:83]
	v_mul_f32_e32 v82, 0xbfb8aa3b, v72
	v_mul_f32_e32 v83, 0xbfb8aa3b, v73
	v_pk_mul_f32 v[78:79], v[78:79], v[84:85]
	v_mul_f32_e32 v84, 0xbfb8aa3b, v74
	v_mul_f32_e32 v85, 0xbfb8aa3b, v75
	v_exp_f32_e32 v82, v82
	v_exp_f32_e32 v83, v83
	v_exp_f32_e32 v84, v84
	v_exp_f32_e32 v85, v85
	v_add_f32_e32 v82, 1.0, v82
	v_add_f32_e32 v83, 1.0, v83
	v_add_f32_e32 v84, 1.0, v84
	v_add_f32_e32 v85, 1.0, v85
	v_rcp_f32_e32 v82, v82
	v_rcp_f32_e32 v83, v83
	v_rcp_f32_e32 v84, v84
	v_rcp_f32_e32 v85, v85
	v_pk_mul_f32 v[68:69], v[68:69], v[76:77]
	v_pk_mul_f32 v[72:73], v[72:73], v[82:83]
	v_pk_mul_f32 v[70:71], v[70:71], v[78:79]
	v_pk_mul_f32 v[74:75], v[74:75], v[84:85]
	v_lshl_add_u64 v[80:81], v[80:81], 0, v[148:149]
	v_pk_mul_f32 v[74:75], v[66:67], v[74:75]
	v_pk_mul_f32 v[66:67], v[64:65], v[72:73]
	v_cvt_pk_bf16_f32 v64, v68, v69
	v_fmamk_f32 v68, v159, 0x3a800000, v170
	v_rsq_f32_e32 v68, v68
	v_cvt_pk_bf16_f32 v65, v70, v71
	v_cvt_pk_bf16_f32 v66, v66, v67
	v_cvt_pk_bf16_f32 v67, v74, v75
	v_pk_mul_f32 v[62:63], v[62:63], v[68:69] op_sel_hi:[1,0]
	v_pk_mul_f32 v[60:61], v[60:61], v[68:69] op_sel_hi:[1,0]
	global_store_dwordx4 v[80:81], v[64:67], off
	v_pk_mul_f32 v[58:59], v[58:59], v[68:69] op_sel_hi:[1,0]
	v_pk_mul_f32 v[56:57], v[56:57], v[68:69] op_sel_hi:[1,0]
	v_pk_mul_f32 v[52:53], v[52:53], v[68:69] op_sel_hi:[1,0]
	v_pk_mul_f32 v[54:55], v[54:55], v[68:69] op_sel_hi:[1,0]
	v_pk_mul_f32 v[48:49], v[48:49], v[68:69] op_sel_hi:[1,0]
	v_pk_mul_f32 v[50:51], v[50:51], v[68:69] op_sel_hi:[1,0]
	v_mul_f32_e32 v66, 0xbfb8aa3b, v60
	v_mul_f32_e32 v67, 0xbfb8aa3b, v61
	v_mul_f32_e32 v68, 0xbfb8aa3b, v62
	v_mul_f32_e32 v69, 0xbfb8aa3b, v63
	v_exp_f32_e32 v66, v66
	v_exp_f32_e32 v67, v67
	v_exp_f32_e32 v68, v68
	v_exp_f32_e32 v69, v69
	v_add_f32_e32 v66, 1.0, v66
	v_add_f32_e32 v67, 1.0, v67
	v_add_f32_e32 v68, 1.0, v68
	v_add_f32_e32 v69, 1.0, v69
	v_rcp_f32_e32 v66, v66
	v_rcp_f32_e32 v67, v67
	v_rcp_f32_e32 v68, v68
	v_rcp_f32_e32 v69, v69
	v_mad_i64_i32 v[64:65], s[24:25], v156, s44, v[144:145]
	v_pk_mul_f32 v[60:61], v[60:61], v[66:67]
	v_mul_f32_e32 v66, 0xbfb8aa3b, v56
	v_mul_f32_e32 v67, 0xbfb8aa3b, v57
	v_pk_mul_f32 v[62:63], v[62:63], v[68:69]
	v_mul_f32_e32 v68, 0xbfb8aa3b, v58
	v_mul_f32_e32 v69, 0xbfb8aa3b, v59
	v_exp_f32_e32 v66, v66
	v_exp_f32_e32 v67, v67
	v_exp_f32_e32 v68, v68
	v_exp_f32_e32 v69, v69
	v_add_f32_e32 v66, 1.0, v66
	v_add_f32_e32 v67, 1.0, v67
	v_add_f32_e32 v68, 1.0, v68
	v_add_f32_e32 v69, 1.0, v69
	v_rcp_f32_e32 v66, v66
	v_rcp_f32_e32 v67, v67
	v_rcp_f32_e32 v68, v68
	v_rcp_f32_e32 v69, v69
	v_pk_mul_f32 v[52:53], v[52:53], v[60:61]
	v_pk_mul_f32 v[56:57], v[56:57], v[66:67]
	v_pk_mul_f32 v[54:55], v[54:55], v[62:63]
	v_pk_mul_f32 v[58:59], v[58:59], v[68:69]
	v_lshl_add_u64 v[64:65], v[64:65], 0, v[148:149]
	v_pk_mul_f32 v[58:59], v[50:51], v[58:59]
	v_pk_mul_f32 v[50:51], v[48:49], v[56:57]
	v_cvt_pk_bf16_f32 v48, v52, v53
	v_fmamk_f32 v52, v177, 0x3a800000, v170
	v_rsq_f32_e32 v52, v52
	v_cvt_pk_bf16_f32 v49, v54, v55
	v_cvt_pk_bf16_f32 v50, v50, v51
	v_cvt_pk_bf16_f32 v51, v58, v59
	v_pk_mul_f32 v[46:47], v[46:47], v[52:53] op_sel_hi:[1,0]
	v_pk_mul_f32 v[44:45], v[44:45], v[52:53] op_sel_hi:[1,0]
	global_store_dwordx4 v[64:65], v[48:51], off
	v_pk_mul_f32 v[42:43], v[42:43], v[52:53] op_sel_hi:[1,0]
	v_pk_mul_f32 v[40:41], v[40:41], v[52:53] op_sel_hi:[1,0]
	v_pk_mul_f32 v[36:37], v[36:37], v[52:53] op_sel_hi:[1,0]
	v_pk_mul_f32 v[38:39], v[38:39], v[52:53] op_sel_hi:[1,0]
	v_pk_mul_f32 v[32:33], v[32:33], v[52:53] op_sel_hi:[1,0]
	v_pk_mul_f32 v[34:35], v[34:35], v[52:53] op_sel_hi:[1,0]
	v_mul_f32_e32 v50, 0xbfb8aa3b, v44
	v_mul_f32_e32 v51, 0xbfb8aa3b, v45
	v_mul_f32_e32 v52, 0xbfb8aa3b, v46
	v_mul_f32_e32 v53, 0xbfb8aa3b, v47
	v_exp_f32_e32 v50, v50
	v_exp_f32_e32 v51, v51
	v_exp_f32_e32 v52, v52
	v_exp_f32_e32 v53, v53
	v_add_f32_e32 v50, 1.0, v50
	v_add_f32_e32 v51, 1.0, v51
	v_add_f32_e32 v52, 1.0, v52
	v_add_f32_e32 v53, 1.0, v53
	v_rcp_f32_e32 v50, v50
	v_rcp_f32_e32 v51, v51
	v_rcp_f32_e32 v52, v52
	v_rcp_f32_e32 v53, v53
	v_mad_i64_i32 v[48:49], s[24:25], v154, s44, v[144:145]
	v_pk_mul_f32 v[44:45], v[44:45], v[50:51]
	v_mul_f32_e32 v50, 0xbfb8aa3b, v40
	v_mul_f32_e32 v51, 0xbfb8aa3b, v41
	v_pk_mul_f32 v[46:47], v[46:47], v[52:53]
	v_mul_f32_e32 v52, 0xbfb8aa3b, v42
	v_mul_f32_e32 v53, 0xbfb8aa3b, v43
	v_exp_f32_e32 v50, v50
	v_exp_f32_e32 v51, v51
	v_exp_f32_e32 v52, v52
	v_exp_f32_e32 v53, v53
	v_add_f32_e32 v50, 1.0, v50
	v_add_f32_e32 v51, 1.0, v51
	v_add_f32_e32 v52, 1.0, v52
	v_add_f32_e32 v53, 1.0, v53
; DI void st8(bf16_t* p, f32x4 a, f32x4 b) { u32x4 w; w.x = cvt_pk_bf16(a.x, a.y); w.y = cvt_pk_bf16(a.z, a.w); w.z = cvt_pk_bf16(b.x, b.y); w.w = cvt_pk_bf16(b.z, b.w); *(u32x4*)p = w; }
; DI f32x4 sigm4(f32x4 v) { f32x4 r; r.x = sigm(v.x); r.y = sigm(v.y); r.z = sigm(v.z); r.w = sigm(v.w); return r; }
; #define PG8_BAR __builtin_amdgcn_s_barrier()
;     DI void prep(const Unit& u, int tid) const { if (tid < 256) *(LAS f32x4*)(tbl + (u.ui & 1) * 4096 + tid * 16) = factors(u.r0 + tid); }
; template <class Epi, bool ALIGN_EPI>
; DI void gemm_phase(lptr lds, const Gemm g, const StaticOrder& S, const Epi& E) {
;     ...
;         if (!has_next) break;
; #pragma unroll
;         for (int a = 0; a < 2; ++a)
; #pragma unroll
;             for (int b = 0; b < 2; ++b)
; #pragma unroll
;                 for (int m = 0; m < 4; ++m)
; #pragma unroll
;                     for (int n = 0; n < 2; ++n) acc[a][b][m][n] = (f32x4){0.f, 0.f, 0.f, 0.f};
;         cur = nxt; cA = nA; cB = nB; ++ui;
;         if constexpr (Epi::RESCALE) E.prep(cur, tid);
;         if constexpr (ALIGN_EPI) { if (wr == 1) PG8_BAR; }
;     template <int NAI> DI void run(AccRef acc, const Unit& u, int wr, int wc, int fr, int fq) const {
;     ...
;         for (int ai = 0; ai < NAI; ++ai)
; #pragma unroll
;             for (int m = 0; m < 4; ++m) {
;                 const int row = EPI_ROW(ai, m); const float rs = __builtin_amdgcn_rsqf(rsv[ai][m] * (1.f / DM) + EPS);
;                 const f32x4 g0 = acc[ai][0][m][0] * rs, g1 = acc[ai][0][m][1] * rs, u0 = acc[ai][1][m][0] * rs, u1 = acc[ai][1][m][1] * rs;
;                 st8(P + G_RV + (size_t)row * DFF + cl, g0 * sigm4(g0) * u0, g1 * sigm4(g1) * u1);
;             }
	v_rcp_f32_e32 v50, v50
	v_rcp_f32_e32 v51, v51
	v_rcp_f32_e32 v52, v52
	v_rcp_f32_e32 v53, v53
	v_pk_mul_f32 v[36:37], v[36:37], v[44:45]
	v_pk_mul_f32 v[40:41], v[40:41], v[50:51]
	v_pk_mul_f32 v[38:39], v[38:39], v[46:47]
	v_pk_mul_f32 v[42:43], v[42:43], v[52:53]
	v_lshl_add_u64 v[48:49], v[48:49], 0, v[148:149]
	v_pk_mul_f32 v[42:43], v[34:35], v[42:43]
	v_pk_mul_f32 v[34:35], v[32:33], v[40:41]
	v_cvt_pk_bf16_f32 v32, v36, v37
	v_fmamk_f32 v36, v151, 0x3a800000, v170
	v_rsq_f32_e32 v36, v36
	v_cvt_pk_bf16_f32 v33, v38, v39
	v_cvt_pk_bf16_f32 v34, v34, v35
	v_cvt_pk_bf16_f32 v35, v42, v43
	v_pk_mul_f32 v[30:31], v[30:31], v[36:37] op_sel_hi:[1,0]
	v_pk_mul_f32 v[28:29], v[28:29], v[36:37] op_sel_hi:[1,0]
	global_store_dwordx4 v[48:49], v[32:35], off
	v_pk_mul_f32 v[26:27], v[26:27], v[36:37] op_sel_hi:[1,0]
	v_pk_mul_f32 v[24:25], v[24:25], v[36:37] op_sel_hi:[1,0]
	v_pk_mul_f32 v[20:21], v[20:21], v[36:37] op_sel_hi:[1,0]
	v_pk_mul_f32 v[22:23], v[22:23], v[36:37] op_sel_hi:[1,0]
	v_pk_mul_f32 v[16:17], v[16:17], v[36:37] op_sel_hi:[1,0]
	v_pk_mul_f32 v[18:19], v[18:19], v[36:37] op_sel_hi:[1,0]
	v_mul_f32_e32 v34, 0xbfb8aa3b, v28
	v_mul_f32_e32 v35, 0xbfb8aa3b, v29
	v_mul_f32_e32 v36, 0xbfb8aa3b, v30
	v_mul_f32_e32 v37, 0xbfb8aa3b, v31
	v_exp_f32_e32 v34, v34
	v_exp_f32_e32 v35, v35
	v_exp_f32_e32 v36, v36
	v_exp_f32_e32 v37, v37
	v_add_f32_e32 v34, 1.0, v34
	v_add_f32_e32 v35, 1.0, v35
	v_add_f32_e32 v36, 1.0, v36
	v_add_f32_e32 v37, 1.0, v37
	v_rcp_f32_e32 v34, v34
	v_rcp_f32_e32 v35, v35
	v_rcp_f32_e32 v36, v36
	v_rcp_f32_e32 v37, v37
	v_mad_i64_i32 v[32:33], s[24:25], v150, s44, v[144:145]
	v_pk_mul_f32 v[28:29], v[28:29], v[34:35]
	v_mul_f32_e32 v34, 0xbfb8aa3b, v24
	v_mul_f32_e32 v35, 0xbfb8aa3b, v25
	v_pk_mul_f32 v[30:31], v[30:31], v[36:37]
	v_mul_f32_e32 v36, 0xbfb8aa3b, v26
	v_mul_f32_e32 v37, 0xbfb8aa3b, v27
	v_exp_f32_e32 v34, v34
	v_exp_f32_e32 v35, v35
	v_exp_f32_e32 v36, v36
	v_exp_f32_e32 v37, v37
	v_add_f32_e32 v34, 1.0, v34
	v_add_f32_e32 v35, 1.0, v35
	v_add_f32_e32 v36, 1.0, v36
	v_add_f32_e32 v37, 1.0, v37
	v_rcp_f32_e32 v34, v34
	v_rcp_f32_e32 v35, v35
	v_rcp_f32_e32 v36, v36
	v_rcp_f32_e32 v37, v37
	v_pk_mul_f32 v[20:21], v[20:21], v[28:29]
	v_pk_mul_f32 v[24:25], v[24:25], v[34:35]
	v_pk_mul_f32 v[22:23], v[22:23], v[30:31]
	v_pk_mul_f32 v[26:27], v[26:27], v[36:37]
	v_lshl_add_u64 v[32:33], v[32:33], 0, v[148:149]
	v_pk_mul_f32 v[26:27], v[18:19], v[26:27]
	v_pk_mul_f32 v[18:19], v[16:17], v[24:25]
	v_cvt_pk_bf16_f32 v16, v20, v21
	v_fmamk_f32 v20, v147, 0x3a800000, v170
	v_rsq_f32_e32 v20, v20
	v_cvt_pk_bf16_f32 v17, v22, v23
	v_cvt_pk_bf16_f32 v18, v18, v19
	v_cvt_pk_bf16_f32 v19, v26, v27
	v_pk_mul_f32 v[14:15], v[14:15], v[20:21] op_sel_hi:[1,0]
	v_pk_mul_f32 v[12:13], v[12:13], v[20:21] op_sel_hi:[1,0]
	global_store_dwordx4 v[32:33], v[16:19], off
	v_pk_mul_f32 v[10:11], v[10:11], v[20:21] op_sel_hi:[1,0]
	v_pk_mul_f32 v[8:9], v[8:9], v[20:21] op_sel_hi:[1,0]
	v_pk_mul_f32 v[4:5], v[4:5], v[20:21] op_sel_hi:[1,0]
	v_pk_mul_f32 v[6:7], v[6:7], v[20:21] op_sel_hi:[1,0]
	v_pk_mul_f32 v[0:1], v[0:1], v[20:21] op_sel_hi:[1,0]
	v_pk_mul_f32 v[2:3], v[2:3], v[20:21] op_sel_hi:[1,0]
	v_mul_f32_e32 v18, 0xbfb8aa3b, v12
	v_mul_f32_e32 v19, 0xbfb8aa3b, v13
	v_mul_f32_e32 v20, 0xbfb8aa3b, v14
	v_mul_f32_e32 v21, 0xbfb8aa3b, v15
	v_exp_f32_e32 v18, v18
	v_exp_f32_e32 v19, v19
	v_exp_f32_e32 v20, v20
	v_exp_f32_e32 v21, v21
	v_add_f32_e32 v18, 1.0, v18
	v_add_f32_e32 v19, 1.0, v19
	v_add_f32_e32 v20, 1.0, v20
	v_add_f32_e32 v21, 1.0, v21
	v_rcp_f32_e32 v18, v18
	v_rcp_f32_e32 v19, v19
	v_rcp_f32_e32 v20, v20
	v_rcp_f32_e32 v21, v21
	v_mad_i64_i32 v[16:17], s[24:25], v146, s44, v[144:145]
	v_pk_mul_f32 v[12:13], v[12:13], v[18:19]
	v_mul_f32_e32 v18, 0xbfb8aa3b, v8
	v_mul_f32_e32 v19, 0xbfb8aa3b, v9
	v_pk_mul_f32 v[14:15], v[14:15], v[20:21]
	v_mul_f32_e32 v20, 0xbfb8aa3b, v10
	v_mul_f32_e32 v21, 0xbfb8aa3b, v11
	v_exp_f32_e32 v18, v18
	v_exp_f32_e32 v19, v19
	v_exp_f32_e32 v20, v20
	v_exp_f32_e32 v21, v21
	v_add_f32_e32 v18, 1.0, v18
	v_add_f32_e32 v19, 1.0, v19
	v_add_f32_e32 v20, 1.0, v20
	v_add_f32_e32 v21, 1.0, v21
	v_rcp_f32_e32 v18, v18
	v_rcp_f32_e32 v19, v19
	v_rcp_f32_e32 v20, v20
	v_rcp_f32_e32 v21, v21
	v_pk_mul_f32 v[6:7], v[6:7], v[14:15]
	v_pk_mul_f32 v[8:9], v[8:9], v[18:19]
	v_pk_mul_f32 v[4:5], v[4:5], v[12:13]
	v_pk_mul_f32 v[10:11], v[10:11], v[20:21]
	v_lshl_add_u64 v[16:17], v[16:17], 0, v[148:149]
	v_pk_mul_f32 v[10:11], v[2:3], v[10:11]
	v_pk_mul_f32 v[2:3], v[0:1], v[8:9]
	v_cvt_pk_bf16_f32 v0, v4, v5
	v_cvt_pk_bf16_f32 v1, v6, v7
	v_cvt_pk_bf16_f32 v2, v2, v3
	v_cvt_pk_bf16_f32 v3, v10, v11
	global_store_dwordx4 v[16:17], v[0:3], off
	s_cbranch_vccnz .LBB0_1277
	s_andn2_b64 vcc, exec, s[8:9]
	s_cbranch_vccnz .LBB0_1276
	s_barrier
	s_branch .LBB0_1276
.Lrx_gu_0:
	s_waitcnt vmcnt(24)
	s_branch .Lrx_gu_0b

; __global__ void __launch_bounds__(512, 2) fwd_mega(Params p) {
;     extern __shared__ __attribute__((aligned(16))) unsigned char lds_raw[];
;     lptr L = (lptr)lds_raw;
;     const int tid = threadIdx.x, lane = tid & 63, wave = __builtin_amdgcn_readfirstlane(tid >> 6);
	.amdhsa_kernel _Z8fwd_mega6Params
		.amdhsa_group_segment_fixed_size 0
		.amdhsa_private_segment_fixed_size 0
		.amdhsa_kernarg_size 488
		.amdhsa_user_sgpr_count 2
		.amdhsa_user_sgpr_dispatch_ptr 0
		.amdhsa_user_sgpr_queue_ptr 0
		.amdhsa_user_sgpr_kernarg_segment_ptr 1
		.amdhsa_user_sgpr_dispatch_id 0
		.amdhsa_user_sgpr_kernarg_preload_length 0
		.amdhsa_user_sgpr_kernarg_preload_offset 0
		.amdhsa_user_sgpr_private_segment_size 0
		.amdhsa_uses_dynamic_stack 0
		.amdhsa_enable_private_segment 0
		.amdhsa_system_sgpr_workgroup_id_x 1
		.amdhsa_system_sgpr_workgroup_id_y 0
		.amdhsa_system_sgpr_workgroup_id_z 0
		.amdhsa_system_sgpr_workgroup_info 0
		.amdhsa_system_vgpr_workitem_id 2
		.amdhsa_next_free_vgpr 255
		.amdhsa_next_free_sgpr 100
		.amdhsa_accum_offset 256
		.amdhsa_reserve_vcc 1
		.amdhsa_float_round_mode_32 0
		.amdhsa_float_round_mode_16_64 0
		.amdhsa_float_denorm_mode_32 3
		.amdhsa_float_denorm_mode_16_64 3
		.amdhsa_dx10_clamp 1
		.amdhsa_ieee_mode 1
		.amdhsa_fp16_overflow 0
		.amdhsa_tg_split 0
		.amdhsa_exception_fp_ieee_invalid_op 0
		.amdhsa_exception_fp_denorm_src 0
		.amdhsa_exception_fp_ieee_div_zero 0
		.amdhsa_exception_fp_ieee_overflow 0
		.amdhsa_exception_fp_ieee_underflow 0
		.amdhsa_exception_fp_ieee_inexact 0
		.amdhsa_exception_int_div_zero 0
	.end_amdhsa_kernel

; __global__ void __launch_bounds__(512, 2) fwd_mega(Params p) {
;     extern __shared__ __attribute__((aligned(16))) unsigned char lds_raw[];
;     lptr L = (lptr)lds_raw;
;     const int tid = threadIdx.x, lane = tid & 63, wave = __builtin_amdgcn_readfirstlane(tid >> 6);
amdhsa.kernels:
  - .agpr_count:     0
    .args:
      - .offset:         0
        .size:           232
        .value_kind:     by_value
      - .offset:         232
        .size:           4
        .value_kind:     hidden_block_count_x
      - .offset:         236
        .size:           4
        .value_kind:     hidden_block_count_y
      - .offset:         240
        .size:           4
        .value_kind:     hidden_block_count_z
      - .offset:         244
        .size:           2
        .value_kind:     hidden_group_size_x
      - .offset:         246
        .size:           2
        .value_kind:     hidden_group_size_y
      - .offset:         248
        .size:           2
        .value_kind:     hidden_group_size_z
      - .offset:         250
        .size:           2
        .value_kind:     hidden_remainder_x
      - .offset:         252
        .size:           2
        .value_kind:     hidden_remainder_y
      - .offset:         254
        .size:           2
        .value_kind:     hidden_remainder_z
      - .offset:         272
        .size:           8
        .value_kind:     hidden_global_offset_x
      - .offset:         280
        .size:           8
        .value_kind:     hidden_global_offset_y
      - .offset:         288
        .size:           8
        .value_kind:     hidden_global_offset_z
      - .offset:         296
        .size:           2
        .value_kind:     hidden_grid_dims
      - .offset:         320
        .size:           8
        .value_kind:     hidden_multigrid_sync_arg
      - .offset:         352
        .size:           4
        .value_kind:     hidden_dynamic_lds_size
    .group_segment_fixed_size: 0
    .kernarg_segment_align: 8
    .kernarg_segment_size: 488
    .language:       OpenCL C
    .language_version:
      - 2
      - 0
    .max_flat_workgroup_size: 512
    .name:           _Z8fwd_mega6Params
    .private_segment_fixed_size: 0
    .sgpr_count:     106
    .sgpr_spill_count: 35
    .symbol:         _Z8fwd_mega6Params.kd
    .uniform_work_group_size: 1
    .uses_dynamic_stack: false
    .vgpr_count:     255
    .vgpr_spill_count: 0
    .wavefront_size: 64
